# on top of v24: 60 per-DMA 64-bit VALU address adds removed from the GEMM mainloops (SGPR-base DMA form, or offset:128 with m0 lowered by 128)
# speedup vs baseline: 1.0100x; 1.0100x over previous
; #define PG8_STAGE(bufoff, gbase) do { _Pragma("unroll") for (int _i = 0; _i < 2; ++_i) \
;         __builtin_amdgcn_global_load_lds((const unsigned*)((const char*)(gbase) + voff[_i]), (LAS unsigned*)(lds + (bufoff) + ldsw + _i * 8192), 16, 0, 0); } while (0)
; #define PG8_LDA(dst, b, h) do { _Pragma("unroll") for (int m = 0; m < 4; ++m) _Pragma("unroll") for (int k = 0; k < 2; ++k) dst[m][k] = *(const LAS bf16x8*)(lds + PG8_SA(b, h) + aoff + m * 2048 + k * 1024); } while (0)
; #define PG8_LDB(dst, b, h) do { _Pragma("unroll") for (int n = 0; n < 2; ++n) _Pragma("unroll") for (int k = 0; k < 2; ++k) dst[n][k] = *(const LAS bf16x8*)(lds + PG8_SB(b, h) + boff + n * 2048 + k * 1024); } while (0)
; #define PG8_MMA(ai, bj, At, Bt) do { __builtin_amdgcn_s_setprio(1); _Pragma("unroll") for (int m = 0; m < 4; ++m) _Pragma("unroll") for (int n = 0; n < 2; ++n) _Pragma("unroll") for (int k = 0; k < 2; ++k) \
;         acc[ai][bj][m][n] = __builtin_amdgcn_mfma_f32_16x16x32_bf16(Bt[n][k], At[m][k], acc[ai][bj][m][n], 0, 0, 0); __builtin_amdgcn_s_setprio(0); } while (0)
; #define PG8_WAIT_L(n) asm volatile("s_waitcnt lgkmcnt(" #n ")" ::: "memory")
; #define PG8_BAR __builtin_amdgcn_s_barrier()
; #define PG8_SCHED __builtin_amdgcn_sched_barrier(0)
; template <class Epi>
; DI void gemm_phase(LAS unsigned char* lds, const Gemm g, const StaticOrder& S, const Epi& E) {
;     ...
;             PG8_LDB(B0, 0, 0); PG8_SCHED; PG8_LDA(At, 0, 0); PG8_STAGE(PG8_SA(1, 1), a1 + hstep);
;             PG8_WAIT_L(8); PG8_BAR; PG8_WAIT_L(0); PG8_MMA(0, 0, At, B0); PG8_BAR; PG8_SCHED;
;             PG8_LDB(B1, 0, 1); PG8_STAGE(PG8_SB(0, 0), b2);
;             PG8_BAR; PG8_WAIT_L(0); PG8_MMA(0, 1, At, B1); PG8_BAR;
;             PG8_LDA(At, 0, 1); PG8_STAGE(PG8_SA(0, 0), a2);
;             PG8_BAR; PG8_WAIT_L(0); PG8_MMA(1, 0, At, B0); PG8_BAR; PG8_SCHED;
.LBB0_37:
	s_add_u32 s20, s18, 0xfff80080
	s_addc_u32 s21, s19, -1
	s_add_i32 s39, 0, 0x10000
	ds_read_b128 v[138:141], v135
	ds_read_b128 v[142:145], v135 offset:1024
	ds_read_b128 v[146:149], v135 offset:2048
	ds_read_b128 v[150:153], v135 offset:3072
	s_cmp_eq_u32 s38, 28
	s_cselect_b32 s23, s4, s21
	s_cselect_b32 s22, s5, s20
	s_cselect_b32 s21, s9, s37
	s_cselect_b32 s20, s11, s33
	s_add_i32 m0, s28, 0xc000
	ds_read_b128 v[186:189], v137
	ds_read_b128 v[190:193], v137 offset:1024
	ds_read_b128 v[194:197], v137 offset:2048
	ds_read_b128 v[198:201], v137 offset:3072
	ds_read_b128 v[202:205], v137 offset:4096
	ds_read_b128 v[206:209], v137 offset:5120
	ds_read_b128 v[210:213], v137 offset:6144
	ds_read_b128 v[214:217], v137 offset:7168
	global_load_lds_dwordx4 v130, s[18:19]
	s_add_i32 m0, s28, 0xe000
	s_nop 0
	global_load_lds_dwordx4 v132, s[18:19]
	s_waitcnt lgkmcnt(8)
	s_setprio 1
	s_barrier
	s_waitcnt lgkmcnt(0)
	v_mfma_f32_16x16x32_bf16 v[124:127], v[138:141], v[186:189], v[124:127]
	v_mfma_f32_16x16x32_bf16 v[120:123], v[146:149], v[186:189], v[120:123]
	v_mfma_f32_16x16x32_bf16 v[108:111], v[138:141], v[194:197], v[108:111]
	v_mfma_f32_16x16x32_bf16 v[104:107], v[146:149], v[194:197], v[104:107]
	v_mfma_f32_16x16x32_bf16 v[92:95], v[138:141], v[202:205], v[92:95]
	v_mfma_f32_16x16x32_bf16 v[88:91], v[146:149], v[202:205], v[88:91]
	v_mfma_f32_16x16x32_bf16 v[76:79], v[138:141], v[210:213], v[76:79]
	v_mfma_f32_16x16x32_bf16 v[72:75], v[146:149], v[210:213], v[72:75]
	v_mfma_f32_16x16x32_bf16 v[124:127], v[142:145], v[190:193], v[124:127]
	v_mfma_f32_16x16x32_bf16 v[120:123], v[150:153], v[190:193], v[120:123]
	v_mfma_f32_16x16x32_bf16 v[108:111], v[142:145], v[198:201], v[108:111]
	v_mfma_f32_16x16x32_bf16 v[104:107], v[150:153], v[198:201], v[104:107]
	v_mfma_f32_16x16x32_bf16 v[92:95], v[142:145], v[206:209], v[92:95]
	v_mfma_f32_16x16x32_bf16 v[88:91], v[150:153], v[206:209], v[88:91]
	v_mfma_f32_16x16x32_bf16 v[76:79], v[142:145], v[214:217], v[76:79]
	s_setprio 0
	v_mfma_f32_16x16x32_bf16 v[72:75], v[150:153], v[214:217], v[72:75]
	s_barrier
	s_add_i32 s42, 0, 0x14000
	s_add_i32 s39, s39, s27
	ds_read_b128 v[226:229], v135 offset:16384
	ds_read_b128 v[230:233], v135 offset:17408
	ds_read_b128 v[234:237], v135 offset:18432
	ds_read_b128 v[238:241], v135 offset:19456
	v_lshl_add_u64 v[154:155], s[20:21], 0, v[158:159]
	s_mov_b32 m0, s39
	v_lshl_add_u64 v[218:219], s[20:21], 0, v[128:129]
	global_load_lds_dwordx4 v[154:155], off
	s_add_i32 m0, s39, 0x2000
	s_nop 0
	global_load_lds_dwordx4 v[218:219], off
	s_waitcnt lgkmcnt(0)
	s_setprio 1
	s_barrier
	v_mfma_f32_16x16x32_bf16 v[116:119], v[226:229], v[186:189], v[116:119]
	v_mfma_f32_16x16x32_bf16 v[112:115], v[234:237], v[186:189], v[112:115]
	v_mfma_f32_16x16x32_bf16 v[100:103], v[226:229], v[194:197], v[100:103]
	v_mfma_f32_16x16x32_bf16 v[96:99], v[234:237], v[194:197], v[96:99]
	v_mfma_f32_16x16x32_bf16 v[84:87], v[226:229], v[202:205], v[84:87]
	v_mfma_f32_16x16x32_bf16 v[80:83], v[234:237], v[202:205], v[80:83]
	v_mfma_f32_16x16x32_bf16 v[68:71], v[226:229], v[210:213], v[68:71]
	v_mfma_f32_16x16x32_bf16 v[64:67], v[234:237], v[210:213], v[64:67]
	v_mfma_f32_16x16x32_bf16 v[116:119], v[230:233], v[190:193], v[116:119]
	s_mov_b32 m0, s28
	v_mfma_f32_16x16x32_bf16 v[112:115], v[238:241], v[190:193], v[112:115]
	v_lshl_add_u64 v[220:221], s[22:23], 0, v[158:159]
	v_mfma_f32_16x16x32_bf16 v[100:103], v[230:233], v[198:201], v[100:103]
	v_mfma_f32_16x16x32_bf16 v[96:99], v[238:241], v[198:201], v[96:99]
	v_mfma_f32_16x16x32_bf16 v[84:87], v[230:233], v[206:209], v[84:87]
	v_mfma_f32_16x16x32_bf16 v[80:83], v[238:241], v[206:209], v[80:83]
	v_mfma_f32_16x16x32_bf16 v[68:71], v[230:233], v[214:217], v[68:71]
	s_setprio 0
	v_mfma_f32_16x16x32_bf16 v[64:67], v[238:241], v[214:217], v[64:67]
	s_barrier
	ds_read_b128 v[186:189], v137 offset:16384
	ds_read_b128 v[190:193], v137 offset:17408
	ds_read_b128 v[194:197], v137 offset:18432
	ds_read_b128 v[198:201], v137 offset:19456
	ds_read_b128 v[202:205], v137 offset:20480
	ds_read_b128 v[206:209], v137 offset:21504
	ds_read_b128 v[210:213], v137 offset:22528
	ds_read_b128 v[214:217], v137 offset:23552
	global_load_lds_dwordx4 v[220:221], off
	v_lshl_add_u64 v[242:243], s[22:23], 0, v[128:129]
	s_mov_b32 m0, s29
	s_nop 0
	global_load_lds_dwordx4 v[242:243], off
	s_waitcnt lgkmcnt(0)
	s_setprio 1
	s_barrier
	v_mfma_f32_16x16x32_bf16 v[60:63], v[138:141], v[186:189], v[60:63]
	v_mfma_f32_16x16x32_bf16 v[56:59], v[146:149], v[186:189], v[56:59]
	v_mfma_f32_16x16x32_bf16 v[44:47], v[138:141], v[194:197], v[44:47]
	v_mfma_f32_16x16x32_bf16 v[40:43], v[146:149], v[194:197], v[40:43]
	v_mfma_f32_16x16x32_bf16 v[28:31], v[138:141], v[202:205], v[28:31]
	v_mfma_f32_16x16x32_bf16 v[24:27], v[146:149], v[202:205], v[24:27]
	v_mfma_f32_16x16x32_bf16 v[12:15], v[138:141], v[210:213], v[12:15]
	v_mfma_f32_16x16x32_bf16 v[8:11], v[146:149], v[210:213], v[8:11]
	v_mfma_f32_16x16x32_bf16 v[60:63], v[142:145], v[190:193], v[60:63]
	v_mfma_f32_16x16x32_bf16 v[56:59], v[150:153], v[190:193], v[56:59]
	v_mfma_f32_16x16x32_bf16 v[44:47], v[142:145], v[198:201], v[44:47]
	v_mfma_f32_16x16x32_bf16 v[40:43], v[150:153], v[198:201], v[40:43]
	v_mfma_f32_16x16x32_bf16 v[28:31], v[142:145], v[206:209], v[28:31]
	v_mfma_f32_16x16x32_bf16 v[24:27], v[150:153], v[206:209], v[24:27]
	v_mfma_f32_16x16x32_bf16 v[12:15], v[142:145], v[214:217], v[12:15]
	s_setprio 0
	v_mfma_f32_16x16x32_bf16 v[8:11], v[150:153], v[214:217], v[8:11]
	s_barrier
; #define PG8_STAGE(bufoff, gbase) do { _Pragma("unroll") for (int _i = 0; _i < 2; ++_i) \
;         __builtin_amdgcn_global_load_lds((const unsigned*)((const char*)(gbase) + voff[_i]), (LAS unsigned*)(lds + (bufoff) + ldsw + _i * 8192), 16, 0, 0); } while (0)
; #define PG8_LDA(dst, b, h) do { _Pragma("unroll") for (int m = 0; m < 4; ++m) _Pragma("unroll") for (int k = 0; k < 2; ++k) dst[m][k] = *(const LAS bf16x8*)(lds + PG8_SA(b, h) + aoff + m * 2048 + k * 1024); } while (0)
; #define PG8_LDB(dst, b, h) do { _Pragma("unroll") for (int n = 0; n < 2; ++n) _Pragma("unroll") for (int k = 0; k < 2; ++k) dst[n][k] = *(const LAS bf16x8*)(lds + PG8_SB(b, h) + boff + n * 2048 + k * 1024); } while (0)
; #define PG8_MMA(ai, bj, At, Bt) do { __builtin_amdgcn_s_setprio(1); _Pragma("unroll") for (int m = 0; m < 4; ++m) _Pragma("unroll") for (int n = 0; n < 2; ++n) _Pragma("unroll") for (int k = 0; k < 2; ++k) \
;         acc[ai][bj][m][n] = __builtin_amdgcn_mfma_f32_16x16x32_bf16(Bt[n][k], At[m][k], acc[ai][bj][m][n], 0, 0, 0); __builtin_amdgcn_s_setprio(0); } while (0)
; #define PG8_WAIT_V(n) asm volatile("s_waitcnt vmcnt(" #n ")" ::: "memory")
; #define PG8_WAIT_L(n) asm volatile("s_waitcnt lgkmcnt(" #n ")" ::: "memory")
; #define PG8_BAR __builtin_amdgcn_s_barrier()
; #define PG8_SCHED __builtin_amdgcn_sched_barrier(0)
; template <class Epi>
; DI void gemm_phase(LAS unsigned char* lds, const Gemm g, const StaticOrder& S, const Epi& E) {
;     ...
;             PG8_STAGE(PG8_SB(0, 1), b2 + hstep);
;             PG8_WAIT_V(6); PG8_BAR; PG8_MMA(1, 1, At, B1); PG8_BAR;
;             PG8_LDB(B0, 1, 0); PG8_SCHED; PG8_LDA(At, 1, 0); PG8_STAGE(PG8_SA(0, 1), a2 + hstep);
;             PG8_WAIT_L(8); PG8_BAR; PG8_WAIT_L(0); PG8_MMA(0, 0, At, B0); PG8_BAR; PG8_SCHED;
;             PG8_LDB(B1, 1, 1); PG8_STAGE(PG8_SB(1, 0), b3);
;             PG8_BAR; PG8_WAIT_L(0); PG8_MMA(0, 1, At, B1); PG8_BAR;
;             PG8_LDA(At, 1, 1); PG8_STAGE(PG8_SA(1, 0), a3);
	s_add_u32 s40, s20, 0x80000
	s_addc_u32 s41, s21, 0
	s_add_i32 s39, s42, s27
	s_mov_b32 m0, s39
	s_nop 0
	global_load_lds_dwordx4 v158, s[40:41]
	s_add_i32 m0, s39, 0x2000
	s_nop 0
	global_load_lds_dwordx4 v128, s[40:41]
	s_waitcnt vmcnt(6)
	s_setprio 1
	s_barrier
	v_mfma_f32_16x16x32_bf16 v[52:55], v[226:229], v[186:189], v[52:55]
	v_mfma_f32_16x16x32_bf16 v[48:51], v[234:237], v[186:189], v[48:51]
	v_mfma_f32_16x16x32_bf16 v[36:39], v[226:229], v[194:197], v[36:39]
	v_mfma_f32_16x16x32_bf16 v[32:35], v[234:237], v[194:197], v[32:35]
	v_mfma_f32_16x16x32_bf16 v[20:23], v[226:229], v[202:205], v[20:23]
	v_mfma_f32_16x16x32_bf16 v[16:19], v[234:237], v[202:205], v[16:19]
	v_mfma_f32_16x16x32_bf16 v[4:7], v[226:229], v[210:213], v[4:7]
	v_mfma_f32_16x16x32_bf16 v[0:3], v[234:237], v[210:213], v[0:3]
	v_mfma_f32_16x16x32_bf16 v[52:55], v[230:233], v[190:193], v[52:55]
	s_add_i32 s39, 0, 0x18000
	v_mfma_f32_16x16x32_bf16 v[48:51], v[238:241], v[190:193], v[48:51]
	v_mfma_f32_16x16x32_bf16 v[36:39], v[230:233], v[198:201], v[36:39]
	v_mfma_f32_16x16x32_bf16 v[32:35], v[238:241], v[198:201], v[32:35]
	v_mfma_f32_16x16x32_bf16 v[20:23], v[230:233], v[206:209], v[20:23]
	v_mfma_f32_16x16x32_bf16 v[16:19], v[238:241], v[206:209], v[16:19]
	v_mfma_f32_16x16x32_bf16 v[4:7], v[230:233], v[214:217], v[4:7]
	s_setprio 0
	v_mfma_f32_16x16x32_bf16 v[0:3], v[238:241], v[214:217], v[0:3]
	s_barrier
	ds_read_b128 v[138:141], v135 offset:32768
	ds_read_b128 v[142:145], v135 offset:33792
	ds_read_b128 v[146:149], v135 offset:34816
	ds_read_b128 v[150:153], v135 offset:35840
	s_add_u32 s22, s22, 0x80000
	s_addc_u32 s23, s23, 0
	s_mov_b32 m0, s30
	ds_read_b128 v[186:189], v137 offset:32768
	ds_read_b128 v[190:193], v137 offset:33792
	ds_read_b128 v[194:197], v137 offset:34816
	ds_read_b128 v[198:201], v137 offset:35840
	ds_read_b128 v[202:205], v137 offset:36864
	ds_read_b128 v[206:209], v137 offset:37888
	ds_read_b128 v[210:213], v137 offset:38912
	ds_read_b128 v[214:217], v137 offset:39936
	global_load_lds_dwordx4 v158, s[22:23]
	s_mov_b32 m0, s31
	s_nop 0
	global_load_lds_dwordx4 v128, s[22:23]
	s_waitcnt lgkmcnt(8)
	s_setprio 1
	s_barrier
	s_waitcnt lgkmcnt(0)
	v_mfma_f32_16x16x32_bf16 v[124:127], v[138:141], v[186:189], v[124:127]
	v_mfma_f32_16x16x32_bf16 v[120:123], v[146:149], v[186:189], v[120:123]
	v_mfma_f32_16x16x32_bf16 v[108:111], v[138:141], v[194:197], v[108:111]
	v_mfma_f32_16x16x32_bf16 v[104:107], v[146:149], v[194:197], v[104:107]
	v_mfma_f32_16x16x32_bf16 v[92:95], v[138:141], v[202:205], v[92:95]
	v_mfma_f32_16x16x32_bf16 v[88:91], v[146:149], v[202:205], v[88:91]
	v_mfma_f32_16x16x32_bf16 v[76:79], v[138:141], v[210:213], v[76:79]
	v_mfma_f32_16x16x32_bf16 v[72:75], v[146:149], v[210:213], v[72:75]
	v_mfma_f32_16x16x32_bf16 v[124:127], v[142:145], v[190:193], v[124:127]
	v_mfma_f32_16x16x32_bf16 v[120:123], v[150:153], v[190:193], v[120:123]
	v_mfma_f32_16x16x32_bf16 v[108:111], v[142:145], v[198:201], v[108:111]
	v_mfma_f32_16x16x32_bf16 v[104:107], v[150:153], v[198:201], v[104:107]
	v_mfma_f32_16x16x32_bf16 v[92:95], v[142:145], v[206:209], v[92:95]
	v_mfma_f32_16x16x32_bf16 v[88:91], v[150:153], v[206:209], v[88:91]
	v_mfma_f32_16x16x32_bf16 v[76:79], v[142:145], v[214:217], v[76:79]
	s_setprio 0
	v_mfma_f32_16x16x32_bf16 v[72:75], v[150:153], v[214:217], v[72:75]
	s_barrier
	s_add_i32 s22, 0, 0x1c000
	s_add_i32 s23, s39, s27
	s_add_i32 m0, s23, 0xffffff80
	ds_read_b128 v[226:229], v135 offset:49152
	ds_read_b128 v[230:233], v135 offset:50176
	ds_read_b128 v[234:237], v135 offset:51200
	ds_read_b128 v[238:241], v135 offset:52224
	global_load_lds_dwordx4 v[154:155], off offset:128
	s_add_i32 m0, s23, 0x1f80
	s_nop 0
	global_load_lds_dwordx4 v[218:219], off offset:128
	s_waitcnt lgkmcnt(0)
	s_setprio 1
	s_barrier
	v_mfma_f32_16x16x32_bf16 v[116:119], v[226:229], v[186:189], v[116:119]
	v_mfma_f32_16x16x32_bf16 v[112:115], v[234:237], v[186:189], v[112:115]
	v_mfma_f32_16x16x32_bf16 v[100:103], v[226:229], v[194:197], v[100:103]
	v_mfma_f32_16x16x32_bf16 v[96:99], v[234:237], v[194:197], v[96:99]
	v_mfma_f32_16x16x32_bf16 v[84:87], v[226:229], v[202:205], v[84:87]
	v_mfma_f32_16x16x32_bf16 v[80:83], v[234:237], v[202:205], v[80:83]
	v_mfma_f32_16x16x32_bf16 v[68:71], v[226:229], v[210:213], v[68:71]
	v_mfma_f32_16x16x32_bf16 v[64:67], v[234:237], v[210:213], v[64:67]
	v_mfma_f32_16x16x32_bf16 v[116:119], v[230:233], v[190:193], v[116:119]
	s_mov_b32 m0, s34
	v_mfma_f32_16x16x32_bf16 v[112:115], v[238:241], v[190:193], v[112:115]
	v_lshl_add_u64 v[154:155], v[220:221], 0, s[94:95]
	v_mfma_f32_16x16x32_bf16 v[100:103], v[230:233], v[198:201], v[100:103]
	v_mfma_f32_16x16x32_bf16 v[96:99], v[238:241], v[198:201], v[96:99]
	v_mfma_f32_16x16x32_bf16 v[84:87], v[230:233], v[206:209], v[84:87]
	v_mfma_f32_16x16x32_bf16 v[80:83], v[238:241], v[206:209], v[80:83]
	v_mfma_f32_16x16x32_bf16 v[68:71], v[230:233], v[214:217], v[68:71]
	s_setprio 0
	v_mfma_f32_16x16x32_bf16 v[64:67], v[238:241], v[214:217], v[64:67]
	s_barrier
	ds_read_b128 v[186:189], v137 offset:49152
	ds_read_b128 v[190:193], v137 offset:50176
	ds_read_b128 v[194:197], v137 offset:51200
	ds_read_b128 v[198:201], v137 offset:52224
	ds_read_b128 v[202:205], v137 offset:53248
	ds_read_b128 v[206:209], v137 offset:54272
	ds_read_b128 v[210:213], v137 offset:55296
	ds_read_b128 v[214:217], v137 offset:56320
	global_load_lds_dwordx4 v[154:155], off
	s_add_i32 m0, s35, 0xffffff80
	s_nop 0
	global_load_lds_dwordx4 v[242:243], off offset:128
	s_waitcnt lgkmcnt(0)
	s_setprio 1
	s_barrier
; #define PG8_STAGE(bufoff, gbase) do { _Pragma("unroll") for (int _i = 0; _i < 2; ++_i) \
;         __builtin_amdgcn_global_load_lds((const unsigned*)((const char*)(gbase) + voff[_i]), (LAS unsigned*)(lds + (bufoff) + ldsw + _i * 8192), 16, 0, 0); } while (0)
; #define PG8_MMA(ai, bj, At, Bt) do { __builtin_amdgcn_s_setprio(1); _Pragma("unroll") for (int m = 0; m < 4; ++m) _Pragma("unroll") for (int n = 0; n < 2; ++n) _Pragma("unroll") for (int k = 0; k < 2; ++k) \
;         acc[ai][bj][m][n] = __builtin_amdgcn_mfma_f32_16x16x32_bf16(Bt[n][k], At[m][k], acc[ai][bj][m][n], 0, 0, 0); __builtin_amdgcn_s_setprio(0); } while (0)
; #define PG8_WAIT_V(n) asm volatile("s_waitcnt vmcnt(" #n ")" ::: "memory")
; #define PG8_WAIT_L(n) asm volatile("s_waitcnt lgkmcnt(" #n ")" ::: "memory")
; #define PG8_BAR __builtin_amdgcn_s_barrier()
; #define PG8_SCHED __builtin_amdgcn_sched_barrier(0)
; template <class Epi>
; DI void gemm_phase(LAS unsigned char* lds, const Gemm g, const StaticOrder& S, const Epi& E) {
;     ...
;             PG8_BAR; PG8_WAIT_L(0); PG8_MMA(1, 0, At, B0); PG8_BAR; PG8_SCHED;
;             PG8_STAGE(PG8_SB(1, 1), b3 + hstep);
;             PG8_WAIT_V(6); PG8_BAR; PG8_MMA(1, 1, At, B1); PG8_BAR;
;         }
;     DI void operator()(const f32x4 (&acc)[2][2][4][2], const Unit& u, int wr, int wc, int fr, int fq) const {
;         const int row0 = u.pm * BM + wr * 64 + fr, col0 = u.pn * HALF + wc * 32 + 8 * fq;
; #pragma unroll
;         for (int ai = 0; ai < 2; ++ai)
; #pragma unroll
;             for (int m = 0; m < 4; ++m) { float hv[8];
; #pragma unroll
;                 for (int n = 0; n < 2; ++n)
; #pragma unroll
;                     for (int e = 0; e < 4; ++e) { const float gt = acc[ai][0][m][n][e], up = acc[ai][1][m][n][e];
;                         hv[n * 4 + e] = gt * __builtin_amdgcn_rcpf(1.f + __builtin_amdgcn_exp2f(-1.4426950408889634f * gt)) * up; }
;                 *(u32x4*)(H + (size_t)(row0 + ai * HALF + m * 16) * DFF + col0) = (u32x4){pk(hv[0], hv[1]), pk(hv[2], hv[3]), pk(hv[4], hv[5]), pk(hv[6], hv[7])}; }
;     }
	v_mfma_f32_16x16x32_bf16 v[60:63], v[138:141], v[186:189], v[60:63]
	v_mfma_f32_16x16x32_bf16 v[56:59], v[146:149], v[186:189], v[56:59]
	v_mfma_f32_16x16x32_bf16 v[44:47], v[138:141], v[194:197], v[44:47]
	v_mfma_f32_16x16x32_bf16 v[40:43], v[146:149], v[194:197], v[40:43]
	v_mfma_f32_16x16x32_bf16 v[28:31], v[138:141], v[202:205], v[28:31]
	v_mfma_f32_16x16x32_bf16 v[24:27], v[146:149], v[202:205], v[24:27]
	v_mfma_f32_16x16x32_bf16 v[12:15], v[138:141], v[210:213], v[12:15]
	v_mfma_f32_16x16x32_bf16 v[8:11], v[146:149], v[210:213], v[8:11]
	v_mfma_f32_16x16x32_bf16 v[60:63], v[142:145], v[190:193], v[60:63]
	v_mfma_f32_16x16x32_bf16 v[56:59], v[150:153], v[190:193], v[56:59]
	v_mfma_f32_16x16x32_bf16 v[44:47], v[142:145], v[198:201], v[44:47]
	v_mfma_f32_16x16x32_bf16 v[40:43], v[150:153], v[198:201], v[40:43]
	v_mfma_f32_16x16x32_bf16 v[28:31], v[142:145], v[206:209], v[28:31]
	v_mfma_f32_16x16x32_bf16 v[24:27], v[150:153], v[206:209], v[24:27]
	v_mfma_f32_16x16x32_bf16 v[12:15], v[142:145], v[214:217], v[12:15]
	s_setprio 0
	v_mfma_f32_16x16x32_bf16 v[8:11], v[150:153], v[214:217], v[8:11]
	s_barrier
	s_add_u32 s20, s20, 0x80080
	s_addc_u32 s21, s21, 0
	s_add_i32 s22, s22, s27
	s_mov_b32 m0, s22
	s_nop 0
	global_load_lds_dwordx4 v158, s[20:21]
	s_add_i32 m0, s22, 0x2000
	s_nop 0
	global_load_lds_dwordx4 v128, s[20:21]
	s_waitcnt vmcnt(6)
	s_setprio 1
	s_barrier
	v_mfma_f32_16x16x32_bf16 v[52:55], v[226:229], v[186:189], v[52:55]
	v_mfma_f32_16x16x32_bf16 v[48:51], v[234:237], v[186:189], v[48:51]
	v_mfma_f32_16x16x32_bf16 v[36:39], v[226:229], v[194:197], v[36:39]
	v_mfma_f32_16x16x32_bf16 v[32:35], v[234:237], v[194:197], v[32:35]
	v_mfma_f32_16x16x32_bf16 v[20:23], v[226:229], v[202:205], v[20:23]
	v_mfma_f32_16x16x32_bf16 v[16:19], v[234:237], v[202:205], v[16:19]
	v_mfma_f32_16x16x32_bf16 v[4:7], v[226:229], v[210:213], v[4:7]
	v_mfma_f32_16x16x32_bf16 v[0:3], v[234:237], v[210:213], v[0:3]
	v_mfma_f32_16x16x32_bf16 v[52:55], v[230:233], v[190:193], v[52:55]
	s_add_i32 s38, s38, 2
	v_mfma_f32_16x16x32_bf16 v[48:51], v[238:241], v[190:193], v[48:51]
	s_add_u32 s18, s18, 0x100
	v_mfma_f32_16x16x32_bf16 v[36:39], v[230:233], v[198:201], v[36:39]
	s_addc_u32 s19, s19, 0
	v_mfma_f32_16x16x32_bf16 v[32:35], v[238:241], v[198:201], v[32:35]
	s_add_u32 s33, s33, 0x100
	v_mfma_f32_16x16x32_bf16 v[20:23], v[230:233], v[206:209], v[20:23]
	s_addc_u32 s37, s37, 0
	v_mfma_f32_16x16x32_bf16 v[16:19], v[238:241], v[206:209], v[16:19]
	s_cmp_gt_u32 s38, 29
	v_mfma_f32_16x16x32_bf16 v[4:7], v[230:233], v[214:217], v[4:7]
	s_setprio 0
	v_mfma_f32_16x16x32_bf16 v[0:3], v[238:241], v[214:217], v[0:3]
	s_barrier
	s_cbranch_scc0 .LBB0_37
	v_mul_f32_e32 v139, 0xbfb8aa3b, v124
	v_exp_f32_e32 v139, v139
	v_lshl_or_b32 v140, s2, 7, v136
	v_lshl_add_u32 v138, s3, 8, v134
	v_ashrrev_i32_e32 v141, 31, v140
	v_add_f32_e32 v139, 1.0, v139
	v_rcp_f32_e32 v142, v139
	v_mul_f32_e32 v139, 0xbfb8aa3b, v125
	v_exp_f32_e32 v139, v139
	s_movk_i32 s4, 0x2c00
	s_and_b64 vcc, exec, s[6:7]
	s_mov_b64 s[20:21], s[16:17]
	v_add_f32_e32 v139, 1.0, v139
	v_rcp_f32_e32 v143, v139
	v_mul_f32_e32 v139, 0xbfb8aa3b, v126
	v_exp_f32_e32 v139, v139
	s_mov_b64 s[18:19], s[14:15]
	v_pk_mul_f32 v[124:125], v[124:125], v[142:143]
	v_add_f32_e32 v139, 1.0, v139
	v_rcp_f32_e32 v144, v139
	v_mul_f32_e32 v139, 0xbfb8aa3b, v127
	v_exp_f32_e32 v139, v139
	v_pk_mul_f32 v[116:117], v[124:125], v[116:117]
	v_add_f32_e32 v139, 1.0, v139
	v_rcp_f32_e32 v145, v139
	v_mul_f32_e32 v139, 0xbfb8aa3b, v120
	v_exp_f32_e32 v139, v139
	v_cvt_pk_bf16_f32 v116, v116, v117
	v_pk_mul_f32 v[124:125], v[126:127], v[144:145]
	v_add_f32_e32 v139, 1.0, v139
	v_rcp_f32_e32 v146, v139
	v_mul_f32_e32 v139, 0xbfb8aa3b, v121
	v_exp_f32_e32 v139, v139
	v_pk_mul_f32 v[118:119], v[124:125], v[118:119]
	v_add_f32_e32 v139, 1.0, v139
	v_rcp_f32_e32 v147, v139
	v_mul_f32_e32 v139, 0xbfb8aa3b, v122
	v_exp_f32_e32 v139, v139
	v_cvt_pk_bf16_f32 v117, v118, v119
	v_pk_mul_f32 v[118:119], v[120:121], v[146:147]
	v_add_f32_e32 v139, 1.0, v139
	v_rcp_f32_e32 v148, v139
	v_mul_f32_e32 v139, 0xbfb8aa3b, v123
	v_exp_f32_e32 v139, v139
	v_pk_mul_f32 v[112:113], v[118:119], v[112:113]
	v_add_f32_e32 v139, 1.0, v139
	v_rcp_f32_e32 v149, v139
	v_cvt_pk_bf16_f32 v118, v112, v113
	v_pk_mul_f32 v[112:113], v[122:123], v[148:149]
	s_nop 0
	v_pk_mul_f32 v[112:113], v[112:113], v[114:115]
	v_lshlrev_b64 v[114:115], 1, v[140:141]
	v_cvt_pk_bf16_f32 v119, v112, v113
	v_mov_b64_e32 v[112:113], s[54:55]
	v_mad_i64_i32 v[120:121], s[2:3], v138, s4, v[112:113]
	v_lshl_add_u64 v[120:121], v[120:121], 0, v[114:115]
	global_store_dwordx4 v[120:121], v[116:119], off
	v_mul_f32_e32 v120, 0xbfb8aa3b, v104
	v_mul_f32_e32 v121, 0xbfb8aa3b, v105
	v_mul_f32_e32 v116, 0xbfb8aa3b, v108
	v_mul_f32_e32 v117, 0xbfb8aa3b, v109
	v_exp_f32_e32 v116, v116
	v_exp_f32_e32 v117, v117
	v_mul_f32_e32 v118, 0xbfb8aa3b, v110
	v_mul_f32_e32 v119, 0xbfb8aa3b, v111
	v_exp_f32_e32 v118, v118
	v_exp_f32_e32 v119, v119
	v_exp_f32_e32 v120, v120
	v_exp_f32_e32 v121, v121
	v_add_f32_e32 v116, 1.0, v116
	v_add_f32_e32 v117, 1.0, v117
	v_mul_f32_e32 v122, 0xbfb8aa3b, v106
	v_mul_f32_e32 v123, 0xbfb8aa3b, v107
	v_rcp_f32_e32 v116, v116
	v_rcp_f32_e32 v117, v117
	v_add_f32_e32 v118, 1.0, v118
	v_add_f32_e32 v119, 1.0, v119
	v_exp_f32_e32 v122, v122
	v_exp_f32_e32 v123, v123
	v_rcp_f32_e32 v118, v118
	v_rcp_f32_e32 v119, v119
	v_add_f32_e32 v120, 1.0, v120
	v_add_f32_e32 v121, 1.0, v121
	v_rcp_f32_e32 v120, v120
	v_rcp_f32_e32 v121, v121
	v_add_f32_e32 v122, 1.0, v122
	v_add_f32_e32 v123, 1.0, v123
	v_pk_mul_f32 v[108:109], v[108:109], v[116:117]
	v_rcp_f32_e32 v122, v122
;     DI void operator()(const f32x4 (&acc)[2][2][4][2], const Unit& u, int wr, int wc, int fr, int fq) const {
;     ...
;             for (int m = 0; m < 4; ++m) { float hv[8];
; #pragma unroll
;                 for (int n = 0; n < 2; ++n)
; #pragma unroll
;                     for (int e = 0; e < 4; ++e) { const float gt = acc[ai][0][m][n][e], up = acc[ai][1][m][n][e];
;                         hv[n * 4 + e] = gt * __builtin_amdgcn_rcpf(1.f + __builtin_amdgcn_exp2f(-1.4426950408889634f * gt)) * up; }
;                 *(u32x4*)(H + (size_t)(row0 + ai * HALF + m * 16) * DFF + col0) = (u32x4){pk(hv[0], hv[1]), pk(hv[2], hv[3]), pk(hv[4], hv[5]), pk(hv[6], hv[7])}; }
	v_rcp_f32_e32 v123, v123
	v_pk_mul_f32 v[100:101], v[108:109], v[100:101]
	v_pk_mul_f32 v[108:109], v[110:111], v[118:119]
	v_cvt_pk_bf16_f32 v100, v100, v101
	v_pk_mul_f32 v[102:103], v[108:109], v[102:103]
	s_nop 0
	v_cvt_pk_bf16_f32 v101, v102, v103
	v_pk_mul_f32 v[102:103], v[104:105], v[120:121]
	s_nop 0
	v_pk_mul_f32 v[96:97], v[102:103], v[96:97]
	s_nop 0
	v_cvt_pk_bf16_f32 v102, v96, v97
	v_pk_mul_f32 v[96:97], v[106:107], v[122:123]
	s_nop 0
	v_pk_mul_f32 v[96:97], v[96:97], v[98:99]
	v_mul_f32_e32 v98, 0xbfb8aa3b, v94
	v_cvt_pk_bf16_f32 v103, v96, v97
	v_or_b32_e32 v96, 16, v138
	v_mad_i64_i32 v[96:97], s[2:3], v96, s4, v[112:113]
	v_lshl_add_u64 v[96:97], v[96:97], 0, v[114:115]
	global_store_dwordx4 v[96:97], v[100:103], off
	v_mul_f32_e32 v96, 0xbfb8aa3b, v92
	v_mul_f32_e32 v97, 0xbfb8aa3b, v93
	v_exp_f32_e32 v96, v96
	v_exp_f32_e32 v97, v97
	v_mul_f32_e32 v99, 0xbfb8aa3b, v95
	v_exp_f32_e32 v98, v98
	v_exp_f32_e32 v99, v99
	v_mul_f32_e32 v100, 0xbfb8aa3b, v88
	v_mul_f32_e32 v101, 0xbfb8aa3b, v89
	v_exp_f32_e32 v100, v100
	v_exp_f32_e32 v101, v101
	v_add_f32_e32 v96, 1.0, v96
	v_add_f32_e32 v97, 1.0, v97
	v_mul_f32_e32 v102, 0xbfb8aa3b, v90
	v_mul_f32_e32 v103, 0xbfb8aa3b, v91
	v_rcp_f32_e32 v96, v96
	v_rcp_f32_e32 v97, v97
	v_add_f32_e32 v98, 1.0, v98
	v_add_f32_e32 v99, 1.0, v99
	v_exp_f32_e32 v102, v102
	v_exp_f32_e32 v103, v103
	v_rcp_f32_e32 v98, v98
	v_rcp_f32_e32 v99, v99
	v_add_f32_e32 v100, 1.0, v100
	v_add_f32_e32 v101, 1.0, v101
	v_rcp_f32_e32 v100, v100
	v_rcp_f32_e32 v101, v101
	v_add_f32_e32 v102, 1.0, v102
	v_add_f32_e32 v103, 1.0, v103
	v_pk_mul_f32 v[92:93], v[92:93], v[96:97]
	v_rcp_f32_e32 v102, v102
	v_rcp_f32_e32 v103, v103
	v_pk_mul_f32 v[84:85], v[92:93], v[84:85]
	v_pk_mul_f32 v[92:93], v[94:95], v[98:99]
	v_cvt_pk_bf16_f32 v84, v84, v85
	v_pk_mul_f32 v[86:87], v[92:93], v[86:87]
	s_nop 0
	v_cvt_pk_bf16_f32 v85, v86, v87
	v_pk_mul_f32 v[86:87], v[88:89], v[100:101]
	s_nop 0
	v_pk_mul_f32 v[80:81], v[86:87], v[80:81]
	s_nop 0
	v_cvt_pk_bf16_f32 v86, v80, v81
	v_pk_mul_f32 v[80:81], v[90:91], v[102:103]
	s_nop 0
	v_pk_mul_f32 v[80:81], v[80:81], v[82:83]
	v_mul_f32_e32 v82, 0xbfb8aa3b, v78
	v_cvt_pk_bf16_f32 v87, v80, v81
	v_or_b32_e32 v80, 32, v138
	v_mad_i64_i32 v[80:81], s[2:3], v80, s4, v[112:113]
	v_lshl_add_u64 v[80:81], v[80:81], 0, v[114:115]
	global_store_dwordx4 v[80:81], v[84:87], off
	v_mul_f32_e32 v80, 0xbfb8aa3b, v76
	v_mul_f32_e32 v81, 0xbfb8aa3b, v77
	v_exp_f32_e32 v80, v80
	v_exp_f32_e32 v81, v81
	v_mul_f32_e32 v83, 0xbfb8aa3b, v79
	v_exp_f32_e32 v82, v82
	v_exp_f32_e32 v83, v83
	v_mul_f32_e32 v84, 0xbfb8aa3b, v72
	v_mul_f32_e32 v85, 0xbfb8aa3b, v73
	v_exp_f32_e32 v84, v84
	v_exp_f32_e32 v85, v85
	v_add_f32_e32 v80, 1.0, v80
	v_add_f32_e32 v81, 1.0, v81
	v_mul_f32_e32 v86, 0xbfb8aa3b, v74
	v_mul_f32_e32 v87, 0xbfb8aa3b, v75
	v_rcp_f32_e32 v80, v80
	v_rcp_f32_e32 v81, v81
	v_add_f32_e32 v82, 1.0, v82
	v_add_f32_e32 v83, 1.0, v83
	v_exp_f32_e32 v86, v86
	v_exp_f32_e32 v87, v87
	v_rcp_f32_e32 v82, v82
	v_rcp_f32_e32 v83, v83
	v_add_f32_e32 v84, 1.0, v84
	v_add_f32_e32 v85, 1.0, v85
	v_rcp_f32_e32 v84, v84
	v_rcp_f32_e32 v85, v85
	v_add_f32_e32 v86, 1.0, v86
	v_add_f32_e32 v87, 1.0, v87
	v_pk_mul_f32 v[76:77], v[76:77], v[80:81]
	v_rcp_f32_e32 v86, v86
	v_rcp_f32_e32 v87, v87
	v_pk_mul_f32 v[68:69], v[76:77], v[68:69]
	v_pk_mul_f32 v[76:77], v[78:79], v[82:83]
	v_cvt_pk_bf16_f32 v68, v68, v69
	v_pk_mul_f32 v[70:71], v[76:77], v[70:71]
	s_nop 0
	v_cvt_pk_bf16_f32 v69, v70, v71
	v_pk_mul_f32 v[70:71], v[72:73], v[84:85]
	v_add_u32_e32 v72, 0x80, v138
	v_pk_mul_f32 v[64:65], v[70:71], v[64:65]
	s_nop 0
	v_cvt_pk_bf16_f32 v70, v64, v65
	v_pk_mul_f32 v[64:65], v[74:75], v[86:87]
	s_nop 0
	v_pk_mul_f32 v[64:65], v[64:65], v[66:67]
	v_mul_f32_e32 v66, 0xbfb8aa3b, v62
	v_cvt_pk_bf16_f32 v71, v64, v65
	v_or_b32_e32 v64, 48, v138
	v_mad_i64_i32 v[64:65], s[2:3], v64, s4, v[112:113]
	v_lshl_add_u64 v[64:65], v[64:65], 0, v[114:115]
	global_store_dwordx4 v[64:65], v[68:71], off
	v_mul_f32_e32 v64, 0xbfb8aa3b, v60
	v_mul_f32_e32 v65, 0xbfb8aa3b, v61
	v_exp_f32_e32 v64, v64
	v_exp_f32_e32 v65, v65
	v_mul_f32_e32 v67, 0xbfb8aa3b, v63
	v_exp_f32_e32 v66, v66
	v_exp_f32_e32 v67, v67
	v_mul_f32_e32 v68, 0xbfb8aa3b, v56
	v_mul_f32_e32 v69, 0xbfb8aa3b, v57
	v_exp_f32_e32 v68, v68
	v_exp_f32_e32 v69, v69
	v_add_f32_e32 v64, 1.0, v64
	v_add_f32_e32 v65, 1.0, v65
	v_mul_f32_e32 v70, 0xbfb8aa3b, v58
	v_mul_f32_e32 v71, 0xbfb8aa3b, v59
	v_rcp_f32_e32 v64, v64
	v_rcp_f32_e32 v65, v65
	v_add_f32_e32 v66, 1.0, v66
	v_add_f32_e32 v67, 1.0, v67
	v_exp_f32_e32 v70, v70
	v_exp_f32_e32 v71, v71
	v_rcp_f32_e32 v66, v66
	v_rcp_f32_e32 v67, v67
	v_add_f32_e32 v68, 1.0, v68
	v_add_f32_e32 v69, 1.0, v69
	v_rcp_f32_e32 v68, v68
	v_rcp_f32_e32 v69, v69
	v_add_f32_e32 v70, 1.0, v70
	v_add_f32_e32 v71, 1.0, v71
	v_pk_mul_f32 v[60:61], v[60:61], v[64:65]
	v_rcp_f32_e32 v70, v70
	v_rcp_f32_e32 v71, v71
	v_pk_mul_f32 v[52:53], v[60:61], v[52:53]
	v_pk_mul_f32 v[60:61], v[62:63], v[66:67]
	v_cvt_pk_bf16_f32 v52, v52, v53
	v_pk_mul_f32 v[54:55], v[60:61], v[54:55]
	s_nop 0
	v_cvt_pk_bf16_f32 v53, v54, v55
	v_pk_mul_f32 v[54:55], v[56:57], v[68:69]
	s_nop 0
	v_pk_mul_f32 v[48:49], v[54:55], v[48:49]
; #define PG8_WAIT_V(n) asm volatile("s_waitcnt vmcnt(" #n ")" ::: "memory")
; #define PG8_BAR __builtin_amdgcn_s_barrier()
; template <class Epi>
; DI void gemm_phase(LAS unsigned char* lds, const Gemm g, const StaticOrder& S, const Epi& E) {
;     ...
;         E(acc, cur, wr, wc, fr, fq);
;         if (!has_next) break;
; #pragma unroll
;         for (int a = 0; a < 2; ++a)
; #pragma unroll
;             for (int b = 0; b < 2; ++b)
; #pragma unroll
;                 for (int m = 0; m < 4; ++m)
; #pragma unroll
;                     for (int n = 0; n < 2; ++n) acc[a][b][m][n] = (f32x4){0.f, 0.f, 0.f, 0.f};
;         cur = nxt; cA = nA; cB = nB; ++ui;
;     }
;     PG8_WAIT_V(0);
;     if (wr == 0) PG8_BAR;
;     DI void operator()(const f32x4 (&acc)[2][2][4][2], const Unit& u, int wr, int wc, int fr, int fq) const {
;     ...
;             for (int m = 0; m < 4; ++m) { float hv[8];
; #pragma unroll
;                 for (int n = 0; n < 2; ++n)
; #pragma unroll
;                     for (int e = 0; e < 4; ++e) { const float gt = acc[ai][0][m][n][e], up = acc[ai][1][m][n][e];
;                         hv[n * 4 + e] = gt * __builtin_amdgcn_rcpf(1.f + __builtin_amdgcn_exp2f(-1.4426950408889634f * gt)) * up; }
;                 *(u32x4*)(H + (size_t)(row0 + ai * HALF + m * 16) * DFF + col0) = (u32x4){pk(hv[0], hv[1]), pk(hv[2], hv[3]), pk(hv[4], hv[5]), pk(hv[6], hv[7])}; }
	s_nop 0
	v_cvt_pk_bf16_f32 v54, v48, v49
	v_pk_mul_f32 v[48:49], v[58:59], v[70:71]
	s_nop 0
	v_pk_mul_f32 v[48:49], v[48:49], v[50:51]
	v_mul_f32_e32 v50, 0xbfb8aa3b, v46
	v_cvt_pk_bf16_f32 v55, v48, v49
	v_mad_i64_i32 v[48:49], s[2:3], v72, s4, v[112:113]
	v_lshl_add_u64 v[48:49], v[48:49], 0, v[114:115]
	global_store_dwordx4 v[48:49], v[52:55], off
	v_mul_f32_e32 v48, 0xbfb8aa3b, v44
	v_mul_f32_e32 v49, 0xbfb8aa3b, v45
	v_exp_f32_e32 v48, v48
	v_exp_f32_e32 v49, v49
	v_mul_f32_e32 v51, 0xbfb8aa3b, v47
	v_exp_f32_e32 v50, v50
	v_exp_f32_e32 v51, v51
	v_mul_f32_e32 v52, 0xbfb8aa3b, v40
	v_mul_f32_e32 v53, 0xbfb8aa3b, v41
	v_exp_f32_e32 v52, v52
	v_exp_f32_e32 v53, v53
	v_add_f32_e32 v48, 1.0, v48
	v_add_f32_e32 v49, 1.0, v49
	v_mul_f32_e32 v54, 0xbfb8aa3b, v42
	v_mul_f32_e32 v55, 0xbfb8aa3b, v43
	v_rcp_f32_e32 v48, v48
	v_rcp_f32_e32 v49, v49
	v_add_f32_e32 v50, 1.0, v50
	v_add_f32_e32 v51, 1.0, v51
	v_exp_f32_e32 v54, v54
	v_exp_f32_e32 v55, v55
	v_rcp_f32_e32 v50, v50
	v_rcp_f32_e32 v51, v51
	v_add_f32_e32 v52, 1.0, v52
	v_add_f32_e32 v53, 1.0, v53
	v_rcp_f32_e32 v52, v52
	v_rcp_f32_e32 v53, v53
	v_add_f32_e32 v54, 1.0, v54
	v_add_f32_e32 v55, 1.0, v55
	v_pk_mul_f32 v[44:45], v[44:45], v[48:49]
	v_rcp_f32_e32 v54, v54
	v_rcp_f32_e32 v55, v55
	v_pk_mul_f32 v[36:37], v[44:45], v[36:37]
	v_pk_mul_f32 v[44:45], v[46:47], v[50:51]
	v_cvt_pk_bf16_f32 v36, v36, v37
	v_pk_mul_f32 v[38:39], v[44:45], v[38:39]
	s_nop 0
	v_cvt_pk_bf16_f32 v37, v38, v39
	v_pk_mul_f32 v[38:39], v[40:41], v[52:53]
	s_nop 0
	v_pk_mul_f32 v[32:33], v[38:39], v[32:33]
	s_nop 0
	v_cvt_pk_bf16_f32 v38, v32, v33
	v_pk_mul_f32 v[32:33], v[42:43], v[54:55]
	s_nop 0
	v_pk_mul_f32 v[32:33], v[32:33], v[34:35]
	v_mul_f32_e32 v34, 0xbfb8aa3b, v30
	v_cvt_pk_bf16_f32 v39, v32, v33
	v_add_u32_e32 v32, 0x90, v138
	v_mad_i64_i32 v[32:33], s[2:3], v32, s4, v[112:113]
	v_lshl_add_u64 v[32:33], v[32:33], 0, v[114:115]
	global_store_dwordx4 v[32:33], v[36:39], off
	v_mul_f32_e32 v32, 0xbfb8aa3b, v28
	v_mul_f32_e32 v33, 0xbfb8aa3b, v29
	v_exp_f32_e32 v32, v32
	v_exp_f32_e32 v33, v33
	v_mul_f32_e32 v35, 0xbfb8aa3b, v31
	v_exp_f32_e32 v34, v34
	v_exp_f32_e32 v35, v35
	v_mul_f32_e32 v36, 0xbfb8aa3b, v24
	v_mul_f32_e32 v37, 0xbfb8aa3b, v25
	v_exp_f32_e32 v36, v36
	v_exp_f32_e32 v37, v37
	v_add_f32_e32 v32, 1.0, v32
	v_add_f32_e32 v33, 1.0, v33
	v_mul_f32_e32 v38, 0xbfb8aa3b, v26
	v_mul_f32_e32 v39, 0xbfb8aa3b, v27
	v_rcp_f32_e32 v32, v32
	v_rcp_f32_e32 v33, v33
	v_add_f32_e32 v34, 1.0, v34
	v_add_f32_e32 v35, 1.0, v35
	v_exp_f32_e32 v38, v38
	v_exp_f32_e32 v39, v39
	v_rcp_f32_e32 v34, v34
	v_rcp_f32_e32 v35, v35
	v_add_f32_e32 v36, 1.0, v36
	v_add_f32_e32 v37, 1.0, v37
	v_rcp_f32_e32 v36, v36
	v_rcp_f32_e32 v37, v37
	v_add_f32_e32 v38, 1.0, v38
	v_add_f32_e32 v39, 1.0, v39
	v_pk_mul_f32 v[28:29], v[28:29], v[32:33]
	v_rcp_f32_e32 v38, v38
	v_rcp_f32_e32 v39, v39
	v_pk_mul_f32 v[20:21], v[28:29], v[20:21]
	v_pk_mul_f32 v[28:29], v[30:31], v[34:35]
	v_cvt_pk_bf16_f32 v20, v20, v21
	v_pk_mul_f32 v[22:23], v[28:29], v[22:23]
	s_nop 0
	v_cvt_pk_bf16_f32 v21, v22, v23
	v_pk_mul_f32 v[22:23], v[24:25], v[36:37]
	s_nop 0
	v_pk_mul_f32 v[16:17], v[22:23], v[16:17]
	s_nop 0
	v_cvt_pk_bf16_f32 v22, v16, v17
	v_pk_mul_f32 v[16:17], v[26:27], v[38:39]
	s_nop 0
	v_pk_mul_f32 v[16:17], v[16:17], v[18:19]
	v_mul_f32_e32 v18, 0xbfb8aa3b, v14
	v_cvt_pk_bf16_f32 v23, v16, v17
	v_add_u32_e32 v16, 0xa0, v138
	v_mad_i64_i32 v[16:17], s[2:3], v16, s4, v[112:113]
	v_lshl_add_u64 v[16:17], v[16:17], 0, v[114:115]
	global_store_dwordx4 v[16:17], v[20:23], off
	v_mul_f32_e32 v16, 0xbfb8aa3b, v12
	v_mul_f32_e32 v17, 0xbfb8aa3b, v13
	v_exp_f32_e32 v16, v16
	v_exp_f32_e32 v17, v17
	v_mul_f32_e32 v19, 0xbfb8aa3b, v15
	v_exp_f32_e32 v18, v18
	v_exp_f32_e32 v19, v19
	v_mul_f32_e32 v20, 0xbfb8aa3b, v8
	v_mul_f32_e32 v21, 0xbfb8aa3b, v9
	v_exp_f32_e32 v20, v20
	v_exp_f32_e32 v21, v21
	v_add_f32_e32 v16, 1.0, v16
	v_add_f32_e32 v17, 1.0, v17
	v_mul_f32_e32 v22, 0xbfb8aa3b, v10
	v_mul_f32_e32 v23, 0xbfb8aa3b, v11
	v_rcp_f32_e32 v16, v16
	v_rcp_f32_e32 v17, v17
	v_add_f32_e32 v18, 1.0, v18
	v_add_f32_e32 v19, 1.0, v19
	v_exp_f32_e32 v22, v22
	v_exp_f32_e32 v23, v23
	v_rcp_f32_e32 v18, v18
	v_rcp_f32_e32 v19, v19
	v_add_f32_e32 v20, 1.0, v20
	v_add_f32_e32 v21, 1.0, v21
	v_rcp_f32_e32 v20, v20
	v_rcp_f32_e32 v21, v21
	v_add_f32_e32 v22, 1.0, v22
	v_add_f32_e32 v23, 1.0, v23
	v_pk_mul_f32 v[12:13], v[12:13], v[16:17]
	v_rcp_f32_e32 v22, v22
	v_rcp_f32_e32 v23, v23
	v_pk_mul_f32 v[4:5], v[12:13], v[4:5]
	v_pk_mul_f32 v[12:13], v[14:15], v[18:19]
	v_cvt_pk_bf16_f32 v4, v4, v5
	v_pk_mul_f32 v[6:7], v[12:13], v[6:7]
	s_nop 0
	v_cvt_pk_bf16_f32 v5, v6, v7
	v_pk_mul_f32 v[6:7], v[8:9], v[20:21]
	s_nop 0
	v_pk_mul_f32 v[0:1], v[6:7], v[0:1]
	s_nop 0
	v_cvt_pk_bf16_f32 v6, v0, v1
	v_pk_mul_f32 v[0:1], v[10:11], v[22:23]
	s_nop 0
	v_pk_mul_f32 v[0:1], v[0:1], v[2:3]
	s_nop 0
	v_cvt_pk_bf16_f32 v7, v0, v1
	v_add_u32_e32 v0, 0xb0, v138
	v_mad_i64_i32 v[0:1], s[2:3], v0, s4, v[112:113]
	v_lshl_add_u64 v[0:1], v[0:1], 0, v[114:115]
	s_mov_b32 s2, s8
	s_mov_b32 s3, s10
	global_store_dwordx4 v[0:1], v[4:7], off
	s_cbranch_vccz .LBB0_34
	s_waitcnt vmcnt(0)
	s_cmpk_gt_u32 s24, 0xff
	s_cbranch_scc1 .LBB0_41
	s_barrier

; #define PG8_STAGE(bufoff, gbase) do { _Pragma("unroll") for (int _i = 0; _i < 2; ++_i) \
;         __builtin_amdgcn_global_load_lds((const unsigned*)((const char*)(gbase) + voff[_i]), (LAS unsigned*)(lds + (bufoff) + ldsw + _i * 8192), 16, 0, 0); } while (0)
; #define PG8_LDA(dst, b, h) do { _Pragma("unroll") for (int m = 0; m < 4; ++m) _Pragma("unroll") for (int k = 0; k < 2; ++k) dst[m][k] = *(const LAS bf16x8*)(lds + PG8_SA(b, h) + aoff + m * 2048 + k * 1024); } while (0)
; #define PG8_LDB(dst, b, h) do { _Pragma("unroll") for (int n = 0; n < 2; ++n) _Pragma("unroll") for (int k = 0; k < 2; ++k) dst[n][k] = *(const LAS bf16x8*)(lds + PG8_SB(b, h) + boff + n * 2048 + k * 1024); } while (0)
; #define PG8_MMA(ai, bj, At, Bt) do { __builtin_amdgcn_s_setprio(1); _Pragma("unroll") for (int m = 0; m < 4; ++m) _Pragma("unroll") for (int n = 0; n < 2; ++n) _Pragma("unroll") for (int k = 0; k < 2; ++k) \
;         acc[ai][bj][m][n] = __builtin_amdgcn_mfma_f32_16x16x32_bf16(Bt[n][k], At[m][k], acc[ai][bj][m][n], 0, 0, 0); __builtin_amdgcn_s_setprio(0); } while (0)
; #define PG8_WAIT_L(n) asm volatile("s_waitcnt lgkmcnt(" #n ")" ::: "memory")
; #define PG8_BAR __builtin_amdgcn_s_barrier()
; #define PG8_SCHED __builtin_amdgcn_sched_barrier(0)
; template <class Epi>
; DI void gemm_phase(LAS unsigned char* lds, const Gemm g, const StaticOrder& S, const Epi& E) {
;     ...
;             PG8_LDB(B0, 0, 0); PG8_SCHED; PG8_LDA(At, 0, 0); PG8_STAGE(PG8_SA(1, 1), a1 + hstep);
;             PG8_WAIT_L(8); PG8_BAR; PG8_WAIT_L(0); PG8_MMA(0, 0, At, B0); PG8_BAR; PG8_SCHED;
;             PG8_LDB(B1, 0, 1); PG8_STAGE(PG8_SB(0, 0), b2);
;             PG8_BAR; PG8_WAIT_L(0); PG8_MMA(0, 1, At, B1); PG8_BAR;
;             PG8_LDA(At, 0, 1); PG8_STAGE(PG8_SA(0, 0), a2);
;             PG8_BAR; PG8_WAIT_L(0); PG8_MMA(1, 0, At, B0); PG8_BAR; PG8_SCHED;
.LBB0_77:
	s_add_u32 s22, s20, 0x100
	s_addc_u32 s23, s21, 0
	s_add_i32 s43, 0, 0x10000
	ds_read_b128 v[128:131], v226
	ds_read_b128 v[132:135], v226 offset:1024
	ds_read_b128 v[136:139], v226 offset:2048
	ds_read_b128 v[140:143], v226 offset:3072
	s_cmp_eq_u32 s33, 32
	s_cselect_b32 s27, s9, s23
	s_cselect_b32 s26, s8, s22
	s_cselect_b32 s25, s11, s5
	s_cselect_b32 s24, s10, s4
	v_lshl_add_u64 v[214:215], s[20:21], 0, v[190:191]
	s_add_i32 m0, s34, 0xc000
	ds_read_b128 v[144:147], v228
	ds_read_b128 v[148:151], v228 offset:1024
	ds_read_b128 v[152:155], v228 offset:2048
	ds_read_b128 v[194:197], v228 offset:3072
	ds_read_b128 v[198:201], v228 offset:4096
	ds_read_b128 v[202:205], v228 offset:5120
	ds_read_b128 v[206:209], v228 offset:6144
	ds_read_b128 v[210:213], v228 offset:7168
	global_load_lds_dwordx4 v[214:215], off
	v_lshl_add_u64 v[214:215], s[20:21], 0, v[192:193]
	s_add_i32 m0, s34, 0xe000
	s_nop 0
	global_load_lds_dwordx4 v[214:215], off
	s_waitcnt lgkmcnt(8)
	s_setprio 1
	s_barrier
	s_waitcnt lgkmcnt(0)
	v_mfma_f32_16x16x32_bf16 v[124:127], v[128:131], v[144:147], v[124:127]
	v_mfma_f32_16x16x32_bf16 v[120:123], v[136:139], v[144:147], v[120:123]
	v_mfma_f32_16x16x32_bf16 v[116:119], v[128:131], v[152:155], v[116:119]
	v_mfma_f32_16x16x32_bf16 v[112:115], v[136:139], v[152:155], v[112:115]
	v_mfma_f32_16x16x32_bf16 v[108:111], v[128:131], v[198:201], v[108:111]
	v_mfma_f32_16x16x32_bf16 v[104:107], v[136:139], v[198:201], v[104:107]
	v_mfma_f32_16x16x32_bf16 v[100:103], v[128:131], v[206:209], v[100:103]
	v_mfma_f32_16x16x32_bf16 v[96:99], v[136:139], v[206:209], v[96:99]
	v_mfma_f32_16x16x32_bf16 v[124:127], v[132:135], v[148:151], v[124:127]
	v_mfma_f32_16x16x32_bf16 v[120:123], v[140:143], v[148:151], v[120:123]
	v_mfma_f32_16x16x32_bf16 v[116:119], v[132:135], v[194:197], v[116:119]
	v_mfma_f32_16x16x32_bf16 v[112:115], v[140:143], v[194:197], v[112:115]
	v_mfma_f32_16x16x32_bf16 v[108:111], v[132:135], v[202:205], v[108:111]
	v_mfma_f32_16x16x32_bf16 v[104:107], v[140:143], v[202:205], v[104:107]
	v_mfma_f32_16x16x32_bf16 v[100:103], v[132:135], v[210:213], v[100:103]
	s_setprio 0
	v_mfma_f32_16x16x32_bf16 v[96:99], v[140:143], v[210:213], v[96:99]
	s_barrier
	s_add_i32 s44, 0, 0x14000
	s_add_i32 s20, s43, s31
	v_lshl_add_u64 v[218:219], s[24:25], 0, v[188:189]
	s_mov_b32 m0, s20
	ds_read_b128 v[214:217], v226 offset:16384
	ds_read_b128 v[230:233], v226 offset:17408
	ds_read_b128 v[234:237], v226 offset:18432
	ds_read_b128 v[238:241], v226 offset:19456
	global_load_lds_dwordx4 v[218:219], off
	v_lshl_add_u64 v[220:221], s[24:25], 0, v[186:187]
	s_add_i32 m0, s20, 0x2000
	s_nop 0
	global_load_lds_dwordx4 v[220:221], off
	s_waitcnt lgkmcnt(0)
	s_setprio 1
	s_barrier
	v_mfma_f32_16x16x32_bf16 v[60:63], v[214:217], v[144:147], v[60:63]
	v_mfma_f32_16x16x32_bf16 v[56:59], v[234:237], v[144:147], v[56:59]
	v_mfma_f32_16x16x32_bf16 v[52:55], v[214:217], v[152:155], v[52:55]
	v_mfma_f32_16x16x32_bf16 v[48:51], v[234:237], v[152:155], v[48:51]
	v_mfma_f32_16x16x32_bf16 v[44:47], v[214:217], v[198:201], v[44:47]
	v_mfma_f32_16x16x32_bf16 v[40:43], v[234:237], v[198:201], v[40:43]
	v_mfma_f32_16x16x32_bf16 v[36:39], v[214:217], v[206:209], v[36:39]
	v_mfma_f32_16x16x32_bf16 v[32:35], v[234:237], v[206:209], v[32:35]
	v_mfma_f32_16x16x32_bf16 v[60:63], v[230:233], v[148:151], v[60:63]
	s_mov_b32 m0, s34
	v_mfma_f32_16x16x32_bf16 v[56:59], v[238:241], v[148:151], v[56:59]
	v_lshl_add_u64 v[242:243], s[26:27], 0, v[188:189]
	v_mfma_f32_16x16x32_bf16 v[52:55], v[230:233], v[194:197], v[52:55]
	v_mfma_f32_16x16x32_bf16 v[48:51], v[238:241], v[194:197], v[48:51]
	v_mfma_f32_16x16x32_bf16 v[44:47], v[230:233], v[202:205], v[44:47]
	v_mfma_f32_16x16x32_bf16 v[40:43], v[238:241], v[202:205], v[40:43]
	v_mfma_f32_16x16x32_bf16 v[36:39], v[230:233], v[210:213], v[36:39]
	s_setprio 0
	v_mfma_f32_16x16x32_bf16 v[32:35], v[238:241], v[210:213], v[32:35]
	s_barrier
	ds_read_b128 v[144:147], v228 offset:16384
	ds_read_b128 v[148:151], v228 offset:17408
	ds_read_b128 v[152:155], v228 offset:18432
	ds_read_b128 v[194:197], v228 offset:19456
	ds_read_b128 v[198:201], v228 offset:20480
	ds_read_b128 v[202:205], v228 offset:21504
	ds_read_b128 v[206:209], v228 offset:22528
	ds_read_b128 v[210:213], v228 offset:23552
	global_load_lds_dwordx4 v[242:243], off
	v_lshl_add_u64 v[244:245], s[26:27], 0, v[186:187]
	s_mov_b32 m0, s35
	s_nop 0
	global_load_lds_dwordx4 v[244:245], off
	s_waitcnt lgkmcnt(0)
	s_setprio 1
	s_barrier
	v_mfma_f32_16x16x32_bf16 v[92:95], v[128:131], v[144:147], v[92:95]
	v_mfma_f32_16x16x32_bf16 v[88:91], v[136:139], v[144:147], v[88:91]
	v_mfma_f32_16x16x32_bf16 v[84:87], v[128:131], v[152:155], v[84:87]
	v_mfma_f32_16x16x32_bf16 v[80:83], v[136:139], v[152:155], v[80:83]
	v_mfma_f32_16x16x32_bf16 v[76:79], v[128:131], v[198:201], v[76:79]
	v_mfma_f32_16x16x32_bf16 v[72:75], v[136:139], v[198:201], v[72:75]
	v_mfma_f32_16x16x32_bf16 v[68:71], v[128:131], v[206:209], v[68:71]
	v_mfma_f32_16x16x32_bf16 v[64:67], v[136:139], v[206:209], v[64:67]
	v_mfma_f32_16x16x32_bf16 v[92:95], v[132:135], v[148:151], v[92:95]
	v_mfma_f32_16x16x32_bf16 v[88:91], v[140:143], v[148:151], v[88:91]
	v_mfma_f32_16x16x32_bf16 v[84:87], v[132:135], v[194:197], v[84:87]
	v_mfma_f32_16x16x32_bf16 v[80:83], v[140:143], v[194:197], v[80:83]
	v_mfma_f32_16x16x32_bf16 v[76:79], v[132:135], v[202:205], v[76:79]
	v_mfma_f32_16x16x32_bf16 v[72:75], v[140:143], v[202:205], v[72:75]
	v_mfma_f32_16x16x32_bf16 v[68:71], v[132:135], v[210:213], v[68:71]
	s_setprio 0
	v_mfma_f32_16x16x32_bf16 v[64:67], v[140:143], v[210:213], v[64:67]
	s_barrier
; #define PG8_STAGE(bufoff, gbase) do { _Pragma("unroll") for (int _i = 0; _i < 2; ++_i) \
;         __builtin_amdgcn_global_load_lds((const unsigned*)((const char*)(gbase) + voff[_i]), (LAS unsigned*)(lds + (bufoff) + ldsw + _i * 8192), 16, 0, 0); } while (0)
; #define PG8_LDA(dst, b, h) do { _Pragma("unroll") for (int m = 0; m < 4; ++m) _Pragma("unroll") for (int k = 0; k < 2; ++k) dst[m][k] = *(const LAS bf16x8*)(lds + PG8_SA(b, h) + aoff + m * 2048 + k * 1024); } while (0)
; #define PG8_LDB(dst, b, h) do { _Pragma("unroll") for (int n = 0; n < 2; ++n) _Pragma("unroll") for (int k = 0; k < 2; ++k) dst[n][k] = *(const LAS bf16x8*)(lds + PG8_SB(b, h) + boff + n * 2048 + k * 1024); } while (0)
; #define PG8_MMA(ai, bj, At, Bt) do { __builtin_amdgcn_s_setprio(1); _Pragma("unroll") for (int m = 0; m < 4; ++m) _Pragma("unroll") for (int n = 0; n < 2; ++n) _Pragma("unroll") for (int k = 0; k < 2; ++k) \
;         acc[ai][bj][m][n] = __builtin_amdgcn_mfma_f32_16x16x32_bf16(Bt[n][k], At[m][k], acc[ai][bj][m][n], 0, 0, 0); __builtin_amdgcn_s_setprio(0); } while (0)
; #define PG8_WAIT_V(n) asm volatile("s_waitcnt vmcnt(" #n ")" ::: "memory")
; #define PG8_WAIT_L(n) asm volatile("s_waitcnt lgkmcnt(" #n ")" ::: "memory")
; #define PG8_BAR __builtin_amdgcn_s_barrier()
; #define PG8_SCHED __builtin_amdgcn_sched_barrier(0)
; template <class Epi>
; DI void gemm_phase(LAS unsigned char* lds, const Gemm g, const StaticOrder& S, const Epi& E) {
;     ...
;             PG8_STAGE(PG8_SB(0, 1), b2 + hstep);
;             PG8_WAIT_V(6); PG8_BAR; PG8_MMA(1, 1, At, B1); PG8_BAR;
;             PG8_LDB(B0, 1, 0); PG8_SCHED; PG8_LDA(At, 1, 0); PG8_STAGE(PG8_SA(0, 1), a2 + hstep);
;             PG8_WAIT_L(8); PG8_BAR; PG8_WAIT_L(0); PG8_MMA(0, 0, At, B0); PG8_BAR; PG8_SCHED;
;             PG8_LDB(B1, 1, 1); PG8_STAGE(PG8_SB(1, 0), b3);
;             PG8_BAR; PG8_WAIT_L(0); PG8_MMA(0, 1, At, B1); PG8_BAR;
;             PG8_LDA(At, 1, 1); PG8_STAGE(PG8_SA(1, 0), a3);
	s_add_u32 s20, s24, 0x90000
	s_addc_u32 s21, s25, 0
	s_add_i32 s43, s44, s31
	s_mov_b32 m0, s43
	s_nop 0
	global_load_lds_dwordx4 v188, s[20:21]
	s_add_i32 m0, s43, 0x2000
	s_nop 0
	global_load_lds_dwordx4 v186, s[20:21]
	s_waitcnt vmcnt(6)
	s_setprio 1
	s_barrier
	v_mfma_f32_16x16x32_bf16 v[28:31], v[214:217], v[144:147], v[28:31]
	v_mfma_f32_16x16x32_bf16 v[24:27], v[234:237], v[144:147], v[24:27]
	v_mfma_f32_16x16x32_bf16 v[20:23], v[214:217], v[152:155], v[20:23]
	v_mfma_f32_16x16x32_bf16 v[16:19], v[234:237], v[152:155], v[16:19]
	v_mfma_f32_16x16x32_bf16 v[12:15], v[214:217], v[198:201], v[12:15]
	v_mfma_f32_16x16x32_bf16 v[8:11], v[234:237], v[198:201], v[8:11]
	v_mfma_f32_16x16x32_bf16 v[4:7], v[214:217], v[206:209], v[4:7]
	v_mfma_f32_16x16x32_bf16 v[0:3], v[234:237], v[206:209], v[0:3]
	v_mfma_f32_16x16x32_bf16 v[28:31], v[230:233], v[148:151], v[28:31]
	s_add_i32 s43, 0, 0x18000
	v_mfma_f32_16x16x32_bf16 v[24:27], v[238:241], v[148:151], v[24:27]
	v_mfma_f32_16x16x32_bf16 v[20:23], v[230:233], v[194:197], v[20:23]
	v_mfma_f32_16x16x32_bf16 v[16:19], v[238:241], v[194:197], v[16:19]
	v_mfma_f32_16x16x32_bf16 v[12:15], v[230:233], v[202:205], v[12:15]
	v_mfma_f32_16x16x32_bf16 v[8:11], v[238:241], v[202:205], v[8:11]
	v_mfma_f32_16x16x32_bf16 v[4:7], v[230:233], v[210:213], v[4:7]
	s_setprio 0
	v_mfma_f32_16x16x32_bf16 v[0:3], v[238:241], v[210:213], v[0:3]
	s_barrier
	ds_read_b128 v[128:131], v226 offset:32768
	ds_read_b128 v[132:135], v226 offset:33792
	ds_read_b128 v[136:139], v226 offset:34816
	ds_read_b128 v[140:143], v226 offset:35840
	s_add_u32 s20, s26, 0x90000
	s_addc_u32 s21, s27, 0
	s_mov_b32 m0, s36
	ds_read_b128 v[144:147], v228 offset:32768
	ds_read_b128 v[148:151], v228 offset:33792
	ds_read_b128 v[152:155], v228 offset:34816
	ds_read_b128 v[194:197], v228 offset:35840
	ds_read_b128 v[198:201], v228 offset:36864
	ds_read_b128 v[202:205], v228 offset:37888
	ds_read_b128 v[206:209], v228 offset:38912
	ds_read_b128 v[210:213], v228 offset:39936
	global_load_lds_dwordx4 v188, s[20:21]
	s_mov_b32 m0, s37
	s_nop 0
	global_load_lds_dwordx4 v186, s[20:21]
	s_waitcnt lgkmcnt(8)
	s_setprio 1
	s_barrier
	s_waitcnt lgkmcnt(0)
	v_mfma_f32_16x16x32_bf16 v[124:127], v[128:131], v[144:147], v[124:127]
	v_mfma_f32_16x16x32_bf16 v[120:123], v[136:139], v[144:147], v[120:123]
	v_mfma_f32_16x16x32_bf16 v[116:119], v[128:131], v[152:155], v[116:119]
	v_mfma_f32_16x16x32_bf16 v[112:115], v[136:139], v[152:155], v[112:115]
	v_mfma_f32_16x16x32_bf16 v[108:111], v[128:131], v[198:201], v[108:111]
	v_mfma_f32_16x16x32_bf16 v[104:107], v[136:139], v[198:201], v[104:107]
	v_mfma_f32_16x16x32_bf16 v[100:103], v[128:131], v[206:209], v[100:103]
	v_mfma_f32_16x16x32_bf16 v[96:99], v[136:139], v[206:209], v[96:99]
	v_mfma_f32_16x16x32_bf16 v[124:127], v[132:135], v[148:151], v[124:127]
	v_mfma_f32_16x16x32_bf16 v[120:123], v[140:143], v[148:151], v[120:123]
	v_mfma_f32_16x16x32_bf16 v[116:119], v[132:135], v[194:197], v[116:119]
	v_mfma_f32_16x16x32_bf16 v[112:115], v[140:143], v[194:197], v[112:115]
	v_mfma_f32_16x16x32_bf16 v[108:111], v[132:135], v[202:205], v[108:111]
	v_mfma_f32_16x16x32_bf16 v[104:107], v[140:143], v[202:205], v[104:107]
	v_mfma_f32_16x16x32_bf16 v[100:103], v[132:135], v[210:213], v[100:103]
	s_setprio 0
	v_mfma_f32_16x16x32_bf16 v[96:99], v[140:143], v[210:213], v[96:99]
	s_barrier
	s_add_i32 s26, 0, 0x1c000
	s_add_i32 s20, s43, s31
	s_add_i32 m0, s20, 0xffffff80
	ds_read_b128 v[214:217], v226 offset:49152
	ds_read_b128 v[230:233], v226 offset:50176
	ds_read_b128 v[234:237], v226 offset:51200
	ds_read_b128 v[238:241], v226 offset:52224
	global_load_lds_dwordx4 v[218:219], off offset:128
	s_add_i32 m0, s20, 0x1f80
	s_nop 0
	global_load_lds_dwordx4 v[220:221], off offset:128
	s_waitcnt lgkmcnt(0)
	s_setprio 1
	s_barrier
	v_mfma_f32_16x16x32_bf16 v[60:63], v[214:217], v[144:147], v[60:63]
	v_mfma_f32_16x16x32_bf16 v[56:59], v[234:237], v[144:147], v[56:59]
	v_mfma_f32_16x16x32_bf16 v[52:55], v[214:217], v[152:155], v[52:55]
	v_mfma_f32_16x16x32_bf16 v[48:51], v[234:237], v[152:155], v[48:51]
	v_mfma_f32_16x16x32_bf16 v[44:47], v[214:217], v[198:201], v[44:47]
	v_mfma_f32_16x16x32_bf16 v[40:43], v[234:237], v[198:201], v[40:43]
	v_mfma_f32_16x16x32_bf16 v[36:39], v[214:217], v[206:209], v[36:39]
	v_mfma_f32_16x16x32_bf16 v[32:35], v[234:237], v[206:209], v[32:35]
	v_mfma_f32_16x16x32_bf16 v[60:63], v[230:233], v[148:151], v[60:63]
	s_mov_b32 m0, s38
	v_mfma_f32_16x16x32_bf16 v[56:59], v[238:241], v[148:151], v[56:59]
	v_lshl_add_u64 v[218:219], v[242:243], 0, s[94:95]
	v_mfma_f32_16x16x32_bf16 v[52:55], v[230:233], v[194:197], v[52:55]
	v_mfma_f32_16x16x32_bf16 v[48:51], v[238:241], v[194:197], v[48:51]
	v_mfma_f32_16x16x32_bf16 v[44:47], v[230:233], v[202:205], v[44:47]
	v_mfma_f32_16x16x32_bf16 v[40:43], v[238:241], v[202:205], v[40:43]
	v_mfma_f32_16x16x32_bf16 v[36:39], v[230:233], v[210:213], v[36:39]
	s_setprio 0
	v_mfma_f32_16x16x32_bf16 v[32:35], v[238:241], v[210:213], v[32:35]
	s_barrier
	ds_read_b128 v[144:147], v228 offset:49152
	ds_read_b128 v[148:151], v228 offset:50176
	ds_read_b128 v[152:155], v228 offset:51200
	ds_read_b128 v[194:197], v228 offset:52224
	ds_read_b128 v[198:201], v228 offset:53248
	ds_read_b128 v[202:205], v228 offset:54272
	ds_read_b128 v[206:209], v228 offset:55296
	ds_read_b128 v[210:213], v228 offset:56320
	global_load_lds_dwordx4 v[218:219], off
	s_add_i32 m0, s39, 0xffffff80
	s_nop 0
	global_load_lds_dwordx4 v[244:245], off offset:128
	s_waitcnt lgkmcnt(0)
	s_setprio 1
	s_barrier
; template <class Epi>
; DI void gemm_phase(LAS unsigned char* lds, const Gemm g, const StaticOrder& S, const Epi& E) {
;     ...
;             PG8_BAR; PG8_WAIT_L(0); PG8_MMA(1, 0, At, B0); PG8_BAR; PG8_SCHED;
;             PG8_STAGE(PG8_SB(1, 1), b3 + hstep);
;             PG8_WAIT_V(6); PG8_BAR; PG8_MMA(1, 1, At, B1); PG8_BAR;
;         }
;     template <bool LN, int BJ, int LO, int HI> DI void batch(const f32x4 (&acc)[2][2][4][2], unsigned row0, unsigned col0, const f32x4 (&gv)[2], const f32x4 (&bv)[2]) const {
;         f32x4 r[HI - LO]; float mean[(HI - LO) / 2], rstd[(HI - LO) / 2];
; #pragma unroll
;         for (int i = LO; i < HI; ++i) { const int ai = i >> 3, m = (i >> 1) & 3, n = i & 1; const unsigned row = row0 + ai * HALF + m * 16;
;             if (n == 0) { mean[(i - LO) >> 1] = 0.f; rstd[(i - LO) >> 1] = 1.f;
;                 if (LN) { const float2 st = *(const float2*)(stats + row * 2u); mean[(i - LO) >> 1] = st.x; rstd[(i - LO) >> 1] = st.y; } }
;             r[i - LO] = *(const f32x4*)(src + (row * (unsigned)DM + col0 + BJ * HALF + n * 16)); }
; #pragma unroll
;         for (int i = LO; i < HI; ++i) { const int ai = i >> 3, m = (i >> 1) & 3, n = i & 1; const unsigned row = row0 + ai * HALF + m * 16;
;             *(f32x4*)(Y + (row * (unsigned)DM + col0 + BJ * HALF + n * 16)) = acc[ai][BJ][m][n] + ((r[i - LO] - mean[(i - LO) >> 1]) * rstd[(i - LO) >> 1]) * gv[n] + bv[n]; }
;         __builtin_amdgcn_sched_barrier(0);
;     }
;     template <bool LN, int BJ> DI void load_gb(unsigned col0, f32x4 (&gv)[2], f32x4 (&bv)[2]) const {
; #pragma unroll
;         for (int n = 0; n < 2; ++n) {
;             if (LN) { gv[n] = *(const f32x4*)(gam + col0 + BJ * HALF + n * 16) * ALPHA; bv[n] = *(const f32x4*)(bet + col0 + BJ * HALF + n * 16) * ALPHA; }
;             else { gv[n] = (f32x4){ALPHA, ALPHA, ALPHA, ALPHA}; bv[n] = (f32x4){0.f, 0.f, 0.f, 0.f}; }
;         }
;     }
;     template <bool LN> DI void run(const f32x4 (&acc)[2][2][4][2], const Unit& u, int wr, int wc, int fr, int fq) const {
;         const unsigned row0 = u.pm * BM + wr * 64 + fr, col0 = u.pn * BM + wc * 32 + 4 * fq;
;         f32x4 gv[2], bv[2];
;         load_gb<LN, 0>(col0, gv, bv);
;         batch<LN, 0, 0, 4>(acc, row0, col0, gv, bv);
;         batch<LN, 0, 4, 8>(acc, row0, col0, gv, bv);
;         batch<LN, 0, 8, 12>(acc, row0, col0, gv, bv);
	v_mfma_f32_16x16x32_bf16 v[92:95], v[128:131], v[144:147], v[92:95]
	v_mfma_f32_16x16x32_bf16 v[88:91], v[136:139], v[144:147], v[88:91]
	v_mfma_f32_16x16x32_bf16 v[84:87], v[128:131], v[152:155], v[84:87]
	v_mfma_f32_16x16x32_bf16 v[80:83], v[136:139], v[152:155], v[80:83]
	v_mfma_f32_16x16x32_bf16 v[76:79], v[128:131], v[198:201], v[76:79]
	v_mfma_f32_16x16x32_bf16 v[72:75], v[136:139], v[198:201], v[72:75]
	v_mfma_f32_16x16x32_bf16 v[68:71], v[128:131], v[206:209], v[68:71]
	v_mfma_f32_16x16x32_bf16 v[64:67], v[136:139], v[206:209], v[64:67]
	v_mfma_f32_16x16x32_bf16 v[92:95], v[132:135], v[148:151], v[92:95]
	v_mfma_f32_16x16x32_bf16 v[88:91], v[140:143], v[148:151], v[88:91]
	v_mfma_f32_16x16x32_bf16 v[84:87], v[132:135], v[194:197], v[84:87]
	v_mfma_f32_16x16x32_bf16 v[80:83], v[140:143], v[194:197], v[80:83]
	v_mfma_f32_16x16x32_bf16 v[76:79], v[132:135], v[202:205], v[76:79]
	v_mfma_f32_16x16x32_bf16 v[72:75], v[140:143], v[202:205], v[72:75]
	v_mfma_f32_16x16x32_bf16 v[68:71], v[132:135], v[210:213], v[68:71]
	s_setprio 0
	v_mfma_f32_16x16x32_bf16 v[64:67], v[140:143], v[210:213], v[64:67]
	s_barrier
	s_add_u32 s20, s24, 0x90080
	s_addc_u32 s21, s25, 0
	s_add_i32 s24, s26, s31
	s_mov_b32 m0, s24
	s_nop 0
	global_load_lds_dwordx4 v188, s[20:21]
	s_add_i32 m0, s24, 0x2000
	s_nop 0
	global_load_lds_dwordx4 v186, s[20:21]
	s_waitcnt vmcnt(6)
	s_setprio 1
	s_barrier
	v_mfma_f32_16x16x32_bf16 v[28:31], v[214:217], v[144:147], v[28:31]
	v_mfma_f32_16x16x32_bf16 v[24:27], v[234:237], v[144:147], v[24:27]
	v_mfma_f32_16x16x32_bf16 v[20:23], v[214:217], v[152:155], v[20:23]
	v_mfma_f32_16x16x32_bf16 v[16:19], v[234:237], v[152:155], v[16:19]
	v_mfma_f32_16x16x32_bf16 v[12:15], v[214:217], v[198:201], v[12:15]
	v_mfma_f32_16x16x32_bf16 v[8:11], v[234:237], v[198:201], v[8:11]
	v_mfma_f32_16x16x32_bf16 v[4:7], v[214:217], v[206:209], v[4:7]
	v_mfma_f32_16x16x32_bf16 v[0:3], v[234:237], v[206:209], v[0:3]
	v_mfma_f32_16x16x32_bf16 v[28:31], v[230:233], v[148:151], v[28:31]
	s_add_i32 s33, s33, 2
	v_mfma_f32_16x16x32_bf16 v[24:27], v[238:241], v[148:151], v[24:27]
	s_add_u32 s4, s4, 0x100
	v_mfma_f32_16x16x32_bf16 v[20:23], v[230:233], v[194:197], v[20:23]
	s_addc_u32 s5, s5, 0
	v_mfma_f32_16x16x32_bf16 v[16:19], v[238:241], v[194:197], v[16:19]
	s_cmp_gt_u32 s33, 33
	v_mfma_f32_16x16x32_bf16 v[12:15], v[230:233], v[202:205], v[12:15]
	s_mov_b64 s[20:21], s[22:23]
	v_mfma_f32_16x16x32_bf16 v[8:11], v[238:241], v[202:205], v[8:11]
	v_mfma_f32_16x16x32_bf16 v[4:7], v[230:233], v[210:213], v[4:7]
	s_setprio 0
	v_mfma_f32_16x16x32_bf16 v[0:3], v[238:241], v[210:213], v[0:3]
	s_barrier
	s_cbranch_scc0 .LBB0_77
	v_lshl_add_u32 v206, s3, 8, v225
	v_lshl_or_b32 v158, s2, 8, v227
	v_lshlrev_b32_e32 v232, 11, v206
	s_andn2_b64 vcc, exec, s[14:15]
	v_or_b32_e32 v231, 16, v158
	v_add_u32_e32 v194, v232, v158
	v_or_b32_e32 v230, 0x80, v158
	v_or_b32_e32 v229, 0x90, v158
	s_cbranch_vccnz .LBB0_80
	v_lshlrev_b64 v[132:133], 2, v[158:159]
	v_lshl_add_u64 v[140:141], s[16:17], 0, v[132:133]
	global_load_dwordx4 v[128:131], v[140:141], off
	v_lshl_add_u64 v[142:143], s[18:19], 0, v[132:133]
	v_readlane_b32 s2, v253, 8
	v_mov_b32_e32 v195, v159
	v_lshlrev_b32_e32 v136, 1, v206
	v_mov_b32_e32 v137, v159
	v_readlane_b32 s3, v253, 9
	v_lshlrev_b64 v[212:213], 2, v[194:195]
	v_add_u32_e32 v146, v232, v231
	v_lshl_add_u64 v[144:145], v[136:137], 2, s[2:3]
	v_lshl_add_u64 v[136:137], s[88:89], 0, v[212:213]
	v_mov_b32_e32 v147, v159
	v_lshl_add_u64 v[146:147], v[146:147], 2, s[88:89]
	v_or_b32_e32 v195, 16, v206
	v_mov_b32_e32 v201, v159
	v_mov_b32_e32 v209, v159
	v_lshl_add_u64 v[212:213], s[90:91], 0, v[212:213]
	s_waitcnt vmcnt(0)
	v_pk_mul_f32 v[152:153], v[130:131], s[78:79] op_sel_hi:[1,0]
	v_pk_mul_f32 v[154:155], v[128:129], s[78:79] op_sel_hi:[1,0]
	global_load_dwordx4 v[132:135], v[142:143], off
	global_load_dwordx4 v[128:131], v[140:141], off offset:64
	global_load_dwordx2 v[204:205], v[144:145], off
	global_load_dwordx4 v[196:199], v[146:147], off
	v_lshlrev_b32_e32 v146, 1, v195
	global_load_dwordx4 v[136:139], v[136:137], off
	v_lshlrev_b32_e32 v195, 11, v195
	v_mov_b32_e32 v147, v159
	v_add_u32_e32 v200, v195, v158
	v_lshl_add_u64 v[146:147], v[146:147], 2, s[2:3]
	v_lshl_add_u64 v[200:201], v[200:201], 2, s[88:89]
	global_load_dwordx2 v[214:215], v[146:147], off
	v_add_u32_e32 v208, v195, v231
	global_load_dwordx4 v[200:203], v[200:201], off
	v_lshl_add_u64 v[208:209], v[208:209], 2, s[88:89]
	global_load_dwordx4 v[208:211], v[208:209], off
	s_waitcnt vmcnt(0)
	v_pk_mul_f32 v[148:149], v[130:131], s[78:79] op_sel_hi:[1,0]
	v_pk_mul_f32 v[150:151], v[128:129], s[78:79] op_sel_hi:[1,0]
	global_load_dwordx4 v[128:131], v[142:143], off offset:64
	v_sub_f32_e32 v137, v137, v204
	v_sub_f32_e32 v136, v136, v204
	v_sub_f32_e32 v139, v139, v204
	v_sub_f32_e32 v138, v138, v204
	v_pk_mul_f32 v[138:139], v[204:205], v[138:139] op_sel:[1,0]
	v_pk_mul_f32 v[136:137], v[204:205], v[136:137] op_sel:[1,0]
	v_pk_fma_f32 v[138:139], v[152:153], v[138:139], v[126:127]
	v_pk_fma_f32 v[136:137], v[154:155], v[136:137], v[124:125]
	v_pk_fma_f32 v[138:139], v[134:135], s[78:79], v[138:139] op_sel_hi:[1,0,1]
	v_pk_fma_f32 v[136:137], v[132:133], s[78:79], v[136:137] op_sel_hi:[1,0,1]
	global_store_dwordx4 v[212:213], v[136:139], off
	s_nop 1
	v_sub_f32_e32 v137, v197, v204
	v_sub_f32_e32 v136, v196, v204
	v_sub_f32_e32 v139, v199, v204
	v_sub_f32_e32 v138, v198, v204
	v_pk_mul_f32 v[138:139], v[204:205], v[138:139] op_sel:[1,0]
	v_pk_mul_f32 v[136:137], v[204:205], v[136:137] op_sel:[1,0]
	v_pk_fma_f32 v[138:139], v[148:149], v[138:139], v[122:123]
	v_pk_fma_f32 v[136:137], v[150:151], v[136:137], v[120:121]
	v_or_b32_e32 v196, 16, v194
	v_mov_b32_e32 v197, v159
	v_lshl_add_u64 v[196:197], v[196:197], 2, s[90:91]
	s_waitcnt vmcnt(0)
;     template <bool LN, int BJ, int LO, int HI> DI void batch(const f32x4 (&acc)[2][2][4][2], unsigned row0, unsigned col0, const f32x4 (&gv)[2], const f32x4 (&bv)[2]) const {
;         f32x4 r[HI - LO]; float mean[(HI - LO) / 2], rstd[(HI - LO) / 2];
; #pragma unroll
;         for (int i = LO; i < HI; ++i) { const int ai = i >> 3, m = (i >> 1) & 3, n = i & 1; const unsigned row = row0 + ai * HALF + m * 16;
;             if (n == 0) { mean[(i - LO) >> 1] = 0.f; rstd[(i - LO) >> 1] = 1.f;
;                 if (LN) { const float2 st = *(const float2*)(stats + row * 2u); mean[(i - LO) >> 1] = st.x; rstd[(i - LO) >> 1] = st.y; } }
;             r[i - LO] = *(const f32x4*)(src + (row * (unsigned)DM + col0 + BJ * HALF + n * 16)); }
; #pragma unroll
;         for (int i = LO; i < HI; ++i) { const int ai = i >> 3, m = (i >> 1) & 3, n = i & 1; const unsigned row = row0 + ai * HALF + m * 16;
;             *(f32x4*)(Y + (row * (unsigned)DM + col0 + BJ * HALF + n * 16)) = acc[ai][BJ][m][n] + ((r[i - LO] - mean[(i - LO) >> 1]) * rstd[(i - LO) >> 1]) * gv[n] + bv[n]; }
;         __builtin_amdgcn_sched_barrier(0);
;     }
;     template <bool LN, int BJ> DI void load_gb(unsigned col0, f32x4 (&gv)[2], f32x4 (&bv)[2]) const {
; #pragma unroll
;         for (int n = 0; n < 2; ++n) {
;             if (LN) { gv[n] = *(const f32x4*)(gam + col0 + BJ * HALF + n * 16) * ALPHA; bv[n] = *(const f32x4*)(bet + col0 + BJ * HALF + n * 16) * ALPHA; }
;             else { gv[n] = (f32x4){ALPHA, ALPHA, ALPHA, ALPHA}; bv[n] = (f32x4){0.f, 0.f, 0.f, 0.f}; }
;         }
;     }
;     template <bool LN> DI void run(const f32x4 (&acc)[2][2][4][2], const Unit& u, int wr, int wc, int fr, int fq) const {
;         const unsigned row0 = u.pm * BM + wr * 64 + fr, col0 = u.pn * BM + wc * 32 + 4 * fq;
;         f32x4 gv[2], bv[2];
;         load_gb<LN, 0>(col0, gv, bv);
;         batch<LN, 0, 0, 4>(acc, row0, col0, gv, bv);
;         batch<LN, 0, 4, 8>(acc, row0, col0, gv, bv);
	v_pk_fma_f32 v[138:139], v[130:131], s[78:79], v[138:139] op_sel_hi:[1,0,1]
	v_pk_fma_f32 v[136:137], v[128:129], s[78:79], v[136:137] op_sel_hi:[1,0,1]
	global_store_dwordx4 v[196:197], v[136:139], off
	v_add_u32_e32 v196, 0x8000, v194
	v_mov_b32_e32 v197, v159
	v_sub_f32_e32 v137, v201, v214
	v_sub_f32_e32 v136, v200, v214
	v_sub_f32_e32 v139, v203, v214
	v_sub_f32_e32 v138, v202, v214
	v_pk_mul_f32 v[138:139], v[214:215], v[138:139] op_sel:[1,0]
	v_pk_mul_f32 v[136:137], v[214:215], v[136:137] op_sel:[1,0]
	v_pk_fma_f32 v[138:139], v[152:153], v[138:139], v[118:119]
	v_pk_fma_f32 v[136:137], v[154:155], v[136:137], v[116:117]
	v_pk_fma_f32 v[138:139], v[134:135], s[78:79], v[138:139] op_sel_hi:[1,0,1]
	v_pk_fma_f32 v[136:137], v[132:133], s[78:79], v[136:137] op_sel_hi:[1,0,1]
	v_lshl_add_u64 v[196:197], v[196:197], 2, s[90:91]
	global_store_dwordx4 v[196:197], v[136:139], off
	v_add_u32_e32 v196, 0x8010, v194
	v_mov_b32_e32 v197, v159
	v_sub_f32_e32 v137, v209, v214
	v_sub_f32_e32 v136, v208, v214
	v_sub_f32_e32 v139, v211, v214
	v_sub_f32_e32 v138, v210, v214
	v_pk_mul_f32 v[138:139], v[214:215], v[138:139] op_sel:[1,0]
	v_pk_mul_f32 v[136:137], v[214:215], v[136:137] op_sel:[1,0]
	v_pk_fma_f32 v[138:139], v[148:149], v[138:139], v[114:115]
	v_pk_fma_f32 v[136:137], v[150:151], v[136:137], v[112:113]
	v_pk_fma_f32 v[138:139], v[130:131], s[78:79], v[138:139] op_sel_hi:[1,0,1]
	v_pk_fma_f32 v[136:137], v[128:129], s[78:79], v[136:137] op_sel_hi:[1,0,1]
	v_lshl_add_u64 v[196:197], v[196:197], 2, s[90:91]
	global_store_dwordx4 v[196:197], v[136:139], off
	s_nop 1
	v_or_b32_e32 v138, 32, v206
	v_lshlrev_b32_e32 v136, 1, v138
	v_mov_b32_e32 v137, v159
	v_lshlrev_b32_e32 v236, 11, v138
	v_lshl_add_u64 v[200:201], v[136:137], 2, s[2:3]
	v_add_u32_e32 v136, v236, v158
	v_lshl_add_u64 v[136:137], v[136:137], 2, s[88:89]
	global_load_dwordx2 v[204:205], v[200:201], off
	v_add_u32_e32 v196, v236, v231
	global_load_dwordx4 v[136:139], v[136:137], off
	v_mov_b32_e32 v197, v159
	v_lshl_add_u64 v[196:197], v[196:197], 2, s[88:89]
	global_load_dwordx4 v[196:199], v[196:197], off
	v_or_b32_e32 v207, 48, v206
	v_lshlrev_b32_e32 v235, 11, v207
	v_lshlrev_b32_e32 v202, 1, v207
	v_mov_b32_e32 v203, v159
	v_add_u32_e32 v208, v235, v158
	v_mov_b32_e32 v209, v159
	v_lshl_add_u64 v[202:203], v[202:203], 2, s[2:3]
	v_lshl_add_u64 v[208:209], v[208:209], 2, s[88:89]
	global_load_dwordx2 v[216:217], v[202:203], off
	v_add_u32_e32 v212, v235, v231
	global_load_dwordx4 v[208:211], v[208:209], off
	v_mov_b32_e32 v213, v159
	v_lshl_add_u64 v[212:213], v[212:213], 2, s[88:89]
	global_load_dwordx4 v[212:215], v[212:213], off
	v_add_u32_e32 v218, 0x10000, v194
	v_mov_b32_e32 v219, v159
	v_lshl_add_u64 v[218:219], v[218:219], 2, s[90:91]
	s_waitcnt vmcnt(0)
	v_sub_f32_e32 v137, v137, v204
	v_sub_f32_e32 v136, v136, v204
	v_sub_f32_e32 v139, v139, v204
	v_sub_f32_e32 v138, v138, v204
	v_pk_mul_f32 v[138:139], v[204:205], v[138:139] op_sel:[1,0]
	v_pk_mul_f32 v[136:137], v[204:205], v[136:137] op_sel:[1,0]
	v_pk_fma_f32 v[138:139], v[152:153], v[138:139], v[110:111]
	v_pk_fma_f32 v[136:137], v[154:155], v[136:137], v[108:109]
	v_pk_fma_f32 v[138:139], v[134:135], s[78:79], v[138:139] op_sel_hi:[1,0,1]
	v_pk_fma_f32 v[136:137], v[132:133], s[78:79], v[136:137] op_sel_hi:[1,0,1]
	global_store_dwordx4 v[218:219], v[136:139], off
	s_nop 1
	v_sub_f32_e32 v137, v197, v204
	v_sub_f32_e32 v136, v196, v204
	v_sub_f32_e32 v139, v199, v204
	v_sub_f32_e32 v138, v198, v204
	v_pk_mul_f32 v[138:139], v[204:205], v[138:139] op_sel:[1,0]
	v_pk_mul_f32 v[136:137], v[204:205], v[136:137] op_sel:[1,0]
	v_pk_fma_f32 v[138:139], v[148:149], v[138:139], v[106:107]
	v_pk_fma_f32 v[136:137], v[150:151], v[136:137], v[104:105]
	v_add_u32_e32 v196, 0x10010, v194
	v_mov_b32_e32 v197, v159
	v_pk_fma_f32 v[138:139], v[130:131], s[78:79], v[138:139] op_sel_hi:[1,0,1]
	v_pk_fma_f32 v[136:137], v[128:129], s[78:79], v[136:137] op_sel_hi:[1,0,1]
	v_lshl_add_u64 v[196:197], v[196:197], 2, s[90:91]
	global_store_dwordx4 v[196:197], v[136:139], off
	v_add_u32_e32 v196, 0x18000, v194
	v_mov_b32_e32 v197, v159
	v_sub_f32_e32 v137, v209, v216
	v_sub_f32_e32 v136, v208, v216
	v_sub_f32_e32 v139, v211, v216
	v_sub_f32_e32 v138, v210, v216
	v_pk_mul_f32 v[138:139], v[216:217], v[138:139] op_sel:[1,0]
	v_pk_mul_f32 v[136:137], v[216:217], v[136:137] op_sel:[1,0]
	v_pk_fma_f32 v[138:139], v[152:153], v[138:139], v[102:103]
	v_pk_fma_f32 v[136:137], v[154:155], v[136:137], v[100:101]
	v_pk_fma_f32 v[138:139], v[134:135], s[78:79], v[138:139] op_sel_hi:[1,0,1]
	v_pk_fma_f32 v[136:137], v[132:133], s[78:79], v[136:137] op_sel_hi:[1,0,1]
	v_lshl_add_u64 v[196:197], v[196:197], 2, s[90:91]
	global_store_dwordx4 v[196:197], v[136:139], off
	v_add_u32_e32 v196, 0x18010, v194
	v_mov_b32_e32 v197, v159
	v_sub_f32_e32 v137, v213, v216
	v_sub_f32_e32 v136, v212, v216
	v_sub_f32_e32 v139, v215, v216
	v_sub_f32_e32 v138, v214, v216
	v_pk_mul_f32 v[138:139], v[216:217], v[138:139] op_sel:[1,0]
	v_pk_mul_f32 v[136:137], v[216:217], v[136:137] op_sel:[1,0]
	v_pk_fma_f32 v[138:139], v[148:149], v[138:139], v[98:99]
	v_pk_fma_f32 v[136:137], v[150:151], v[136:137], v[96:97]
	v_pk_fma_f32 v[138:139], v[130:131], s[78:79], v[138:139] op_sel_hi:[1,0,1]
	v_pk_fma_f32 v[136:137], v[128:129], s[78:79], v[136:137] op_sel_hi:[1,0,1]
	v_lshl_add_u64 v[196:197], v[196:197], 2, s[90:91]
	global_store_dwordx4 v[196:197], v[136:139], off
	s_nop 1
	v_add_u32_e32 v138, 0x80, v206
	v_lshlrev_b32_e32 v136, 1, v138
	v_mov_b32_e32 v137, v159
	v_lshlrev_b32_e32 v233, 11, v138
	v_lshl_add_u64 v[196:197], v[136:137], 2, s[2:3]
	v_add_u32_e32 v136, v233, v158
	v_lshl_add_u64 v[136:137], v[136:137], 2, s[88:89]
	global_load_dwordx2 v[204:205], v[196:197], off
	v_add_u32_e32 v198, v233, v231
	global_load_dwordx4 v[136:139], v[136:137], off
	v_mov_b32_e32 v199, v159
	v_add_u32_e32 v207, 0x90, v206
	v_lshl_add_u64 v[198:199], v[198:199], 2, s[88:89]
	v_lshlrev_b32_e32 v234, 11, v207
	global_load_dwordx4 v[208:211], v[198:199], off
	v_add_u32_e32 v212, v234, v158
	v_mov_b32_e32 v213, v159
	v_lshl_add_u64 v[212:213], v[212:213], 2, s[88:89]
	global_load_dwordx4 v[212:215], v[212:213], off
	v_lshlrev_b32_e32 v198, 1, v207
	v_mov_b32_e32 v199, v159
	v_lshl_add_u64 v[198:199], v[198:199], 2, s[2:3]
	global_load_dwordx2 v[220:221], v[198:199], off
	v_add_u32_e32 v216, v234, v231
	v_mov_b32_e32 v217, v159
	v_lshl_add_u64 v[216:217], v[216:217], 2, s[88:89]
	global_load_dwordx4 v[216:219], v[216:217], off
	v_add_u32_e32 v238, 0x40000, v194
	v_mov_b32_e32 v239, v159
	v_lshl_add_u64 v[238:239], v[238:239], 2, s[90:91]
	s_waitcnt vmcnt(0)
;     template <bool LN, int BJ, int LO, int HI> DI void batch(const f32x4 (&acc)[2][2][4][2], unsigned row0, unsigned col0, const f32x4 (&gv)[2], const f32x4 (&bv)[2]) const {
;         f32x4 r[HI - LO]; float mean[(HI - LO) / 2], rstd[(HI - LO) / 2];
; #pragma unroll
;         for (int i = LO; i < HI; ++i) { const int ai = i >> 3, m = (i >> 1) & 3, n = i & 1; const unsigned row = row0 + ai * HALF + m * 16;
;             if (n == 0) { mean[(i - LO) >> 1] = 0.f; rstd[(i - LO) >> 1] = 1.f;
;                 if (LN) { const float2 st = *(const float2*)(stats + row * 2u); mean[(i - LO) >> 1] = st.x; rstd[(i - LO) >> 1] = st.y; } }
;             r[i - LO] = *(const f32x4*)(src + (row * (unsigned)DM + col0 + BJ * HALF + n * 16)); }
; #pragma unroll
;         for (int i = LO; i < HI; ++i) { const int ai = i >> 3, m = (i >> 1) & 3, n = i & 1; const unsigned row = row0 + ai * HALF + m * 16;
;             *(f32x4*)(Y + (row * (unsigned)DM + col0 + BJ * HALF + n * 16)) = acc[ai][BJ][m][n] + ((r[i - LO] - mean[(i - LO) >> 1]) * rstd[(i - LO) >> 1]) * gv[n] + bv[n]; }
;         __builtin_amdgcn_sched_barrier(0);
;     }
;     template <bool LN, int BJ> DI void load_gb(unsigned col0, f32x4 (&gv)[2], f32x4 (&bv)[2]) const {
; #pragma unroll
;         for (int n = 0; n < 2; ++n) {
;             if (LN) { gv[n] = *(const f32x4*)(gam + col0 + BJ * HALF + n * 16) * ALPHA; bv[n] = *(const f32x4*)(bet + col0 + BJ * HALF + n * 16) * ALPHA; }
;             else { gv[n] = (f32x4){ALPHA, ALPHA, ALPHA, ALPHA}; bv[n] = (f32x4){0.f, 0.f, 0.f, 0.f}; }
;         }
;     }
;     template <bool LN> DI void run(const f32x4 (&acc)[2][2][4][2], const Unit& u, int wr, int wc, int fr, int fq) const {
;         const unsigned row0 = u.pm * BM + wr * 64 + fr, col0 = u.pn * BM + wc * 32 + 4 * fq;
;         f32x4 gv[2], bv[2];
;         load_gb<LN, 0>(col0, gv, bv);
;         batch<LN, 0, 0, 4>(acc, row0, col0, gv, bv);
;         batch<LN, 0, 4, 8>(acc, row0, col0, gv, bv);
	v_sub_f32_e32 v137, v137, v204
	v_sub_f32_e32 v136, v136, v204
	v_sub_f32_e32 v139, v139, v204
	v_sub_f32_e32 v138, v138, v204
	v_pk_mul_f32 v[138:139], v[204:205], v[138:139] op_sel:[1,0]
	v_pk_mul_f32 v[136:137], v[204:205], v[136:137] op_sel:[1,0]
	v_pk_fma_f32 v[138:139], v[152:153], v[138:139], v[94:95]
	v_pk_fma_f32 v[136:137], v[154:155], v[136:137], v[92:93]
	v_pk_fma_f32 v[138:139], v[134:135], s[78:79], v[138:139] op_sel_hi:[1,0,1]
	v_pk_fma_f32 v[136:137], v[132:133], s[78:79], v[136:137] op_sel_hi:[1,0,1]
	global_store_dwordx4 v[238:239], v[136:139], off
	s_nop 1
	v_sub_f32_e32 v137, v209, v204
	v_sub_f32_e32 v136, v208, v204
	v_sub_f32_e32 v139, v211, v204
	v_sub_f32_e32 v138, v210, v204
	v_pk_mul_f32 v[138:139], v[204:205], v[138:139] op_sel:[1,0]
	v_pk_mul_f32 v[136:137], v[204:205], v[136:137] op_sel:[1,0]
	v_pk_fma_f32 v[138:139], v[148:149], v[138:139], v[90:91]
	v_pk_fma_f32 v[136:137], v[150:151], v[136:137], v[88:89]
	v_add_u32_e32 v204, 0x40010, v194
	v_mov_b32_e32 v205, v159
	v_pk_fma_f32 v[138:139], v[130:131], s[78:79], v[138:139] op_sel_hi:[1,0,1]
	v_pk_fma_f32 v[136:137], v[128:129], s[78:79], v[136:137] op_sel_hi:[1,0,1]
	v_lshl_add_u64 v[204:205], v[204:205], 2, s[90:91]
	global_store_dwordx4 v[204:205], v[136:139], off
	v_add_u32_e32 v204, 0x48000, v194
	v_mov_b32_e32 v205, v159
	v_sub_f32_e32 v137, v213, v220
	v_sub_f32_e32 v136, v212, v220
	v_sub_f32_e32 v139, v215, v220
	v_sub_f32_e32 v138, v214, v220
	v_pk_mul_f32 v[138:139], v[220:221], v[138:139] op_sel:[1,0]
	v_pk_mul_f32 v[136:137], v[220:221], v[136:137] op_sel:[1,0]
	v_pk_fma_f32 v[138:139], v[152:153], v[138:139], v[86:87]
	v_pk_fma_f32 v[136:137], v[154:155], v[136:137], v[84:85]
	v_pk_fma_f32 v[138:139], v[134:135], s[78:79], v[138:139] op_sel_hi:[1,0,1]
	v_pk_fma_f32 v[136:137], v[132:133], s[78:79], v[136:137] op_sel_hi:[1,0,1]
	v_lshl_add_u64 v[204:205], v[204:205], 2, s[90:91]
	global_store_dwordx4 v[204:205], v[136:139], off
	v_add_u32_e32 v204, 0x48010, v194
	v_mov_b32_e32 v205, v159
	v_sub_f32_e32 v137, v217, v220
	v_sub_f32_e32 v136, v216, v220
	v_sub_f32_e32 v139, v219, v220
	v_sub_f32_e32 v138, v218, v220
	v_pk_mul_f32 v[138:139], v[220:221], v[138:139] op_sel:[1,0]
	v_pk_mul_f32 v[136:137], v[220:221], v[136:137] op_sel:[1,0]
	v_pk_fma_f32 v[138:139], v[148:149], v[138:139], v[82:83]
	v_pk_fma_f32 v[136:137], v[150:151], v[136:137], v[80:81]
	v_pk_fma_f32 v[138:139], v[130:131], s[78:79], v[138:139] op_sel_hi:[1,0,1]
	v_pk_fma_f32 v[136:137], v[128:129], s[78:79], v[136:137] op_sel_hi:[1,0,1]
	v_lshl_add_u64 v[204:205], v[204:205], 2, s[90:91]
	global_store_dwordx4 v[204:205], v[136:139], off
	s_nop 1
	v_add_u32_e32 v138, 0xa0, v206
	v_lshlrev_b32_e32 v136, 1, v138
	v_mov_b32_e32 v137, v159
	v_lshlrev_b32_e32 v237, 11, v138
	v_lshl_add_u64 v[204:205], v[136:137], 2, s[2:3]
	v_add_u32_e32 v136, v237, v158
	v_lshl_add_u64 v[136:137], v[136:137], 2, s[88:89]
	global_load_dwordx2 v[220:221], v[204:205], off
	v_add_u32_e32 v208, v237, v231
	global_load_dwordx4 v[136:139], v[136:137], off
	v_mov_b32_e32 v209, v159
	v_lshl_add_u64 v[208:209], v[208:209], 2, s[88:89]
	global_load_dwordx4 v[212:215], v[208:209], off
	v_add_u32_e32 v208, 0xb0, v206
	v_lshlrev_b32_e32 v206, 1, v208
	v_mov_b32_e32 v207, v159
	v_lshlrev_b32_e32 v238, 11, v208
	v_lshl_add_u64 v[210:211], v[206:207], 2, s[2:3]
	v_add_u32_e32 v206, v238, v158
	v_lshl_add_u64 v[206:207], v[206:207], 2, s[88:89]
	global_load_dwordx2 v[240:241], v[210:211], off
	v_add_u32_e32 v216, v238, v231
	global_load_dwordx4 v[206:209], v[206:207], off
	v_mov_b32_e32 v217, v159
	v_lshl_add_u64 v[216:217], v[216:217], 2, s[88:89]
	global_load_dwordx4 v[216:219], v[216:217], off
	v_add_u32_e32 v242, 0x50000, v194
	v_mov_b32_e32 v243, v159
	v_lshl_add_u64 v[242:243], v[242:243], 2, s[90:91]
	s_waitcnt vmcnt(0)
	v_sub_f32_e32 v137, v137, v220
	v_sub_f32_e32 v136, v136, v220
	v_sub_f32_e32 v139, v139, v220
	v_sub_f32_e32 v138, v138, v220
	v_pk_mul_f32 v[138:139], v[220:221], v[138:139] op_sel:[1,0]
	v_pk_mul_f32 v[136:137], v[220:221], v[136:137] op_sel:[1,0]
	v_pk_fma_f32 v[138:139], v[152:153], v[138:139], v[78:79]
	v_pk_fma_f32 v[136:137], v[154:155], v[136:137], v[76:77]
	v_pk_fma_f32 v[138:139], v[134:135], s[78:79], v[138:139] op_sel_hi:[1,0,1]
	v_pk_fma_f32 v[136:137], v[132:133], s[78:79], v[136:137] op_sel_hi:[1,0,1]
	global_store_dwordx4 v[242:243], v[136:139], off
	s_nop 1
	v_sub_f32_e32 v137, v213, v220
	v_sub_f32_e32 v136, v212, v220
	v_sub_f32_e32 v139, v215, v220
	v_sub_f32_e32 v138, v214, v220
	v_pk_mul_f32 v[138:139], v[220:221], v[138:139] op_sel:[1,0]
	v_pk_mul_f32 v[136:137], v[220:221], v[136:137] op_sel:[1,0]
	v_pk_fma_f32 v[138:139], v[148:149], v[138:139], v[74:75]
	v_pk_fma_f32 v[136:137], v[150:151], v[136:137], v[72:73]
	v_add_u32_e32 v212, 0x50010, v194
	v_mov_b32_e32 v213, v159
	v_pk_fma_f32 v[138:139], v[130:131], s[78:79], v[138:139] op_sel_hi:[1,0,1]
	v_pk_fma_f32 v[136:137], v[128:129], s[78:79], v[136:137] op_sel_hi:[1,0,1]
	v_lshl_add_u64 v[212:213], v[212:213], 2, s[90:91]
	global_store_dwordx4 v[212:213], v[136:139], off
	s_nop 1
	v_sub_f32_e32 v137, v207, v240
	v_sub_f32_e32 v136, v206, v240
	v_sub_f32_e32 v139, v209, v240
	v_sub_f32_e32 v138, v208, v240
	v_pk_mul_f32 v[136:137], v[240:241], v[136:137] op_sel:[1,0]
	v_pk_mul_f32 v[138:139], v[240:241], v[138:139] op_sel:[1,0]
	v_pk_fma_f32 v[136:137], v[154:155], v[136:137], v[68:69]
	v_pk_fma_f32 v[138:139], v[152:153], v[138:139], v[70:71]
	v_pk_fma_f32 v[132:133], v[132:133], s[78:79], v[136:137] op_sel_hi:[1,0,1]
	v_add_u32_e32 v136, 0x58000, v194
	v_mov_b32_e32 v137, v159
	v_pk_fma_f32 v[134:135], v[134:135], s[78:79], v[138:139] op_sel_hi:[1,0,1]
	v_lshl_add_u64 v[136:137], v[136:137], 2, s[90:91]
	global_store_dwordx4 v[136:137], v[132:135], off
	s_nop 1
	v_sub_f32_e32 v133, v217, v240
	v_sub_f32_e32 v132, v216, v240
	v_sub_f32_e32 v135, v219, v240
	v_sub_f32_e32 v134, v218, v240
	v_pk_mul_f32 v[132:133], v[240:241], v[132:133] op_sel:[1,0]
	v_pk_mul_f32 v[134:135], v[240:241], v[134:135] op_sel:[1,0]
	v_pk_fma_f32 v[132:133], v[150:151], v[132:133], v[64:65]
	v_pk_fma_f32 v[134:135], v[148:149], v[134:135], v[66:67]
	v_pk_fma_f32 v[128:129], v[128:129], s[78:79], v[132:133] op_sel_hi:[1,0,1]
	v_add_u32_e32 v132, 0x58010, v194
	v_mov_b32_e32 v133, v159
	v_pk_fma_f32 v[130:131], v[130:131], s[78:79], v[134:135] op_sel_hi:[1,0,1]
	v_lshl_add_u64 v[132:133], v[132:133], 2, s[90:91]
	global_store_dwordx4 v[132:133], v[128:131], off
	global_load_dwordx4 v[128:131], v[140:141], off offset:512
	v_add_u32_e32 v136, v232, v230
	v_mov_b32_e32 v137, v159
	v_lshl_add_u64 v[136:137], v[136:137], 2, s[88:89]
	s_waitcnt vmcnt(0)
;     template <bool LN, int BJ> DI void load_gb(unsigned col0, f32x4 (&gv)[2], f32x4 (&bv)[2]) const {
; #pragma unroll
;         for (int n = 0; n < 2; ++n) {
;             if (LN) { gv[n] = *(const f32x4*)(gam + col0 + BJ * HALF + n * 16) * ALPHA; bv[n] = *(const f32x4*)(bet + col0 + BJ * HALF + n * 16) * ALPHA; }
;             else { gv[n] = (f32x4){ALPHA, ALPHA, ALPHA, ALPHA}; bv[n] = (f32x4){0.f, 0.f, 0.f, 0.f}; }
;         }
;     }
;     template <bool LN> DI void run(const f32x4 (&acc)[2][2][4][2], const Unit& u, int wr, int wc, int fr, int fq) const {
;         const unsigned row0 = u.pm * BM + wr * 64 + fr, col0 = u.pn * BM + wc * 32 + 4 * fq;
;         f32x4 gv[2], bv[2];
;         load_gb<LN, 0>(col0, gv, bv);
;         batch<LN, 0, 0, 4>(acc, row0, col0, gv, bv);
;         batch<LN, 0, 4, 8>(acc, row0, col0, gv, bv);
	v_pk_mul_f32 v[212:213], v[130:131], s[78:79] op_sel_hi:[1,0]
	v_pk_mul_f32 v[214:215], v[128:129], s[78:79] op_sel_hi:[1,0]
	global_load_dwordx4 v[132:135], v[142:143], off offset:512
	global_load_dwordx4 v[128:131], v[140:141], off offset:576
	s_waitcnt vmcnt(0)
	v_pk_mul_f32 v[206:207], v[130:131], s[78:79] op_sel_hi:[1,0]
	v_pk_mul_f32 v[208:209], v[128:129], s[78:79] op_sel_hi:[1,0]
	global_load_dwordx4 v[128:131], v[142:143], off offset:576
	global_load_dwordx2 v[220:221], v[144:145], off
	global_load_dwordx4 v[240:243], v[136:137], off
	v_add_u32_e32 v136, v232, v229
	v_mov_b32_e32 v137, v159
	v_lshl_add_u64 v[136:137], v[136:137], 2, s[88:89]
	global_load_dwordx4 v[244:247], v[136:137], off
	global_load_dwordx2 v[218:219], v[146:147], off
	v_add_u32_e32 v136, v195, v230
	v_mov_b32_e32 v137, v159
	v_lshl_add_u64 v[136:137], v[136:137], 2, s[88:89]
	global_load_dwordx4 v[248:251], v[136:137], off
	v_add_u32_e32 v136, v195, v229
	v_mov_b32_e32 v137, v159
	v_lshl_add_u64 v[136:137], v[136:137], 2, s[88:89]
	global_load_dwordx4 v[152:155], v[136:137], off
	global_load_dwordx2 v[216:217], v[200:201], off
	v_add_u32_e32 v136, v236, v230
	v_mov_b32_e32 v137, v159
	v_lshl_add_u64 v[136:137], v[136:137], 2, s[88:89]
	global_load_dwordx4 v[148:151], v[136:137], off
	v_add_u32_e32 v136, v236, v229
	v_mov_b32_e32 v137, v159
	v_lshl_add_u64 v[136:137], v[136:137], 2, s[88:89]
	global_load_dwordx4 v[144:147], v[136:137], off
	global_load_dwordx2 v[200:201], v[202:203], off
	v_add_u32_e32 v136, v235, v230
	v_mov_b32_e32 v137, v159
	v_lshl_add_u64 v[136:137], v[136:137], 2, s[88:89]
	global_load_dwordx4 v[140:143], v[136:137], off
	v_add_u32_e32 v136, v235, v229
	v_mov_b32_e32 v137, v159
	v_lshl_add_u64 v[136:137], v[136:137], 2, s[88:89]
	global_load_dwordx4 v[136:139], v[136:137], off
	v_add_u32_e32 v202, 0x80, v194
	v_mov_b32_e32 v203, v159
	v_lshl_add_u64 v[202:203], v[202:203], 2, s[90:91]
	s_waitcnt vmcnt(0)
	v_sub_f32_e32 v241, v241, v220
	v_sub_f32_e32 v240, v240, v220
	v_sub_f32_e32 v243, v243, v220
	v_sub_f32_e32 v242, v242, v220
	v_pk_mul_f32 v[242:243], v[220:221], v[242:243] op_sel:[1,0]
	v_pk_mul_f32 v[240:241], v[220:221], v[240:241] op_sel:[1,0]
	v_pk_fma_f32 v[242:243], v[212:213], v[242:243], v[62:63]
	v_pk_fma_f32 v[240:241], v[214:215], v[240:241], v[60:61]
	v_pk_fma_f32 v[242:243], v[134:135], s[78:79], v[242:243] op_sel_hi:[1,0,1]
	v_pk_fma_f32 v[240:241], v[132:133], s[78:79], v[240:241] op_sel_hi:[1,0,1]
	global_store_dwordx4 v[202:203], v[240:243], off
	v_sub_f32_e32 v203, v245, v220
	v_sub_f32_e32 v202, v244, v220
	v_sub_f32_e32 v241, v247, v220
	v_sub_f32_e32 v240, v246, v220
	v_pk_mul_f32 v[202:203], v[220:221], v[202:203] op_sel:[1,0]
	v_pk_mul_f32 v[240:241], v[220:221], v[240:241] op_sel:[1,0]
	v_pk_fma_f32 v[202:203], v[208:209], v[202:203], v[56:57]
	v_pk_fma_f32 v[220:221], v[206:207], v[240:241], v[58:59]
	v_pk_fma_f32 v[240:241], v[128:129], s[78:79], v[202:203] op_sel_hi:[1,0,1]
	v_add_u32_e32 v202, 0x90, v194
	v_mov_b32_e32 v203, v159
	v_pk_fma_f32 v[242:243], v[130:131], s[78:79], v[220:221] op_sel_hi:[1,0,1]
	v_lshl_add_u64 v[202:203], v[202:203], 2, s[90:91]
	global_store_dwordx4 v[202:203], v[240:243], off
	v_sub_f32_e32 v203, v249, v218
	v_sub_f32_e32 v202, v248, v218
	v_sub_f32_e32 v221, v251, v218
	v_sub_f32_e32 v220, v250, v218
	v_pk_mul_f32 v[202:203], v[218:219], v[202:203] op_sel:[1,0]
	v_pk_mul_f32 v[220:221], v[218:219], v[220:221] op_sel:[1,0]
	v_pk_fma_f32 v[202:203], v[214:215], v[202:203], v[52:53]
	v_pk_fma_f32 v[220:221], v[212:213], v[220:221], v[54:55]
	v_pk_fma_f32 v[240:241], v[132:133], s[78:79], v[202:203] op_sel_hi:[1,0,1]
	v_add_u32_e32 v202, 0x8080, v194
	v_mov_b32_e32 v203, v159
	v_sub_f32_e32 v153, v153, v218
	v_sub_f32_e32 v152, v152, v218
	v_sub_f32_e32 v155, v155, v218
	v_sub_f32_e32 v154, v154, v218
	v_pk_fma_f32 v[242:243], v[134:135], s[78:79], v[220:221] op_sel_hi:[1,0,1]
	v_lshl_add_u64 v[202:203], v[202:203], 2, s[90:91]
	v_pk_mul_f32 v[154:155], v[218:219], v[154:155] op_sel:[1,0]
	v_pk_mul_f32 v[152:153], v[218:219], v[152:153] op_sel:[1,0]
	global_store_dwordx4 v[202:203], v[240:243], off
	v_pk_fma_f32 v[152:153], v[208:209], v[152:153], v[48:49]
	v_pk_fma_f32 v[154:155], v[206:207], v[154:155], v[50:51]
	v_add_u32_e32 v202, 0x8090, v194
	v_mov_b32_e32 v203, v159
	v_sub_f32_e32 v149, v149, v216
	v_sub_f32_e32 v148, v148, v216
	v_sub_f32_e32 v151, v151, v216
	v_sub_f32_e32 v150, v150, v216
	v_pk_fma_f32 v[154:155], v[130:131], s[78:79], v[154:155] op_sel_hi:[1,0,1]
	v_pk_fma_f32 v[152:153], v[128:129], s[78:79], v[152:153] op_sel_hi:[1,0,1]
	v_lshl_add_u64 v[202:203], v[202:203], 2, s[90:91]
	v_pk_mul_f32 v[150:151], v[216:217], v[150:151] op_sel:[1,0]
	v_pk_mul_f32 v[148:149], v[216:217], v[148:149] op_sel:[1,0]
	global_store_dwordx4 v[202:203], v[152:155], off
	v_pk_fma_f32 v[148:149], v[214:215], v[148:149], v[44:45]
	v_pk_fma_f32 v[150:151], v[212:213], v[150:151], v[46:47]
	v_add_u32_e32 v152, 0x10080, v194
	v_mov_b32_e32 v153, v159
	v_sub_f32_e32 v145, v145, v216
	v_sub_f32_e32 v144, v144, v216
	v_sub_f32_e32 v147, v147, v216
	v_sub_f32_e32 v146, v146, v216
	v_pk_fma_f32 v[150:151], v[134:135], s[78:79], v[150:151] op_sel_hi:[1,0,1]
	v_pk_fma_f32 v[148:149], v[132:133], s[78:79], v[148:149] op_sel_hi:[1,0,1]
	v_lshl_add_u64 v[152:153], v[152:153], 2, s[90:91]
	v_pk_mul_f32 v[146:147], v[216:217], v[146:147] op_sel:[1,0]
	v_pk_mul_f32 v[144:145], v[216:217], v[144:145] op_sel:[1,0]
	global_store_dwordx4 v[152:153], v[148:151], off
	v_pk_fma_f32 v[144:145], v[208:209], v[144:145], v[40:41]
	v_pk_fma_f32 v[146:147], v[206:207], v[146:147], v[42:43]
;     template <bool LN, int BJ, int LO, int HI> DI void batch(const f32x4 (&acc)[2][2][4][2], unsigned row0, unsigned col0, const f32x4 (&gv)[2], const f32x4 (&bv)[2]) const {
;     ...
;         for (int i = LO; i < HI; ++i) { const int ai = i >> 3, m = (i >> 1) & 3, n = i & 1; const unsigned row = row0 + ai * HALF + m * 16;
;             if (n == 0) { mean[(i - LO) >> 1] = 0.f; rstd[(i - LO) >> 1] = 1.f;
;                 if (LN) { const float2 st = *(const float2*)(stats + row * 2u); mean[(i - LO) >> 1] = st.x; rstd[(i - LO) >> 1] = st.y; } }
;             r[i - LO] = *(const f32x4*)(src + (row * (unsigned)DM + col0 + BJ * HALF + n * 16)); }
; #pragma unroll
;         for (int i = LO; i < HI; ++i) { const int ai = i >> 3, m = (i >> 1) & 3, n = i & 1; const unsigned row = row0 + ai * HALF + m * 16;
;             *(f32x4*)(Y + (row * (unsigned)DM + col0 + BJ * HALF + n * 16)) = acc[ai][BJ][m][n] + ((r[i - LO] - mean[(i - LO) >> 1]) * rstd[(i - LO) >> 1]) * gv[n] + bv[n]; }
;     template <bool LN> DI void run(const f32x4 (&acc)[2][2][4][2], const Unit& u, int wr, int wc, int fr, int fq) const {
;     ...
;         batch<LN, 1, 0, 8>(acc, row0, col0, gv, bv);
;         batch<LN, 1, 8, 16>(acc, row0, col0, gv, bv);
	v_add_u32_e32 v148, 0x10090, v194
	v_mov_b32_e32 v149, v159
	v_sub_f32_e32 v141, v141, v200
	v_sub_f32_e32 v140, v140, v200
	v_sub_f32_e32 v143, v143, v200
	v_sub_f32_e32 v142, v142, v200
	v_pk_fma_f32 v[146:147], v[130:131], s[78:79], v[146:147] op_sel_hi:[1,0,1]
	v_pk_fma_f32 v[144:145], v[128:129], s[78:79], v[144:145] op_sel_hi:[1,0,1]
	v_lshl_add_u64 v[148:149], v[148:149], 2, s[90:91]
	v_pk_mul_f32 v[142:143], v[200:201], v[142:143] op_sel:[1,0]
	v_pk_mul_f32 v[140:141], v[200:201], v[140:141] op_sel:[1,0]
	global_store_dwordx4 v[148:149], v[144:147], off
	v_pk_fma_f32 v[140:141], v[214:215], v[140:141], v[36:37]
	v_pk_fma_f32 v[142:143], v[212:213], v[142:143], v[38:39]
	v_add_u32_e32 v144, 0x18080, v194
	v_mov_b32_e32 v145, v159
	v_sub_f32_e32 v137, v137, v200
	v_sub_f32_e32 v136, v136, v200
	v_sub_f32_e32 v139, v139, v200
	v_sub_f32_e32 v138, v138, v200
	v_pk_fma_f32 v[142:143], v[134:135], s[78:79], v[142:143] op_sel_hi:[1,0,1]
	v_pk_fma_f32 v[140:141], v[132:133], s[78:79], v[140:141] op_sel_hi:[1,0,1]
	v_lshl_add_u64 v[144:145], v[144:145], 2, s[90:91]
	v_pk_mul_f32 v[138:139], v[200:201], v[138:139] op_sel:[1,0]
	v_pk_mul_f32 v[136:137], v[200:201], v[136:137] op_sel:[1,0]
	global_store_dwordx4 v[144:145], v[140:143], off
	v_pk_fma_f32 v[136:137], v[208:209], v[136:137], v[32:33]
	v_pk_fma_f32 v[138:139], v[206:207], v[138:139], v[34:35]
	v_add_u32_e32 v140, 0x18090, v194
	v_mov_b32_e32 v141, v159
	v_pk_fma_f32 v[138:139], v[130:131], s[78:79], v[138:139] op_sel_hi:[1,0,1]
	v_pk_fma_f32 v[136:137], v[128:129], s[78:79], v[136:137] op_sel_hi:[1,0,1]
	v_lshl_add_u64 v[140:141], v[140:141], 2, s[90:91]
	global_store_dwordx4 v[140:141], v[136:139], off
	s_nop 1
	v_add_u32_e32 v136, v233, v230
	v_mov_b32_e32 v137, v159
	v_lshl_add_u64 v[136:137], v[136:137], 2, s[88:89]
	global_load_dwordx2 v[220:221], v[196:197], off
	global_load_dwordx4 v[216:219], v[136:137], off
	v_add_u32_e32 v136, v233, v229
	v_mov_b32_e32 v137, v159
	v_lshl_add_u64 v[136:137], v[136:137], 2, s[88:89]
	global_load_dwordx4 v[240:243], v[136:137], off
	global_load_dwordx2 v[200:201], v[198:199], off
	v_add_u32_e32 v136, v234, v230
	v_mov_b32_e32 v137, v159
	v_lshl_add_u64 v[136:137], v[136:137], 2, s[88:89]
	global_load_dwordx4 v[244:247], v[136:137], off
	v_add_u32_e32 v136, v234, v229
	v_mov_b32_e32 v137, v159
	v_lshl_add_u64 v[136:137], v[136:137], 2, s[88:89]
	global_load_dwordx4 v[152:155], v[136:137], off
	global_load_dwordx2 v[198:199], v[204:205], off
	v_add_u32_e32 v136, v237, v230
	v_mov_b32_e32 v137, v159
	v_lshl_add_u64 v[136:137], v[136:137], 2, s[88:89]
	global_load_dwordx4 v[148:151], v[136:137], off
	v_add_u32_e32 v136, v237, v229
	v_mov_b32_e32 v137, v159
	v_lshl_add_u64 v[136:137], v[136:137], 2, s[88:89]
	global_load_dwordx4 v[144:147], v[136:137], off
	global_load_dwordx2 v[196:197], v[210:211], off
	v_add_u32_e32 v136, v238, v230
	v_mov_b32_e32 v137, v159
	v_lshl_add_u64 v[136:137], v[136:137], 2, s[88:89]
	global_load_dwordx4 v[140:143], v[136:137], off
	v_add_u32_e32 v136, v238, v229
	v_mov_b32_e32 v137, v159
	v_lshl_add_u64 v[136:137], v[136:137], 2, s[88:89]
	global_load_dwordx4 v[136:139], v[136:137], off
	v_add_u32_e32 v210, 0x40080, v194
	v_mov_b32_e32 v211, v159
	v_lshl_add_u64 v[210:211], v[210:211], 2, s[90:91]
	s_waitcnt vmcnt(0)
;     template <bool LN, int BJ, int LO, int HI> DI void batch(const f32x4 (&acc)[2][2][4][2], unsigned row0, unsigned col0, const f32x4 (&gv)[2], const f32x4 (&bv)[2]) const {
;     ...
;         for (int i = LO; i < HI; ++i) { const int ai = i >> 3, m = (i >> 1) & 3, n = i & 1; const unsigned row = row0 + ai * HALF + m * 16;
;             if (n == 0) { mean[(i - LO) >> 1] = 0.f; rstd[(i - LO) >> 1] = 1.f;
;                 if (LN) { const float2 st = *(const float2*)(stats + row * 2u); mean[(i - LO) >> 1] = st.x; rstd[(i - LO) >> 1] = st.y; } }
;             r[i - LO] = *(const f32x4*)(src + (row * (unsigned)DM + col0 + BJ * HALF + n * 16)); }
; #pragma unroll
;         for (int i = LO; i < HI; ++i) { const int ai = i >> 3, m = (i >> 1) & 3, n = i & 1; const unsigned row = row0 + ai * HALF + m * 16;
;             *(f32x4*)(Y + (row * (unsigned)DM + col0 + BJ * HALF + n * 16)) = acc[ai][BJ][m][n] + ((r[i - LO] - mean[(i - LO) >> 1]) * rstd[(i - LO) >> 1]) * gv[n] + bv[n]; }
	v_sub_f32_e32 v203, v217, v220
	v_sub_f32_e32 v202, v216, v220
	v_sub_f32_e32 v205, v219, v220
	v_sub_f32_e32 v204, v218, v220
	v_pk_mul_f32 v[204:205], v[220:221], v[204:205] op_sel:[1,0]
	v_pk_mul_f32 v[202:203], v[220:221], v[202:203] op_sel:[1,0]
	v_pk_fma_f32 v[204:205], v[212:213], v[204:205], v[30:31]
	v_pk_fma_f32 v[202:203], v[214:215], v[202:203], v[28:29]
	v_pk_fma_f32 v[204:205], v[134:135], s[78:79], v[204:205] op_sel_hi:[1,0,1]
	v_pk_fma_f32 v[202:203], v[132:133], s[78:79], v[202:203] op_sel_hi:[1,0,1]
	global_store_dwordx4 v[210:211], v[202:205], off
	v_add_u32_e32 v210, 0x40090, v194
	v_mov_b32_e32 v211, v159
	v_sub_f32_e32 v203, v241, v220
	v_sub_f32_e32 v202, v240, v220
	v_sub_f32_e32 v205, v243, v220
	v_sub_f32_e32 v204, v242, v220
	v_pk_mul_f32 v[204:205], v[220:221], v[204:205] op_sel:[1,0]
	v_pk_mul_f32 v[202:203], v[220:221], v[202:203] op_sel:[1,0]
	v_pk_fma_f32 v[204:205], v[206:207], v[204:205], v[26:27]
	v_pk_fma_f32 v[202:203], v[208:209], v[202:203], v[24:25]
	v_pk_fma_f32 v[204:205], v[130:131], s[78:79], v[204:205] op_sel_hi:[1,0,1]
	v_pk_fma_f32 v[202:203], v[128:129], s[78:79], v[202:203] op_sel_hi:[1,0,1]
	v_lshl_add_u64 v[210:211], v[210:211], 2, s[90:91]
	global_store_dwordx4 v[210:211], v[202:205], off
	v_sub_f32_e32 v149, v149, v198
	v_sub_f32_e32 v148, v148, v198
	v_sub_f32_e32 v203, v245, v200
	v_sub_f32_e32 v202, v244, v200
	v_sub_f32_e32 v141, v141, v196
	v_sub_f32_e32 v140, v140, v196
	v_sub_f32_e32 v205, v247, v200
	v_sub_f32_e32 v204, v246, v200
	v_pk_mul_f32 v[202:203], v[200:201], v[202:203] op_sel:[1,0]
	v_sub_f32_e32 v151, v151, v198
	v_sub_f32_e32 v150, v150, v198
	v_pk_mul_f32 v[148:149], v[198:199], v[148:149] op_sel:[1,0]
	v_sub_f32_e32 v143, v143, v196
	v_sub_f32_e32 v142, v142, v196
	v_pk_mul_f32 v[140:141], v[196:197], v[140:141] op_sel:[1,0]
	v_pk_mul_f32 v[204:205], v[200:201], v[204:205] op_sel:[1,0]
	v_pk_fma_f32 v[202:203], v[214:215], v[202:203], v[20:21]
	v_sub_f32_e32 v153, v153, v200
	v_sub_f32_e32 v152, v152, v200
	v_sub_f32_e32 v155, v155, v200
	v_sub_f32_e32 v154, v154, v200
	v_pk_mul_f32 v[150:151], v[198:199], v[150:151] op_sel:[1,0]
	v_pk_fma_f32 v[148:149], v[214:215], v[148:149], v[12:13]
	v_pk_mul_f32 v[142:143], v[196:197], v[142:143] op_sel:[1,0]
	v_pk_fma_f32 v[140:141], v[214:215], v[140:141], v[4:5]
	v_pk_fma_f32 v[204:205], v[212:213], v[204:205], v[22:23]
	v_pk_fma_f32 v[202:203], v[132:133], s[78:79], v[202:203] op_sel_hi:[1,0,1]
	v_pk_mul_f32 v[154:155], v[200:201], v[154:155] op_sel:[1,0]
	v_pk_mul_f32 v[152:153], v[200:201], v[152:153] op_sel:[1,0]
	v_pk_fma_f32 v[150:151], v[212:213], v[150:151], v[14:15]
	v_pk_fma_f32 v[148:149], v[132:133], s[78:79], v[148:149] op_sel_hi:[1,0,1]
	v_pk_fma_f32 v[142:143], v[212:213], v[142:143], v[6:7]
	v_pk_fma_f32 v[132:133], v[132:133], s[78:79], v[140:141] op_sel_hi:[1,0,1]
	v_add_u32_e32 v140, 0x58080, v194
	v_mov_b32_e32 v141, v159
	v_pk_fma_f32 v[204:205], v[134:135], s[78:79], v[204:205] op_sel_hi:[1,0,1]
	v_pk_fma_f32 v[152:153], v[208:209], v[152:153], v[16:17]
	v_pk_fma_f32 v[154:155], v[206:207], v[154:155], v[18:19]
	v_add_u32_e32 v200, 0x48090, v194
	v_mov_b32_e32 v201, v159
	v_pk_fma_f32 v[150:151], v[134:135], s[78:79], v[150:151] op_sel_hi:[1,0,1]
	v_pk_fma_f32 v[134:135], v[134:135], s[78:79], v[142:143] op_sel_hi:[1,0,1]
	v_lshl_add_u64 v[140:141], v[140:141], 2, s[90:91]
	v_pk_fma_f32 v[154:155], v[130:131], s[78:79], v[154:155] op_sel_hi:[1,0,1]
	v_pk_fma_f32 v[152:153], v[128:129], s[78:79], v[152:153] op_sel_hi:[1,0,1]
	v_lshl_add_u64 v[200:201], v[200:201], 2, s[90:91]
	v_sub_f32_e32 v145, v145, v198
	v_sub_f32_e32 v144, v144, v198
	global_store_dwordx4 v[140:141], v[132:135], off
	global_store_dwordx4 v[200:201], v[152:155], off
	v_sub_f32_e32 v147, v147, v198
	v_sub_f32_e32 v133, v137, v196
	v_sub_f32_e32 v132, v136, v196
	v_add_u32_e32 v152, 0x50080, v194
	v_mov_b32_e32 v153, v159
	v_sub_f32_e32 v146, v146, v198
	v_pk_mul_f32 v[144:145], v[198:199], v[144:145] op_sel:[1,0]
	v_sub_f32_e32 v135, v139, v196
	v_sub_f32_e32 v134, v138, v196
	v_pk_mul_f32 v[132:133], v[196:197], v[132:133] op_sel:[1,0]
	v_lshl_add_u64 v[152:153], v[152:153], 2, s[90:91]
	v_pk_mul_f32 v[146:147], v[198:199], v[146:147] op_sel:[1,0]
	v_pk_fma_f32 v[144:145], v[208:209], v[144:145], v[8:9]
	v_pk_mul_f32 v[134:135], v[196:197], v[134:135] op_sel:[1,0]
	v_pk_fma_f32 v[132:133], v[208:209], v[132:133], v[0:1]
	v_add_u32_e32 v210, 0x48080, v194
	v_mov_b32_e32 v211, v159
	global_store_dwordx4 v[152:153], v[148:151], off
	v_pk_fma_f32 v[146:147], v[206:207], v[146:147], v[10:11]
	v_pk_fma_f32 v[144:145], v[128:129], s[78:79], v[144:145] op_sel_hi:[1,0,1]
	v_add_u32_e32 v148, 0x50090, v194
	v_mov_b32_e32 v149, v159
	v_pk_fma_f32 v[134:135], v[206:207], v[134:135], v[2:3]
	v_pk_fma_f32 v[128:129], v[128:129], s[78:79], v[132:133] op_sel_hi:[1,0,1]
	v_add_u32_e32 v132, 0x58090, v194
	v_mov_b32_e32 v133, v159
	v_lshl_add_u64 v[210:211], v[210:211], 2, s[90:91]
	v_pk_fma_f32 v[146:147], v[130:131], s[78:79], v[146:147] op_sel_hi:[1,0,1]
	v_lshl_add_u64 v[148:149], v[148:149], 2, s[90:91]
	v_pk_fma_f32 v[130:131], v[130:131], s[78:79], v[134:135] op_sel_hi:[1,0,1]
	v_lshl_add_u64 v[132:133], v[132:133], 2, s[90:91]
	global_store_dwordx4 v[210:211], v[202:205], off
	global_store_dwordx4 v[148:149], v[144:147], off
	global_store_dwordx4 v[132:133], v[128:131], off
	s_mov_b64 s[20:21], 0
	s_branch .LBB0_81

; #define PG8_STAGE(bufoff, gbase) do { _Pragma("unroll") for (int _i = 0; _i < 2; ++_i) \
;         __builtin_amdgcn_global_load_lds((const unsigned*)((const char*)(gbase) + voff[_i]), (LAS unsigned*)(lds + (bufoff) + ldsw + _i * 8192), 16, 0, 0); } while (0)
; #define PG8_LDA(dst, b, h) do { _Pragma("unroll") for (int m = 0; m < 4; ++m) _Pragma("unroll") for (int k = 0; k < 2; ++k) dst[m][k] = *(const LAS bf16x8*)(lds + PG8_SA(b, h) + aoff + m * 2048 + k * 1024); } while (0)
; #define PG8_LDB(dst, b, h) do { _Pragma("unroll") for (int n = 0; n < 2; ++n) _Pragma("unroll") for (int k = 0; k < 2; ++k) dst[n][k] = *(const LAS bf16x8*)(lds + PG8_SB(b, h) + boff + n * 2048 + k * 1024); } while (0)
; #define PG8_MMA(ai, bj, At, Bt) do { __builtin_amdgcn_s_setprio(1); _Pragma("unroll") for (int m = 0; m < 4; ++m) _Pragma("unroll") for (int n = 0; n < 2; ++n) _Pragma("unroll") for (int k = 0; k < 2; ++k) \
;         acc[ai][bj][m][n] = __builtin_amdgcn_mfma_f32_16x16x32_bf16(Bt[n][k], At[m][k], acc[ai][bj][m][n], 0, 0, 0); __builtin_amdgcn_s_setprio(0); } while (0)
; #define PG8_WAIT_L(n) asm volatile("s_waitcnt lgkmcnt(" #n ")" ::: "memory")
; #define PG8_BAR __builtin_amdgcn_s_barrier()
; #define PG8_SCHED __builtin_amdgcn_sched_barrier(0)
; template <class Epi>
; DI void gemm_phase(LAS unsigned char* lds, const Gemm g, const StaticOrder& S, const Epi& E) {
;     ...
;             PG8_LDB(B0, 0, 0); PG8_SCHED; PG8_LDA(At, 0, 0); PG8_STAGE(PG8_SA(1, 1), a1 + hstep);
;             PG8_WAIT_L(8); PG8_BAR; PG8_WAIT_L(0); PG8_MMA(0, 0, At, B0); PG8_BAR; PG8_SCHED;
;             PG8_LDB(B1, 0, 1); PG8_STAGE(PG8_SB(0, 0), b2);
;             PG8_BAR; PG8_WAIT_L(0); PG8_MMA(0, 1, At, B1); PG8_BAR;
;             PG8_LDA(At, 0, 1); PG8_STAGE(PG8_SA(0, 0), a2);
;             PG8_BAR; PG8_WAIT_L(0); PG8_MMA(1, 0, At, B0); PG8_BAR; PG8_SCHED;
.LBB0_134:
	s_add_u32 s18, s16, 0x100
	s_addc_u32 s19, s17, 0
	s_add_i32 s39, 0, 0x10000
	ds_read_b128 v[96:99], v199
	ds_read_b128 v[100:103], v199 offset:1024
	ds_read_b128 v[136:139], v199 offset:2048
	ds_read_b128 v[148:151], v199 offset:3072
	s_cmpk_eq_i32 s33, 0x54
	s_cselect_b32 s23, s9, s19
	s_cselect_b32 s22, s8, s18
	s_cselect_b32 s21, s11, s5
	s_cselect_b32 s20, s10, s4
	v_lshl_add_u64 v[218:219], s[16:17], 0, v[144:145]
	s_add_i32 m0, s28, 0xc000
	ds_read_b128 v[152:155], v201
	ds_read_b128 v[186:189], v201 offset:1024
	ds_read_b128 v[190:193], v201 offset:2048
	ds_read_b128 v[194:197], v201 offset:3072
	ds_read_b128 v[202:205], v201 offset:4096
	ds_read_b128 v[206:209], v201 offset:5120
	ds_read_b128 v[210:213], v201 offset:6144
	ds_read_b128 v[214:217], v201 offset:7168
	global_load_lds_dwordx4 v[218:219], off
	v_lshl_add_u64 v[218:219], s[16:17], 0, v[146:147]
	s_add_i32 m0, s28, 0xe000
	s_nop 0
	global_load_lds_dwordx4 v[218:219], off
	s_waitcnt lgkmcnt(8)
	s_setprio 1
	s_barrier
	s_waitcnt lgkmcnt(0)
	v_mfma_f32_16x16x32_bf16 v[132:135], v[96:99], v[152:155], v[132:135]
	v_mfma_f32_16x16x32_bf16 v[128:131], v[136:139], v[152:155], v[128:131]
	v_mfma_f32_16x16x32_bf16 v[124:127], v[96:99], v[190:193], v[124:127]
	v_mfma_f32_16x16x32_bf16 v[120:123], v[136:139], v[190:193], v[120:123]
	v_mfma_f32_16x16x32_bf16 v[116:119], v[96:99], v[202:205], v[116:119]
	v_mfma_f32_16x16x32_bf16 v[112:115], v[136:139], v[202:205], v[112:115]
	v_mfma_f32_16x16x32_bf16 v[108:111], v[96:99], v[210:213], v[108:111]
	v_mfma_f32_16x16x32_bf16 v[104:107], v[136:139], v[210:213], v[104:107]
	v_mfma_f32_16x16x32_bf16 v[132:135], v[100:103], v[186:189], v[132:135]
	v_mfma_f32_16x16x32_bf16 v[128:131], v[148:151], v[186:189], v[128:131]
	v_mfma_f32_16x16x32_bf16 v[124:127], v[100:103], v[194:197], v[124:127]
	v_mfma_f32_16x16x32_bf16 v[120:123], v[148:151], v[194:197], v[120:123]
	v_mfma_f32_16x16x32_bf16 v[116:119], v[100:103], v[206:209], v[116:119]
	v_mfma_f32_16x16x32_bf16 v[112:115], v[148:151], v[206:209], v[112:115]
	v_mfma_f32_16x16x32_bf16 v[108:111], v[100:103], v[214:217], v[108:111]
	s_setprio 0
	v_mfma_f32_16x16x32_bf16 v[104:107], v[148:151], v[214:217], v[104:107]
	s_barrier
	s_add_i32 s40, 0, 0x14000
	s_add_i32 s16, s39, s27
	v_lshl_add_u64 v[218:219], s[20:21], 0, v[142:143]
	s_mov_b32 m0, s16
	ds_read_b128 v[226:229], v199 offset:16384
	ds_read_b128 v[230:233], v199 offset:17408
	ds_read_b128 v[234:237], v199 offset:18432
	ds_read_b128 v[238:241], v199 offset:19456
	global_load_lds_dwordx4 v[218:219], off
	v_lshl_add_u64 v[220:221], s[20:21], 0, v[140:141]
	s_add_i32 m0, s16, 0x2000
	s_nop 0
	global_load_lds_dwordx4 v[220:221], off
	s_waitcnt lgkmcnt(0)
	s_setprio 1
	s_barrier
	v_mfma_f32_16x16x32_bf16 v[60:63], v[226:229], v[152:155], v[60:63]
	v_mfma_f32_16x16x32_bf16 v[56:59], v[234:237], v[152:155], v[56:59]
	v_mfma_f32_16x16x32_bf16 v[52:55], v[226:229], v[190:193], v[52:55]
	v_mfma_f32_16x16x32_bf16 v[48:51], v[234:237], v[190:193], v[48:51]
	v_mfma_f32_16x16x32_bf16 v[44:47], v[226:229], v[202:205], v[44:47]
	v_mfma_f32_16x16x32_bf16 v[40:43], v[234:237], v[202:205], v[40:43]
	v_mfma_f32_16x16x32_bf16 v[36:39], v[226:229], v[210:213], v[36:39]
	v_mfma_f32_16x16x32_bf16 v[32:35], v[234:237], v[210:213], v[32:35]
	v_mfma_f32_16x16x32_bf16 v[60:63], v[230:233], v[186:189], v[60:63]
	s_mov_b32 m0, s28
	v_mfma_f32_16x16x32_bf16 v[56:59], v[238:241], v[186:189], v[56:59]
	v_lshl_add_u64 v[242:243], s[22:23], 0, v[142:143]
	v_mfma_f32_16x16x32_bf16 v[52:55], v[230:233], v[194:197], v[52:55]
	v_mfma_f32_16x16x32_bf16 v[48:51], v[238:241], v[194:197], v[48:51]
	v_mfma_f32_16x16x32_bf16 v[44:47], v[230:233], v[206:209], v[44:47]
	v_mfma_f32_16x16x32_bf16 v[40:43], v[238:241], v[206:209], v[40:43]
	v_mfma_f32_16x16x32_bf16 v[36:39], v[230:233], v[214:217], v[36:39]
	s_setprio 0
	v_mfma_f32_16x16x32_bf16 v[32:35], v[238:241], v[214:217], v[32:35]
	s_barrier
	ds_read_b128 v[152:155], v201 offset:16384
	ds_read_b128 v[186:189], v201 offset:17408
	ds_read_b128 v[190:193], v201 offset:18432
	ds_read_b128 v[194:197], v201 offset:19456
	ds_read_b128 v[202:205], v201 offset:20480
	ds_read_b128 v[206:209], v201 offset:21504
	ds_read_b128 v[210:213], v201 offset:22528
	ds_read_b128 v[214:217], v201 offset:23552
	global_load_lds_dwordx4 v[242:243], off
	v_lshl_add_u64 v[244:245], s[22:23], 0, v[140:141]
	s_mov_b32 m0, s29
	s_nop 0
	global_load_lds_dwordx4 v[244:245], off
	s_waitcnt lgkmcnt(0)
	s_setprio 1
	s_barrier
	v_mfma_f32_16x16x32_bf16 v[92:95], v[96:99], v[152:155], v[92:95]
	v_mfma_f32_16x16x32_bf16 v[88:91], v[136:139], v[152:155], v[88:91]
	v_mfma_f32_16x16x32_bf16 v[84:87], v[96:99], v[190:193], v[84:87]
	v_mfma_f32_16x16x32_bf16 v[80:83], v[136:139], v[190:193], v[80:83]
	v_mfma_f32_16x16x32_bf16 v[76:79], v[96:99], v[202:205], v[76:79]
	v_mfma_f32_16x16x32_bf16 v[72:75], v[136:139], v[202:205], v[72:75]
	v_mfma_f32_16x16x32_bf16 v[68:71], v[96:99], v[210:213], v[68:71]
	v_mfma_f32_16x16x32_bf16 v[64:67], v[136:139], v[210:213], v[64:67]
	v_mfma_f32_16x16x32_bf16 v[92:95], v[100:103], v[186:189], v[92:95]
	v_mfma_f32_16x16x32_bf16 v[88:91], v[148:151], v[186:189], v[88:91]
	v_mfma_f32_16x16x32_bf16 v[84:87], v[100:103], v[194:197], v[84:87]
	v_mfma_f32_16x16x32_bf16 v[80:83], v[148:151], v[194:197], v[80:83]
	v_mfma_f32_16x16x32_bf16 v[76:79], v[100:103], v[206:209], v[76:79]
	v_mfma_f32_16x16x32_bf16 v[72:75], v[148:151], v[206:209], v[72:75]
	v_mfma_f32_16x16x32_bf16 v[68:71], v[100:103], v[214:217], v[68:71]
	s_setprio 0
	v_mfma_f32_16x16x32_bf16 v[64:67], v[148:151], v[214:217], v[64:67]
	s_barrier
; #define PG8_STAGE(bufoff, gbase) do { _Pragma("unroll") for (int _i = 0; _i < 2; ++_i) \
;         __builtin_amdgcn_global_load_lds((const unsigned*)((const char*)(gbase) + voff[_i]), (LAS unsigned*)(lds + (bufoff) + ldsw + _i * 8192), 16, 0, 0); } while (0)
; #define PG8_LDA(dst, b, h) do { _Pragma("unroll") for (int m = 0; m < 4; ++m) _Pragma("unroll") for (int k = 0; k < 2; ++k) dst[m][k] = *(const LAS bf16x8*)(lds + PG8_SA(b, h) + aoff + m * 2048 + k * 1024); } while (0)
; #define PG8_LDB(dst, b, h) do { _Pragma("unroll") for (int n = 0; n < 2; ++n) _Pragma("unroll") for (int k = 0; k < 2; ++k) dst[n][k] = *(const LAS bf16x8*)(lds + PG8_SB(b, h) + boff + n * 2048 + k * 1024); } while (0)
; #define PG8_MMA(ai, bj, At, Bt) do { __builtin_amdgcn_s_setprio(1); _Pragma("unroll") for (int m = 0; m < 4; ++m) _Pragma("unroll") for (int n = 0; n < 2; ++n) _Pragma("unroll") for (int k = 0; k < 2; ++k) \
;         acc[ai][bj][m][n] = __builtin_amdgcn_mfma_f32_16x16x32_bf16(Bt[n][k], At[m][k], acc[ai][bj][m][n], 0, 0, 0); __builtin_amdgcn_s_setprio(0); } while (0)
; #define PG8_WAIT_V(n) asm volatile("s_waitcnt vmcnt(" #n ")" ::: "memory")
; #define PG8_WAIT_L(n) asm volatile("s_waitcnt lgkmcnt(" #n ")" ::: "memory")
; #define PG8_BAR __builtin_amdgcn_s_barrier()
; #define PG8_SCHED __builtin_amdgcn_sched_barrier(0)
; template <class Epi>
; DI void gemm_phase(LAS unsigned char* lds, const Gemm g, const StaticOrder& S, const Epi& E) {
;     ...
;             PG8_BAR; PG8_WAIT_L(0); PG8_MMA(1, 0, At, B0); PG8_BAR; PG8_SCHED;
;             PG8_STAGE(PG8_SB(0, 1), b2 + hstep);
;             PG8_WAIT_V(6); PG8_BAR; PG8_MMA(1, 1, At, B1); PG8_BAR;
;             PG8_LDB(B0, 1, 0); PG8_SCHED; PG8_LDA(At, 1, 0); PG8_STAGE(PG8_SA(0, 1), a2 + hstep);
;             PG8_WAIT_L(8); PG8_BAR; PG8_WAIT_L(0); PG8_MMA(0, 0, At, B0); PG8_BAR; PG8_SCHED;
;             PG8_LDB(B1, 1, 1); PG8_STAGE(PG8_SB(1, 0), b3);
;             PG8_BAR; PG8_WAIT_L(0); PG8_MMA(0, 1, At, B1); PG8_BAR;
;             PG8_LDA(At, 1, 1); PG8_STAGE(PG8_SA(1, 0), a3);
;             PG8_BAR; PG8_WAIT_L(0); PG8_MMA(1, 0, At, B0); PG8_BAR; PG8_SCHED;
	s_add_u32 s16, s20, 0x160000
	s_addc_u32 s17, s21, 0
	s_add_i32 s39, s40, s27
	s_mov_b32 m0, s39
	s_nop 0
	global_load_lds_dwordx4 v142, s[16:17]
	s_add_i32 m0, s39, 0x2000
	s_nop 0
	global_load_lds_dwordx4 v140, s[16:17]
	s_waitcnt vmcnt(6)
	s_setprio 1
	s_barrier
	v_mfma_f32_16x16x32_bf16 v[28:31], v[226:229], v[152:155], v[28:31]
	v_mfma_f32_16x16x32_bf16 v[24:27], v[234:237], v[152:155], v[24:27]
	v_mfma_f32_16x16x32_bf16 v[20:23], v[226:229], v[190:193], v[20:23]
	v_mfma_f32_16x16x32_bf16 v[16:19], v[234:237], v[190:193], v[16:19]
	v_mfma_f32_16x16x32_bf16 v[12:15], v[226:229], v[202:205], v[12:15]
	v_mfma_f32_16x16x32_bf16 v[8:11], v[234:237], v[202:205], v[8:11]
	v_mfma_f32_16x16x32_bf16 v[4:7], v[226:229], v[210:213], v[4:7]
	v_mfma_f32_16x16x32_bf16 v[0:3], v[234:237], v[210:213], v[0:3]
	v_mfma_f32_16x16x32_bf16 v[28:31], v[230:233], v[186:189], v[28:31]
	s_add_i32 s39, 0, 0x18000
	v_mfma_f32_16x16x32_bf16 v[24:27], v[238:241], v[186:189], v[24:27]
	v_mfma_f32_16x16x32_bf16 v[20:23], v[230:233], v[194:197], v[20:23]
	v_mfma_f32_16x16x32_bf16 v[16:19], v[238:241], v[194:197], v[16:19]
	v_mfma_f32_16x16x32_bf16 v[12:15], v[230:233], v[206:209], v[12:15]
	v_mfma_f32_16x16x32_bf16 v[8:11], v[238:241], v[206:209], v[8:11]
	v_mfma_f32_16x16x32_bf16 v[4:7], v[230:233], v[214:217], v[4:7]
	s_setprio 0
	v_mfma_f32_16x16x32_bf16 v[0:3], v[238:241], v[214:217], v[0:3]
	s_barrier
	ds_read_b128 v[96:99], v199 offset:32768
	ds_read_b128 v[100:103], v199 offset:33792
	ds_read_b128 v[136:139], v199 offset:34816
	ds_read_b128 v[148:151], v199 offset:35840
	s_add_u32 s16, s22, 0x160000
	s_addc_u32 s17, s23, 0
	s_mov_b32 m0, s30
	ds_read_b128 v[152:155], v201 offset:32768
	ds_read_b128 v[186:189], v201 offset:33792
	ds_read_b128 v[190:193], v201 offset:34816
	ds_read_b128 v[194:197], v201 offset:35840
	ds_read_b128 v[202:205], v201 offset:36864
	ds_read_b128 v[206:209], v201 offset:37888
	ds_read_b128 v[210:213], v201 offset:38912
	ds_read_b128 v[214:217], v201 offset:39936
	global_load_lds_dwordx4 v142, s[16:17]
	s_mov_b32 m0, s31
	s_nop 0
	global_load_lds_dwordx4 v140, s[16:17]
	s_waitcnt lgkmcnt(8)
	s_setprio 1
	s_barrier
	s_waitcnt lgkmcnt(0)
	v_mfma_f32_16x16x32_bf16 v[132:135], v[96:99], v[152:155], v[132:135]
	v_mfma_f32_16x16x32_bf16 v[128:131], v[136:139], v[152:155], v[128:131]
	v_mfma_f32_16x16x32_bf16 v[124:127], v[96:99], v[190:193], v[124:127]
	v_mfma_f32_16x16x32_bf16 v[120:123], v[136:139], v[190:193], v[120:123]
	v_mfma_f32_16x16x32_bf16 v[116:119], v[96:99], v[202:205], v[116:119]
	v_mfma_f32_16x16x32_bf16 v[112:115], v[136:139], v[202:205], v[112:115]
	v_mfma_f32_16x16x32_bf16 v[108:111], v[96:99], v[210:213], v[108:111]
	v_mfma_f32_16x16x32_bf16 v[104:107], v[136:139], v[210:213], v[104:107]
	v_mfma_f32_16x16x32_bf16 v[132:135], v[100:103], v[186:189], v[132:135]
	v_mfma_f32_16x16x32_bf16 v[128:131], v[148:151], v[186:189], v[128:131]
	v_mfma_f32_16x16x32_bf16 v[124:127], v[100:103], v[194:197], v[124:127]
	v_mfma_f32_16x16x32_bf16 v[120:123], v[148:151], v[194:197], v[120:123]
	v_mfma_f32_16x16x32_bf16 v[116:119], v[100:103], v[206:209], v[116:119]
	v_mfma_f32_16x16x32_bf16 v[112:115], v[148:151], v[206:209], v[112:115]
	v_mfma_f32_16x16x32_bf16 v[108:111], v[100:103], v[214:217], v[108:111]
	s_setprio 0
	v_mfma_f32_16x16x32_bf16 v[104:107], v[148:151], v[214:217], v[104:107]
	s_barrier
	s_add_i32 s22, 0, 0x1c000
	s_add_i32 s16, s39, s27
	s_add_i32 m0, s16, 0xffffff80
	ds_read_b128 v[226:229], v199 offset:49152
	ds_read_b128 v[230:233], v199 offset:50176
	ds_read_b128 v[234:237], v199 offset:51200
	ds_read_b128 v[238:241], v199 offset:52224
	global_load_lds_dwordx4 v[218:219], off offset:128
	s_add_i32 m0, s16, 0x1f80
	s_nop 0
	global_load_lds_dwordx4 v[220:221], off offset:128
	s_waitcnt lgkmcnt(0)
	s_setprio 1
	s_barrier
	v_mfma_f32_16x16x32_bf16 v[60:63], v[226:229], v[152:155], v[60:63]
	v_mfma_f32_16x16x32_bf16 v[56:59], v[234:237], v[152:155], v[56:59]
	v_mfma_f32_16x16x32_bf16 v[52:55], v[226:229], v[190:193], v[52:55]
	v_mfma_f32_16x16x32_bf16 v[48:51], v[234:237], v[190:193], v[48:51]
	v_mfma_f32_16x16x32_bf16 v[44:47], v[226:229], v[202:205], v[44:47]
	v_mfma_f32_16x16x32_bf16 v[40:43], v[234:237], v[202:205], v[40:43]
	v_mfma_f32_16x16x32_bf16 v[36:39], v[226:229], v[210:213], v[36:39]
	v_mfma_f32_16x16x32_bf16 v[32:35], v[234:237], v[210:213], v[32:35]
	v_mfma_f32_16x16x32_bf16 v[60:63], v[230:233], v[186:189], v[60:63]
	s_mov_b32 m0, s34
	v_mfma_f32_16x16x32_bf16 v[56:59], v[238:241], v[186:189], v[56:59]
	v_lshl_add_u64 v[218:219], v[242:243], 0, s[94:95]
	v_mfma_f32_16x16x32_bf16 v[52:55], v[230:233], v[194:197], v[52:55]
	v_mfma_f32_16x16x32_bf16 v[48:51], v[238:241], v[194:197], v[48:51]
	v_mfma_f32_16x16x32_bf16 v[44:47], v[230:233], v[206:209], v[44:47]
	v_mfma_f32_16x16x32_bf16 v[40:43], v[238:241], v[206:209], v[40:43]
	v_mfma_f32_16x16x32_bf16 v[36:39], v[230:233], v[214:217], v[36:39]
	s_setprio 0
	v_mfma_f32_16x16x32_bf16 v[32:35], v[238:241], v[214:217], v[32:35]
	s_barrier
	ds_read_b128 v[152:155], v201 offset:49152
	ds_read_b128 v[186:189], v201 offset:50176
	ds_read_b128 v[190:193], v201 offset:51200
	ds_read_b128 v[194:197], v201 offset:52224
	ds_read_b128 v[202:205], v201 offset:53248
	ds_read_b128 v[206:209], v201 offset:54272
	ds_read_b128 v[210:213], v201 offset:55296
	ds_read_b128 v[214:217], v201 offset:56320
	global_load_lds_dwordx4 v[218:219], off
	s_add_i32 m0, s35, 0xffffff80
	s_nop 0
	global_load_lds_dwordx4 v[244:245], off offset:128
	s_waitcnt lgkmcnt(0)
	s_setprio 1
	s_barrier
; #define PG8_STAGE(bufoff, gbase) do { _Pragma("unroll") for (int _i = 0; _i < 2; ++_i) \
;         __builtin_amdgcn_global_load_lds((const unsigned*)((const char*)(gbase) + voff[_i]), (LAS unsigned*)(lds + (bufoff) + ldsw + _i * 8192), 16, 0, 0); } while (0)
; #define PG8_MMA(ai, bj, At, Bt) do { __builtin_amdgcn_s_setprio(1); _Pragma("unroll") for (int m = 0; m < 4; ++m) _Pragma("unroll") for (int n = 0; n < 2; ++n) _Pragma("unroll") for (int k = 0; k < 2; ++k) \
;         acc[ai][bj][m][n] = __builtin_amdgcn_mfma_f32_16x16x32_bf16(Bt[n][k], At[m][k], acc[ai][bj][m][n], 0, 0, 0); __builtin_amdgcn_s_setprio(0); } while (0)
; #define PG8_WAIT_V(n) asm volatile("s_waitcnt vmcnt(" #n ")" ::: "memory")
; #define PG8_WAIT_L(n) asm volatile("s_waitcnt lgkmcnt(" #n ")" ::: "memory")
; #define PG8_BAR __builtin_amdgcn_s_barrier()
; #define PG8_SCHED __builtin_amdgcn_sched_barrier(0)
; template <class Epi>
; DI void gemm_phase(LAS unsigned char* lds, const Gemm g, const StaticOrder& S, const Epi& E) {
;     ...
;             PG8_BAR; PG8_WAIT_L(0); PG8_MMA(1, 0, At, B0); PG8_BAR; PG8_SCHED;
;             PG8_STAGE(PG8_SB(1, 1), b3 + hstep);
;             PG8_WAIT_V(6); PG8_BAR; PG8_MMA(1, 1, At, B1); PG8_BAR;
;     template <bool LN, int BJ> DI void load_gb(unsigned col0, f32x4 (&gv)[2], f32x4 (&bv)[2]) const {
; #pragma unroll
;         for (int n = 0; n < 2; ++n) {
;             if (LN) { gv[n] = *(const f32x4*)(gam + col0 + BJ * HALF + n * 16) * ALPHA; bv[n] = *(const f32x4*)(bet + col0 + BJ * HALF + n * 16) * ALPHA; }
;             else { gv[n] = (f32x4){ALPHA, ALPHA, ALPHA, ALPHA}; bv[n] = (f32x4){0.f, 0.f, 0.f, 0.f}; }
;         }
;     }
;     template <bool LN> DI void run(const f32x4 (&acc)[2][2][4][2], const Unit& u, int wr, int wc, int fr, int fq) const {
;         const unsigned row0 = u.pm * BM + wr * 64 + fr, col0 = u.pn * BM + wc * 32 + 4 * fq;
;         f32x4 gv[2], bv[2];
;         load_gb<LN, 0>(col0, gv, bv);
;         batch<LN, 0, 0, 4>(acc, row0, col0, gv, bv);
	v_mfma_f32_16x16x32_bf16 v[92:95], v[96:99], v[152:155], v[92:95]
	v_mfma_f32_16x16x32_bf16 v[88:91], v[136:139], v[152:155], v[88:91]
	v_mfma_f32_16x16x32_bf16 v[84:87], v[96:99], v[190:193], v[84:87]
	v_mfma_f32_16x16x32_bf16 v[80:83], v[136:139], v[190:193], v[80:83]
	v_mfma_f32_16x16x32_bf16 v[76:79], v[96:99], v[202:205], v[76:79]
	v_mfma_f32_16x16x32_bf16 v[72:75], v[136:139], v[202:205], v[72:75]
	v_mfma_f32_16x16x32_bf16 v[68:71], v[96:99], v[210:213], v[68:71]
	v_mfma_f32_16x16x32_bf16 v[64:67], v[136:139], v[210:213], v[64:67]
	v_mfma_f32_16x16x32_bf16 v[92:95], v[100:103], v[186:189], v[92:95]
	v_mfma_f32_16x16x32_bf16 v[88:91], v[148:151], v[186:189], v[88:91]
	v_mfma_f32_16x16x32_bf16 v[84:87], v[100:103], v[194:197], v[84:87]
	v_mfma_f32_16x16x32_bf16 v[80:83], v[148:151], v[194:197], v[80:83]
	v_mfma_f32_16x16x32_bf16 v[76:79], v[100:103], v[206:209], v[76:79]
	v_mfma_f32_16x16x32_bf16 v[72:75], v[148:151], v[206:209], v[72:75]
	v_mfma_f32_16x16x32_bf16 v[68:71], v[100:103], v[214:217], v[68:71]
	s_setprio 0
	v_mfma_f32_16x16x32_bf16 v[64:67], v[148:151], v[214:217], v[64:67]
	s_barrier
	s_add_u32 s16, s20, 0x160080
	s_addc_u32 s17, s21, 0
	s_add_i32 s20, s22, s27
	s_mov_b32 m0, s20
	s_nop 0
	global_load_lds_dwordx4 v142, s[16:17]
	s_add_i32 m0, s20, 0x2000
	s_nop 0
	global_load_lds_dwordx4 v140, s[16:17]
	s_waitcnt vmcnt(6)
	s_setprio 1
	s_barrier
	v_mfma_f32_16x16x32_bf16 v[28:31], v[226:229], v[152:155], v[28:31]
	v_mfma_f32_16x16x32_bf16 v[24:27], v[234:237], v[152:155], v[24:27]
	v_mfma_f32_16x16x32_bf16 v[20:23], v[226:229], v[190:193], v[20:23]
	v_mfma_f32_16x16x32_bf16 v[16:19], v[234:237], v[190:193], v[16:19]
	v_mfma_f32_16x16x32_bf16 v[12:15], v[226:229], v[202:205], v[12:15]
	v_mfma_f32_16x16x32_bf16 v[8:11], v[234:237], v[202:205], v[8:11]
	v_mfma_f32_16x16x32_bf16 v[4:7], v[226:229], v[210:213], v[4:7]
	v_mfma_f32_16x16x32_bf16 v[0:3], v[234:237], v[210:213], v[0:3]
	v_mfma_f32_16x16x32_bf16 v[28:31], v[230:233], v[186:189], v[28:31]
	s_add_i32 s33, s33, 2
	v_mfma_f32_16x16x32_bf16 v[24:27], v[238:241], v[186:189], v[24:27]
	s_add_u32 s4, s4, 0x100
	v_mfma_f32_16x16x32_bf16 v[20:23], v[230:233], v[194:197], v[20:23]
	s_addc_u32 s5, s5, 0
	v_mfma_f32_16x16x32_bf16 v[16:19], v[238:241], v[194:197], v[16:19]
	s_cmpk_gt_u32 s33, 0x55
	v_mfma_f32_16x16x32_bf16 v[12:15], v[230:233], v[206:209], v[12:15]
	s_mov_b64 s[16:17], s[18:19]
	v_mfma_f32_16x16x32_bf16 v[8:11], v[238:241], v[206:209], v[8:11]
	v_mfma_f32_16x16x32_bf16 v[4:7], v[230:233], v[214:217], v[4:7]
	s_setprio 0
	v_mfma_f32_16x16x32_bf16 v[0:3], v[238:241], v[214:217], v[0:3]
	s_barrier
	s_cbranch_scc0 .LBB0_134
	v_lshl_or_b32 v158, s2, 8, v200
	v_lshlrev_b64 v[100:101], 2, v[158:159]
	v_lshl_add_u64 v[150:151], s[12:13], 0, v[100:101]
	global_load_dwordx4 v[96:99], v[150:151], off
	v_lshl_add_u64 v[152:153], s[14:15], 0, v[100:101]
	v_lshl_add_u32 v203, s3, 8, v198
	v_lshlrev_b32_e32 v202, 11, v203
	v_add_u32_e32 v148, v202, v158
	v_mov_b32_e32 v149, v159
	v_lshlrev_b32_e32 v136, 1, v203
	v_mov_b32_e32 v137, v159
	v_lshlrev_b64 v[220:221], 2, v[148:149]
	v_lshl_add_u64 v[154:155], v[136:137], 2, s[96:97]
	v_lshl_add_u64 v[136:137], s[90:91], 0, v[220:221]
	v_or_b32_e32 v204, 16, v158
	v_or_b32_e32 v138, 16, v203
	v_lshlrev_b32_e32 v149, 11, v138
	s_waitcnt vmcnt(0)
	v_pk_mul_f32 v[192:193], v[98:99], s[78:79] op_sel_hi:[1,0]
	v_pk_mul_f32 v[194:195], v[96:97], s[78:79] op_sel_hi:[1,0]
	global_load_dwordx4 v[100:103], v[152:153], off
	global_load_dwordx4 v[96:99], v[150:151], off offset:64
	global_load_dwordx2 v[218:219], v[154:155], off
	global_load_dwordx4 v[206:209], v[136:137], off
	v_add_u32_e32 v136, v202, v204
	v_mov_b32_e32 v137, v159
	v_lshl_add_u64 v[136:137], v[136:137], 2, s[90:91]
	global_load_dwordx4 v[210:213], v[136:137], off
	v_lshlrev_b32_e32 v136, 1, v138
	v_mov_b32_e32 v137, v159
	v_lshl_add_u64 v[186:187], v[136:137], 2, s[96:97]
	v_add_u32_e32 v136, v149, v158
	v_lshl_add_u64 v[136:137], v[136:137], 2, s[90:91]
	global_load_dwordx2 v[196:197], v[186:187], off
	global_load_dwordx4 v[214:217], v[136:137], off
	v_add_u32_e32 v136, v149, v204
	v_mov_b32_e32 v137, v159
	v_lshl_add_u64 v[136:137], v[136:137], 2, s[90:91]
	global_load_dwordx4 v[136:139], v[136:137], off
	s_waitcnt vmcnt(0)
	v_pk_mul_f32 v[188:189], v[98:99], s[78:79] op_sel_hi:[1,0]
	v_pk_mul_f32 v[190:191], v[96:97], s[78:79] op_sel_hi:[1,0]
	global_load_dwordx4 v[96:99], v[152:153], off offset:64
	v_sub_f32_e32 v207, v207, v218
	v_sub_f32_e32 v206, v206, v218
	v_sub_f32_e32 v209, v209, v218
	v_sub_f32_e32 v208, v208, v218
	v_pk_mul_f32 v[208:209], v[218:219], v[208:209] op_sel:[1,0]
	v_pk_mul_f32 v[206:207], v[218:219], v[206:207] op_sel:[1,0]
	v_pk_fma_f32 v[134:135], v[192:193], v[208:209], v[134:135]
	v_pk_fma_f32 v[132:133], v[194:195], v[206:207], v[132:133]
	v_pk_fma_f32 v[134:135], v[102:103], s[78:79], v[134:135] op_sel_hi:[1,0,1]
	v_pk_fma_f32 v[132:133], v[100:101], s[78:79], v[132:133] op_sel_hi:[1,0,1]
	v_lshl_add_u64 v[206:207], s[88:89], 0, v[220:221]
	global_store_dwordx4 v[206:207], v[132:135], off
	s_nop 1
	v_sub_f32_e32 v133, v211, v218
	v_sub_f32_e32 v132, v210, v218
	v_sub_f32_e32 v135, v213, v218
	v_sub_f32_e32 v134, v212, v218
	v_pk_mul_f32 v[134:135], v[218:219], v[134:135] op_sel:[1,0]
	v_pk_mul_f32 v[132:133], v[218:219], v[132:133] op_sel:[1,0]
	v_pk_fma_f32 v[130:131], v[188:189], v[134:135], v[130:131]
	v_pk_fma_f32 v[128:129], v[190:191], v[132:133], v[128:129]
	v_or_b32_e32 v132, 16, v148
	v_mov_b32_e32 v133, v159
	v_lshl_add_u64 v[132:133], v[132:133], 2, s[88:89]
	s_waitcnt vmcnt(0)
;     template <bool LN, int BJ, int LO, int HI> DI void batch(const f32x4 (&acc)[2][2][4][2], unsigned row0, unsigned col0, const f32x4 (&gv)[2], const f32x4 (&bv)[2]) const {
;         f32x4 r[HI - LO]; float mean[(HI - LO) / 2], rstd[(HI - LO) / 2];
; #pragma unroll
;         for (int i = LO; i < HI; ++i) { const int ai = i >> 3, m = (i >> 1) & 3, n = i & 1; const unsigned row = row0 + ai * HALF + m * 16;
;             if (n == 0) { mean[(i - LO) >> 1] = 0.f; rstd[(i - LO) >> 1] = 1.f;
;                 if (LN) { const float2 st = *(const float2*)(stats + row * 2u); mean[(i - LO) >> 1] = st.x; rstd[(i - LO) >> 1] = st.y; } }
;             r[i - LO] = *(const f32x4*)(src + (row * (unsigned)DM + col0 + BJ * HALF + n * 16)); }
; #pragma unroll
;         for (int i = LO; i < HI; ++i) { const int ai = i >> 3, m = (i >> 1) & 3, n = i & 1; const unsigned row = row0 + ai * HALF + m * 16;
;             *(f32x4*)(Y + (row * (unsigned)DM + col0 + BJ * HALF + n * 16)) = acc[ai][BJ][m][n] + ((r[i - LO] - mean[(i - LO) >> 1]) * rstd[(i - LO) >> 1]) * gv[n] + bv[n]; }
	v_pk_fma_f32 v[130:131], v[98:99], s[78:79], v[130:131] op_sel_hi:[1,0,1]
	v_pk_fma_f32 v[128:129], v[96:97], s[78:79], v[128:129] op_sel_hi:[1,0,1]
	global_store_dwordx4 v[132:133], v[128:131], off
	s_nop 1
	v_sub_f32_e32 v129, v215, v196
	v_sub_f32_e32 v128, v214, v196
	v_sub_f32_e32 v131, v217, v196
	v_sub_f32_e32 v130, v216, v196
	v_pk_mul_f32 v[130:131], v[196:197], v[130:131] op_sel:[1,0]
	v_pk_mul_f32 v[128:129], v[196:197], v[128:129] op_sel:[1,0]
	v_pk_fma_f32 v[126:127], v[192:193], v[130:131], v[126:127]
	v_pk_fma_f32 v[124:125], v[194:195], v[128:129], v[124:125]
	v_add_u32_e32 v128, 0x8000, v148
	v_mov_b32_e32 v129, v159
	v_pk_fma_f32 v[126:127], v[102:103], s[78:79], v[126:127] op_sel_hi:[1,0,1]
	v_pk_fma_f32 v[124:125], v[100:101], s[78:79], v[124:125] op_sel_hi:[1,0,1]
	v_lshl_add_u64 v[128:129], v[128:129], 2, s[88:89]
	global_store_dwordx4 v[128:129], v[124:127], off
	s_nop 1
	v_sub_f32_e32 v125, v137, v196
	v_sub_f32_e32 v124, v136, v196
	v_sub_f32_e32 v127, v139, v196
	v_sub_f32_e32 v126, v138, v196
	v_pk_mul_f32 v[126:127], v[196:197], v[126:127] op_sel:[1,0]
	v_pk_mul_f32 v[124:125], v[196:197], v[124:125] op_sel:[1,0]
	v_pk_fma_f32 v[122:123], v[188:189], v[126:127], v[122:123]
	v_pk_fma_f32 v[120:121], v[190:191], v[124:125], v[120:121]
	v_add_u32_e32 v124, 0x8010, v148
	v_mov_b32_e32 v125, v159
	v_pk_fma_f32 v[122:123], v[98:99], s[78:79], v[122:123] op_sel_hi:[1,0,1]
	v_pk_fma_f32 v[120:121], v[96:97], s[78:79], v[120:121] op_sel_hi:[1,0,1]
	v_lshl_add_u64 v[124:125], v[124:125], 2, s[88:89]
	global_store_dwordx4 v[124:125], v[120:123], off
	s_nop 1
	v_or_b32_e32 v122, 32, v203
	v_lshlrev_b32_e32 v124, 11, v122
	v_lshlrev_b32_e32 v120, 1, v122
	v_mov_b32_e32 v121, v159
	v_add_u32_e32 v122, v124, v158
	v_mov_b32_e32 v123, v159
	v_lshl_add_u64 v[120:121], v[120:121], 2, s[96:97]
	v_lshl_add_u64 v[122:123], v[122:123], 2, s[90:91]
	global_load_dwordx2 v[138:139], v[120:121], off
	global_load_dwordx4 v[126:129], v[122:123], off
	v_add_u32_e32 v122, v124, v204
	v_mov_b32_e32 v123, v159
	v_lshl_add_u64 v[122:123], v[122:123], 2, s[90:91]
	global_load_dwordx4 v[130:133], v[122:123], off
	v_or_b32_e32 v125, 48, v203
	v_lshlrev_b32_e32 v122, 1, v125
	v_lshlrev_b32_e32 v125, 11, v125
	v_mov_b32_e32 v123, v159
	v_add_u32_e32 v134, v125, v158
	v_mov_b32_e32 v135, v159
	v_lshl_add_u64 v[122:123], v[122:123], 2, s[96:97]
	v_lshl_add_u64 v[134:135], v[134:135], 2, s[90:91]
	global_load_dwordx2 v[196:197], v[122:123], off
	v_add_u32_e32 v206, v125, v204
	global_load_dwordx4 v[134:137], v[134:135], off
	v_mov_b32_e32 v207, v159
	v_lshl_add_u64 v[206:207], v[206:207], 2, s[90:91]
	global_load_dwordx4 v[206:209], v[206:207], off
	s_waitcnt vmcnt(0)
	v_sub_f32_e32 v127, v127, v138
	v_sub_f32_e32 v126, v126, v138
	v_sub_f32_e32 v129, v129, v138
	v_sub_f32_e32 v128, v128, v138
	v_pk_mul_f32 v[128:129], v[138:139], v[128:129] op_sel:[1,0]
	v_pk_mul_f32 v[126:127], v[138:139], v[126:127] op_sel:[1,0]
	v_pk_fma_f32 v[118:119], v[192:193], v[128:129], v[118:119]
	v_pk_fma_f32 v[116:117], v[194:195], v[126:127], v[116:117]
	v_add_u32_e32 v126, 0x10000, v148
	v_mov_b32_e32 v127, v159
	v_pk_fma_f32 v[118:119], v[102:103], s[78:79], v[118:119] op_sel_hi:[1,0,1]
	v_pk_fma_f32 v[116:117], v[100:101], s[78:79], v[116:117] op_sel_hi:[1,0,1]
	v_lshl_add_u64 v[126:127], v[126:127], 2, s[88:89]
	global_store_dwordx4 v[126:127], v[116:119], off
	s_nop 1
	v_sub_f32_e32 v117, v131, v138
	v_sub_f32_e32 v116, v130, v138
	v_sub_f32_e32 v119, v133, v138
	v_sub_f32_e32 v118, v132, v138
	v_pk_mul_f32 v[118:119], v[138:139], v[118:119] op_sel:[1,0]
	v_pk_mul_f32 v[116:117], v[138:139], v[116:117] op_sel:[1,0]
	v_pk_fma_f32 v[114:115], v[188:189], v[118:119], v[114:115]
	v_pk_fma_f32 v[112:113], v[190:191], v[116:117], v[112:113]
	v_add_u32_e32 v116, 0x10010, v148
	v_mov_b32_e32 v117, v159
	v_pk_fma_f32 v[114:115], v[98:99], s[78:79], v[114:115] op_sel_hi:[1,0,1]
	v_pk_fma_f32 v[112:113], v[96:97], s[78:79], v[112:113] op_sel_hi:[1,0,1]
	v_lshl_add_u64 v[116:117], v[116:117], 2, s[88:89]
	global_store_dwordx4 v[116:117], v[112:115], off
	s_nop 1
	v_sub_f32_e32 v113, v135, v196
	v_sub_f32_e32 v112, v134, v196
	v_sub_f32_e32 v115, v137, v196
	v_sub_f32_e32 v114, v136, v196
	v_pk_mul_f32 v[114:115], v[196:197], v[114:115] op_sel:[1,0]
	v_pk_mul_f32 v[112:113], v[196:197], v[112:113] op_sel:[1,0]
	v_pk_fma_f32 v[110:111], v[192:193], v[114:115], v[110:111]
	v_pk_fma_f32 v[108:109], v[194:195], v[112:113], v[108:109]
	v_add_u32_e32 v112, 0x18000, v148
	v_mov_b32_e32 v113, v159
	v_pk_fma_f32 v[110:111], v[102:103], s[78:79], v[110:111] op_sel_hi:[1,0,1]
	v_pk_fma_f32 v[108:109], v[100:101], s[78:79], v[108:109] op_sel_hi:[1,0,1]
	v_lshl_add_u64 v[112:113], v[112:113], 2, s[88:89]
	global_store_dwordx4 v[112:113], v[108:111], off
	s_nop 1
	v_sub_f32_e32 v109, v207, v196
	v_sub_f32_e32 v108, v206, v196
	v_sub_f32_e32 v111, v209, v196
	v_sub_f32_e32 v110, v208, v196
	v_pk_mul_f32 v[110:111], v[196:197], v[110:111] op_sel:[1,0]
	v_pk_mul_f32 v[108:109], v[196:197], v[108:109] op_sel:[1,0]
	v_pk_fma_f32 v[106:107], v[188:189], v[110:111], v[106:107]
	v_pk_fma_f32 v[104:105], v[190:191], v[108:109], v[104:105]
	v_add_u32_e32 v108, 0x18010, v148
	v_mov_b32_e32 v109, v159
	v_pk_fma_f32 v[106:107], v[98:99], s[78:79], v[106:107] op_sel_hi:[1,0,1]
	v_pk_fma_f32 v[104:105], v[96:97], s[78:79], v[104:105] op_sel_hi:[1,0,1]
	v_lshl_add_u64 v[108:109], v[108:109], 2, s[88:89]
	global_store_dwordx4 v[108:109], v[104:107], off
	s_nop 1
	v_add_u32_e32 v106, 0x80, v203
	v_lshlrev_b32_e32 v114, 11, v106
	v_lshlrev_b32_e32 v104, 1, v106
	v_mov_b32_e32 v105, v159
	v_add_u32_e32 v106, v114, v158
	v_mov_b32_e32 v107, v159
	v_lshl_add_u64 v[104:105], v[104:105], 2, s[96:97]
	v_lshl_add_u64 v[106:107], v[106:107], 2, s[90:91]
	global_load_dwordx2 v[112:113], v[104:105], off
	global_load_dwordx4 v[108:111], v[106:107], off
	v_add_u32_e32 v106, v114, v204
	v_mov_b32_e32 v107, v159
	v_lshl_add_u64 v[106:107], v[106:107], 2, s[90:91]
	global_load_dwordx4 v[116:119], v[106:107], off
	v_add_u32_e32 v115, 0x90, v203
	v_lshlrev_b32_e32 v106, 1, v115
	v_lshlrev_b32_e32 v115, 11, v115
	v_mov_b32_e32 v107, v159
	v_add_u32_e32 v126, v115, v158
	v_mov_b32_e32 v127, v159
	v_lshl_add_u64 v[106:107], v[106:107], 2, s[96:97]
	v_lshl_add_u64 v[126:127], v[126:127], 2, s[90:91]
	global_load_dwordx2 v[134:135], v[106:107], off
	v_add_u32_e32 v130, v115, v204
	global_load_dwordx4 v[126:129], v[126:127], off
	v_mov_b32_e32 v131, v159
	v_lshl_add_u64 v[130:131], v[130:131], 2, s[90:91]
	global_load_dwordx4 v[130:133], v[130:131], off
	s_waitcnt vmcnt(0)
;     template <bool LN, int BJ, int LO, int HI> DI void batch(const f32x4 (&acc)[2][2][4][2], unsigned row0, unsigned col0, const f32x4 (&gv)[2], const f32x4 (&bv)[2]) const {
;         f32x4 r[HI - LO]; float mean[(HI - LO) / 2], rstd[(HI - LO) / 2];
; #pragma unroll
;         for (int i = LO; i < HI; ++i) { const int ai = i >> 3, m = (i >> 1) & 3, n = i & 1; const unsigned row = row0 + ai * HALF + m * 16;
;             if (n == 0) { mean[(i - LO) >> 1] = 0.f; rstd[(i - LO) >> 1] = 1.f;
;                 if (LN) { const float2 st = *(const float2*)(stats + row * 2u); mean[(i - LO) >> 1] = st.x; rstd[(i - LO) >> 1] = st.y; } }
;             r[i - LO] = *(const f32x4*)(src + (row * (unsigned)DM + col0 + BJ * HALF + n * 16)); }
; #pragma unroll
;         for (int i = LO; i < HI; ++i) { const int ai = i >> 3, m = (i >> 1) & 3, n = i & 1; const unsigned row = row0 + ai * HALF + m * 16;
;             *(f32x4*)(Y + (row * (unsigned)DM + col0 + BJ * HALF + n * 16)) = acc[ai][BJ][m][n] + ((r[i - LO] - mean[(i - LO) >> 1]) * rstd[(i - LO) >> 1]) * gv[n] + bv[n]; }
	v_sub_f32_e32 v109, v109, v112
	v_sub_f32_e32 v108, v108, v112
	v_sub_f32_e32 v111, v111, v112
	v_sub_f32_e32 v110, v110, v112
	v_pk_mul_f32 v[110:111], v[112:113], v[110:111] op_sel:[1,0]
	v_pk_mul_f32 v[108:109], v[112:113], v[108:109] op_sel:[1,0]
	v_pk_fma_f32 v[94:95], v[192:193], v[110:111], v[94:95]
	v_pk_fma_f32 v[92:93], v[194:195], v[108:109], v[92:93]
	v_add_u32_e32 v108, 0x40000, v148
	v_mov_b32_e32 v109, v159
	v_pk_fma_f32 v[94:95], v[102:103], s[78:79], v[94:95] op_sel_hi:[1,0,1]
	v_pk_fma_f32 v[92:93], v[100:101], s[78:79], v[92:93] op_sel_hi:[1,0,1]
	v_lshl_add_u64 v[108:109], v[108:109], 2, s[88:89]
	global_store_dwordx4 v[108:109], v[92:95], off
	s_nop 1
	v_sub_f32_e32 v93, v117, v112
	v_sub_f32_e32 v92, v116, v112
	v_sub_f32_e32 v95, v119, v112
	v_sub_f32_e32 v94, v118, v112
	v_pk_mul_f32 v[94:95], v[112:113], v[94:95] op_sel:[1,0]
	v_pk_mul_f32 v[92:93], v[112:113], v[92:93] op_sel:[1,0]
	v_pk_fma_f32 v[90:91], v[188:189], v[94:95], v[90:91]
	v_pk_fma_f32 v[88:89], v[190:191], v[92:93], v[88:89]
	v_add_u32_e32 v92, 0x40010, v148
	v_mov_b32_e32 v93, v159
	v_pk_fma_f32 v[90:91], v[98:99], s[78:79], v[90:91] op_sel_hi:[1,0,1]
	v_pk_fma_f32 v[88:89], v[96:97], s[78:79], v[88:89] op_sel_hi:[1,0,1]
	v_lshl_add_u64 v[92:93], v[92:93], 2, s[88:89]
	global_store_dwordx4 v[92:93], v[88:91], off
	s_nop 1
	v_sub_f32_e32 v89, v127, v134
	v_sub_f32_e32 v88, v126, v134
	v_sub_f32_e32 v91, v129, v134
	v_sub_f32_e32 v90, v128, v134
	v_pk_mul_f32 v[90:91], v[134:135], v[90:91] op_sel:[1,0]
	v_pk_mul_f32 v[88:89], v[134:135], v[88:89] op_sel:[1,0]
	v_pk_fma_f32 v[86:87], v[192:193], v[90:91], v[86:87]
	v_pk_fma_f32 v[84:85], v[194:195], v[88:89], v[84:85]
	v_add_u32_e32 v88, 0x48000, v148
	v_mov_b32_e32 v89, v159
	v_pk_fma_f32 v[86:87], v[102:103], s[78:79], v[86:87] op_sel_hi:[1,0,1]
	v_pk_fma_f32 v[84:85], v[100:101], s[78:79], v[84:85] op_sel_hi:[1,0,1]
	v_lshl_add_u64 v[88:89], v[88:89], 2, s[88:89]
	global_store_dwordx4 v[88:89], v[84:87], off
	s_nop 1
	v_sub_f32_e32 v85, v131, v134
	v_sub_f32_e32 v84, v130, v134
	v_sub_f32_e32 v87, v133, v134
	v_sub_f32_e32 v86, v132, v134
	v_pk_mul_f32 v[86:87], v[134:135], v[86:87] op_sel:[1,0]
	v_pk_mul_f32 v[84:85], v[134:135], v[84:85] op_sel:[1,0]
	v_pk_fma_f32 v[82:83], v[188:189], v[86:87], v[82:83]
	v_pk_fma_f32 v[80:81], v[190:191], v[84:85], v[80:81]
	v_add_u32_e32 v84, 0x48010, v148
	v_mov_b32_e32 v85, v159
	v_pk_fma_f32 v[82:83], v[98:99], s[78:79], v[82:83] op_sel_hi:[1,0,1]
	v_pk_fma_f32 v[80:81], v[96:97], s[78:79], v[80:81] op_sel_hi:[1,0,1]
	v_lshl_add_u64 v[84:85], v[84:85], 2, s[88:89]
	global_store_dwordx4 v[84:85], v[80:83], off
	s_nop 1
	v_add_u32_e32 v82, 0xa0, v203
	v_lshlrev_b32_e32 v80, 1, v82
	v_mov_b32_e32 v81, v159
	v_lshlrev_b32_e32 v116, 11, v82
	v_lshl_add_u64 v[108:109], v[80:81], 2, s[96:97]
	v_add_u32_e32 v80, v116, v158
	v_lshl_add_u64 v[80:81], v[80:81], 2, s[90:91]
	global_load_dwordx2 v[112:113], v[108:109], off
	v_add_u32_e32 v84, v116, v204
	global_load_dwordx4 v[80:83], v[80:81], off
	v_mov_b32_e32 v85, v159
	v_lshl_add_u64 v[84:85], v[84:85], 2, s[90:91]
	global_load_dwordx4 v[84:87], v[84:85], off
	v_add_u32_e32 v90, 0xb0, v203
	v_lshlrev_b32_e32 v88, 1, v90
	v_mov_b32_e32 v89, v159
	v_lshlrev_b32_e32 v117, 11, v90
	v_lshl_add_u64 v[110:111], v[88:89], 2, s[96:97]
	v_add_u32_e32 v88, v117, v158
	v_lshl_add_u64 v[88:89], v[88:89], 2, s[90:91]
	global_load_dwordx2 v[118:119], v[110:111], off
	v_add_u32_e32 v92, v117, v204
	global_load_dwordx4 v[88:91], v[88:89], off
	v_mov_b32_e32 v93, v159
	v_lshl_add_u64 v[92:93], v[92:93], 2, s[90:91]
	global_load_dwordx4 v[92:95], v[92:93], off
	s_waitcnt vmcnt(0)
	v_sub_f32_e32 v81, v81, v112
	v_sub_f32_e32 v80, v80, v112
	v_sub_f32_e32 v83, v83, v112
	v_sub_f32_e32 v82, v82, v112
	v_pk_mul_f32 v[82:83], v[112:113], v[82:83] op_sel:[1,0]
	v_pk_mul_f32 v[80:81], v[112:113], v[80:81] op_sel:[1,0]
	v_pk_fma_f32 v[78:79], v[192:193], v[82:83], v[78:79]
	v_pk_fma_f32 v[76:77], v[194:195], v[80:81], v[76:77]
	v_add_u32_e32 v80, 0x50000, v148
	v_mov_b32_e32 v81, v159
	v_pk_fma_f32 v[78:79], v[102:103], s[78:79], v[78:79] op_sel_hi:[1,0,1]
	v_pk_fma_f32 v[76:77], v[100:101], s[78:79], v[76:77] op_sel_hi:[1,0,1]
	v_lshl_add_u64 v[80:81], v[80:81], 2, s[88:89]
	global_store_dwordx4 v[80:81], v[76:79], off
	s_nop 1
	v_sub_f32_e32 v77, v85, v112
	v_sub_f32_e32 v76, v84, v112
	v_sub_f32_e32 v79, v87, v112
	v_sub_f32_e32 v78, v86, v112
	v_pk_mul_f32 v[78:79], v[112:113], v[78:79] op_sel:[1,0]
	v_pk_mul_f32 v[76:77], v[112:113], v[76:77] op_sel:[1,0]
	v_pk_fma_f32 v[74:75], v[188:189], v[78:79], v[74:75]
	v_pk_fma_f32 v[72:73], v[190:191], v[76:77], v[72:73]
	v_add_u32_e32 v76, 0x50010, v148
	v_mov_b32_e32 v77, v159
	v_pk_fma_f32 v[74:75], v[98:99], s[78:79], v[74:75] op_sel_hi:[1,0,1]
	v_pk_fma_f32 v[72:73], v[96:97], s[78:79], v[72:73] op_sel_hi:[1,0,1]
	v_lshl_add_u64 v[76:77], v[76:77], 2, s[88:89]
	global_store_dwordx4 v[76:77], v[72:75], off
	s_nop 1
	v_sub_f32_e32 v73, v89, v118
	v_sub_f32_e32 v72, v88, v118
	v_sub_f32_e32 v75, v91, v118
	v_sub_f32_e32 v74, v90, v118
	v_pk_mul_f32 v[74:75], v[118:119], v[74:75] op_sel:[1,0]
	v_pk_mul_f32 v[72:73], v[118:119], v[72:73] op_sel:[1,0]
	v_pk_fma_f32 v[70:71], v[192:193], v[74:75], v[70:71]
	v_pk_fma_f32 v[68:69], v[194:195], v[72:73], v[68:69]
	v_add_u32_e32 v72, 0x58000, v148
	v_mov_b32_e32 v73, v159
	v_pk_fma_f32 v[70:71], v[102:103], s[78:79], v[70:71] op_sel_hi:[1,0,1]
	v_pk_fma_f32 v[68:69], v[100:101], s[78:79], v[68:69] op_sel_hi:[1,0,1]
	v_lshl_add_u64 v[72:73], v[72:73], 2, s[88:89]
	global_store_dwordx4 v[72:73], v[68:71], off
	s_nop 1
	v_sub_f32_e32 v69, v93, v118
	v_sub_f32_e32 v68, v92, v118
	v_sub_f32_e32 v71, v95, v118
	v_sub_f32_e32 v70, v94, v118
	v_pk_mul_f32 v[70:71], v[118:119], v[70:71] op_sel:[1,0]
	v_pk_mul_f32 v[68:69], v[118:119], v[68:69] op_sel:[1,0]
	v_pk_fma_f32 v[66:67], v[188:189], v[70:71], v[66:67]
	v_pk_fma_f32 v[64:65], v[190:191], v[68:69], v[64:65]
	v_add_u32_e32 v68, 0x58010, v148
	v_mov_b32_e32 v69, v159
	v_pk_fma_f32 v[66:67], v[98:99], s[78:79], v[66:67] op_sel_hi:[1,0,1]
	v_pk_fma_f32 v[64:65], v[96:97], s[78:79], v[64:65] op_sel_hi:[1,0,1]
	v_lshl_add_u64 v[68:69], v[68:69], 2, s[88:89]
	global_store_dwordx4 v[68:69], v[64:67], off
	global_load_dwordx4 v[64:67], v[150:151], off offset:512
	v_or_b32_e32 v119, 0x80, v158
	v_add_u32_e32 v72, v202, v119
	v_mov_b32_e32 v73, v159
	v_lshl_add_u64 v[72:73], v[72:73], 2, s[90:91]
	v_or_b32_e32 v118, 0x90, v158
	v_add_u32_e32 v158, v202, v118
	s_waitcnt vmcnt(0)
;     template <bool LN, int BJ, int LO, int HI> DI void batch(const f32x4 (&acc)[2][2][4][2], unsigned row0, unsigned col0, const f32x4 (&gv)[2], const f32x4 (&bv)[2]) const {
;         f32x4 r[HI - LO]; float mean[(HI - LO) / 2], rstd[(HI - LO) / 2];
; #pragma unroll
;         for (int i = LO; i < HI; ++i) { const int ai = i >> 3, m = (i >> 1) & 3, n = i & 1; const unsigned row = row0 + ai * HALF + m * 16;
;             if (n == 0) { mean[(i - LO) >> 1] = 0.f; rstd[(i - LO) >> 1] = 1.f;
;                 if (LN) { const float2 st = *(const float2*)(stats + row * 2u); mean[(i - LO) >> 1] = st.x; rstd[(i - LO) >> 1] = st.y; } }
;             r[i - LO] = *(const f32x4*)(src + (row * (unsigned)DM + col0 + BJ * HALF + n * 16)); }
; #pragma unroll
;         for (int i = LO; i < HI; ++i) { const int ai = i >> 3, m = (i >> 1) & 3, n = i & 1; const unsigned row = row0 + ai * HALF + m * 16;
;             *(f32x4*)(Y + (row * (unsigned)DM + col0 + BJ * HALF + n * 16)) = acc[ai][BJ][m][n] + ((r[i - LO] - mean[(i - LO) >> 1]) * rstd[(i - LO) >> 1]) * gv[n] + bv[n]; }
;         __builtin_amdgcn_sched_barrier(0);
;     }
;     template <bool LN, int BJ> DI void load_gb(unsigned col0, f32x4 (&gv)[2], f32x4 (&bv)[2]) const {
; #pragma unroll
;         for (int n = 0; n < 2; ++n) {
;             if (LN) { gv[n] = *(const f32x4*)(gam + col0 + BJ * HALF + n * 16) * ALPHA; bv[n] = *(const f32x4*)(bet + col0 + BJ * HALF + n * 16) * ALPHA; }
;     template <bool LN> DI void run(const f32x4 (&acc)[2][2][4][2], const Unit& u, int wr, int wc, int fr, int fq) const {
;     ...
;         load_gb<LN, 1>(col0, gv, bv);
;         batch<LN, 1, 0, 8>(acc, row0, col0, gv, bv);
	v_pk_mul_f32 v[96:97], v[66:67], s[78:79] op_sel_hi:[1,0]
	v_pk_mul_f32 v[98:99], v[64:65], s[78:79] op_sel_hi:[1,0]
	global_load_dwordx4 v[68:71], v[152:153], off offset:512
	global_load_dwordx4 v[64:67], v[150:151], off offset:576
	global_load_dwordx2 v[138:139], v[154:155], off
	global_load_dwordx4 v[126:129], v[72:73], off
	v_lshl_add_u64 v[72:73], v[158:159], 2, s[90:91]
	v_add_u32_e32 v158, v149, v119
	s_waitcnt vmcnt(0)
	v_pk_mul_f32 v[92:93], v[66:67], s[78:79] op_sel_hi:[1,0]
	v_pk_mul_f32 v[94:95], v[64:65], s[78:79] op_sel_hi:[1,0]
	global_load_dwordx4 v[64:67], v[152:153], off offset:576
	global_load_dwordx4 v[130:133], v[72:73], off
	global_load_dwordx2 v[112:113], v[186:187], off
	v_lshl_add_u64 v[72:73], v[158:159], 2, s[90:91]
	global_load_dwordx4 v[134:137], v[72:73], off
	v_add_u32_e32 v158, v149, v118
	v_lshl_add_u64 v[72:73], v[158:159], 2, s[90:91]
	global_load_dwordx4 v[88:91], v[72:73], off
	global_load_dwordx2 v[102:103], v[120:121], off
	v_add_u32_e32 v158, v124, v119
	v_lshl_add_u64 v[72:73], v[158:159], 2, s[90:91]
	global_load_dwordx4 v[84:87], v[72:73], off
	v_add_u32_e32 v158, v124, v118
	v_lshl_add_u64 v[72:73], v[158:159], 2, s[90:91]
	global_load_dwordx4 v[80:83], v[72:73], off
	global_load_dwordx2 v[100:101], v[122:123], off
	v_add_u32_e32 v158, v125, v119
	v_lshl_add_u64 v[72:73], v[158:159], 2, s[90:91]
	global_load_dwordx4 v[76:79], v[72:73], off
	v_add_u32_e32 v158, v125, v118
	v_lshl_add_u64 v[72:73], v[158:159], 2, s[90:91]
	global_load_dwordx4 v[72:75], v[72:73], off
	v_sub_f32_e32 v121, v127, v138
	v_sub_f32_e32 v120, v126, v138
	v_sub_f32_e32 v123, v129, v138
	v_sub_f32_e32 v122, v128, v138
	v_pk_mul_f32 v[122:123], v[138:139], v[122:123] op_sel:[1,0]
	v_pk_mul_f32 v[120:121], v[138:139], v[120:121] op_sel:[1,0]
	v_or_b32_e32 v158, 0x80, v148
	v_pk_fma_f32 v[60:61], v[98:99], v[120:121], v[60:61]
	v_pk_fma_f32 v[62:63], v[96:97], v[122:123], v[62:63]
	v_pk_fma_f32 v[60:61], v[68:69], s[78:79], v[60:61] op_sel_hi:[1,0,1]
	v_pk_fma_f32 v[62:63], v[70:71], s[78:79], v[62:63] op_sel_hi:[1,0,1]
	v_lshl_add_u64 v[120:121], v[158:159], 2, s[88:89]
	global_store_dwordx4 v[120:121], v[60:63], off
	v_or_b32_e32 v158, 0x90, v148
	s_waitcnt vmcnt(0)
	v_sub_f32_e32 v61, v131, v138
	v_sub_f32_e32 v60, v130, v138
	v_sub_f32_e32 v63, v133, v138
	v_sub_f32_e32 v62, v132, v138
	v_pk_mul_f32 v[62:63], v[138:139], v[62:63] op_sel:[1,0]
	v_pk_mul_f32 v[60:61], v[138:139], v[60:61] op_sel:[1,0]
	v_pk_fma_f32 v[58:59], v[92:93], v[62:63], v[58:59]
	v_pk_fma_f32 v[56:57], v[94:95], v[60:61], v[56:57]
	v_pk_fma_f32 v[58:59], v[66:67], s[78:79], v[58:59] op_sel_hi:[1,0,1]
	v_pk_fma_f32 v[56:57], v[64:65], s[78:79], v[56:57] op_sel_hi:[1,0,1]
	v_lshl_add_u64 v[60:61], v[158:159], 2, s[88:89]
	global_store_dwordx4 v[60:61], v[56:59], off
	v_add_u32_e32 v158, 0x8080, v148
	s_nop 0
	v_sub_f32_e32 v57, v135, v112
	v_sub_f32_e32 v56, v134, v112
	v_sub_f32_e32 v59, v137, v112
	v_sub_f32_e32 v58, v136, v112
	v_pk_mul_f32 v[58:59], v[112:113], v[58:59] op_sel:[1,0]
	v_pk_mul_f32 v[56:57], v[112:113], v[56:57] op_sel:[1,0]
	v_pk_fma_f32 v[54:55], v[96:97], v[58:59], v[54:55]
	v_pk_fma_f32 v[52:53], v[98:99], v[56:57], v[52:53]
	v_pk_fma_f32 v[54:55], v[70:71], s[78:79], v[54:55] op_sel_hi:[1,0,1]
	v_pk_fma_f32 v[52:53], v[68:69], s[78:79], v[52:53] op_sel_hi:[1,0,1]
	v_lshl_add_u64 v[56:57], v[158:159], 2, s[88:89]
	global_store_dwordx4 v[56:57], v[52:55], off
	v_add_u32_e32 v158, 0x8090, v148
	s_nop 0
	v_sub_f32_e32 v53, v89, v112
	v_sub_f32_e32 v52, v88, v112
	v_sub_f32_e32 v55, v91, v112
	v_sub_f32_e32 v54, v90, v112
	v_pk_mul_f32 v[54:55], v[112:113], v[54:55] op_sel:[1,0]
	v_pk_mul_f32 v[52:53], v[112:113], v[52:53] op_sel:[1,0]
	v_pk_fma_f32 v[50:51], v[92:93], v[54:55], v[50:51]
	v_pk_fma_f32 v[48:49], v[94:95], v[52:53], v[48:49]
	v_pk_fma_f32 v[50:51], v[66:67], s[78:79], v[50:51] op_sel_hi:[1,0,1]
	v_pk_fma_f32 v[48:49], v[64:65], s[78:79], v[48:49] op_sel_hi:[1,0,1]
	v_lshl_add_u64 v[52:53], v[158:159], 2, s[88:89]
	global_store_dwordx4 v[52:53], v[48:51], off
	v_add_u32_e32 v158, 0x10080, v148
	s_nop 0
	v_sub_f32_e32 v49, v85, v102
	v_sub_f32_e32 v48, v84, v102
	v_sub_f32_e32 v51, v87, v102
	v_sub_f32_e32 v50, v86, v102
	v_pk_mul_f32 v[50:51], v[102:103], v[50:51] op_sel:[1,0]
	v_pk_mul_f32 v[48:49], v[102:103], v[48:49] op_sel:[1,0]
	v_pk_fma_f32 v[46:47], v[96:97], v[50:51], v[46:47]
	v_pk_fma_f32 v[44:45], v[98:99], v[48:49], v[44:45]
	v_pk_fma_f32 v[46:47], v[70:71], s[78:79], v[46:47] op_sel_hi:[1,0,1]
	v_pk_fma_f32 v[44:45], v[68:69], s[78:79], v[44:45] op_sel_hi:[1,0,1]
	v_lshl_add_u64 v[48:49], v[158:159], 2, s[88:89]
	global_store_dwordx4 v[48:49], v[44:47], off
	v_add_u32_e32 v158, 0x10090, v148
	s_nop 0
	v_sub_f32_e32 v45, v81, v102
	v_sub_f32_e32 v44, v80, v102
	v_sub_f32_e32 v47, v83, v102
	v_sub_f32_e32 v46, v82, v102
	v_pk_mul_f32 v[46:47], v[102:103], v[46:47] op_sel:[1,0]
	v_pk_mul_f32 v[44:45], v[102:103], v[44:45] op_sel:[1,0]
	v_pk_fma_f32 v[42:43], v[92:93], v[46:47], v[42:43]
	v_pk_fma_f32 v[40:41], v[94:95], v[44:45], v[40:41]
	v_pk_fma_f32 v[42:43], v[66:67], s[78:79], v[42:43] op_sel_hi:[1,0,1]
	v_pk_fma_f32 v[40:41], v[64:65], s[78:79], v[40:41] op_sel_hi:[1,0,1]
	v_lshl_add_u64 v[44:45], v[158:159], 2, s[88:89]
	global_store_dwordx4 v[44:45], v[40:43], off
	v_add_u32_e32 v158, 0x18080, v148
	s_nop 0
	v_sub_f32_e32 v41, v77, v100
	v_sub_f32_e32 v40, v76, v100
	v_sub_f32_e32 v43, v79, v100
	v_sub_f32_e32 v42, v78, v100
	v_pk_mul_f32 v[42:43], v[100:101], v[42:43] op_sel:[1,0]
	v_pk_mul_f32 v[40:41], v[100:101], v[40:41] op_sel:[1,0]
	v_pk_fma_f32 v[38:39], v[96:97], v[42:43], v[38:39]
;     template <bool LN, int BJ, int LO, int HI> DI void batch(const f32x4 (&acc)[2][2][4][2], unsigned row0, unsigned col0, const f32x4 (&gv)[2], const f32x4 (&bv)[2]) const {
;         f32x4 r[HI - LO]; float mean[(HI - LO) / 2], rstd[(HI - LO) / 2];
; #pragma unroll
;         for (int i = LO; i < HI; ++i) { const int ai = i >> 3, m = (i >> 1) & 3, n = i & 1; const unsigned row = row0 + ai * HALF + m * 16;
;             if (n == 0) { mean[(i - LO) >> 1] = 0.f; rstd[(i - LO) >> 1] = 1.f;
;                 if (LN) { const float2 st = *(const float2*)(stats + row * 2u); mean[(i - LO) >> 1] = st.x; rstd[(i - LO) >> 1] = st.y; } }
;             r[i - LO] = *(const f32x4*)(src + (row * (unsigned)DM + col0 + BJ * HALF + n * 16)); }
; #pragma unroll
;         for (int i = LO; i < HI; ++i) { const int ai = i >> 3, m = (i >> 1) & 3, n = i & 1; const unsigned row = row0 + ai * HALF + m * 16;
;             *(f32x4*)(Y + (row * (unsigned)DM + col0 + BJ * HALF + n * 16)) = acc[ai][BJ][m][n] + ((r[i - LO] - mean[(i - LO) >> 1]) * rstd[(i - LO) >> 1]) * gv[n] + bv[n]; }
	v_pk_fma_f32 v[36:37], v[98:99], v[40:41], v[36:37]
	v_pk_fma_f32 v[38:39], v[70:71], s[78:79], v[38:39] op_sel_hi:[1,0,1]
	v_pk_fma_f32 v[36:37], v[68:69], s[78:79], v[36:37] op_sel_hi:[1,0,1]
	v_lshl_add_u64 v[40:41], v[158:159], 2, s[88:89]
	global_store_dwordx4 v[40:41], v[36:39], off
	v_add_u32_e32 v158, 0x18090, v148
	s_nop 0
	v_sub_f32_e32 v37, v73, v100
	v_sub_f32_e32 v36, v72, v100
	v_sub_f32_e32 v39, v75, v100
	v_sub_f32_e32 v38, v74, v100
	v_pk_mul_f32 v[38:39], v[100:101], v[38:39] op_sel:[1,0]
	v_pk_mul_f32 v[36:37], v[100:101], v[36:37] op_sel:[1,0]
	v_pk_fma_f32 v[34:35], v[92:93], v[38:39], v[34:35]
	v_pk_fma_f32 v[32:33], v[94:95], v[36:37], v[32:33]
	v_pk_fma_f32 v[34:35], v[66:67], s[78:79], v[34:35] op_sel_hi:[1,0,1]
	v_pk_fma_f32 v[32:33], v[64:65], s[78:79], v[32:33] op_sel_hi:[1,0,1]
	v_lshl_add_u64 v[36:37], v[158:159], 2, s[88:89]
	global_store_dwordx4 v[36:37], v[32:35], off
	v_add_u32_e32 v158, v114, v119
	s_nop 0
	v_lshl_add_u64 v[32:33], v[158:159], 2, s[90:91]
	global_load_dwordx2 v[62:63], v[104:105], off
	global_load_dwordx4 v[54:57], v[32:33], off
	v_add_u32_e32 v158, v114, v118
	v_lshl_add_u64 v[32:33], v[158:159], 2, s[90:91]
	global_load_dwordx4 v[58:61], v[32:33], off
	global_load_dwordx2 v[52:53], v[106:107], off
	v_add_u32_e32 v158, v115, v119
	v_lshl_add_u64 v[32:33], v[158:159], 2, s[90:91]
	global_load_dwordx4 v[72:75], v[32:33], off
	v_add_u32_e32 v158, v115, v118
	v_lshl_add_u64 v[32:33], v[158:159], 2, s[90:91]
	global_load_dwordx4 v[76:79], v[32:33], off
	global_load_dwordx2 v[50:51], v[108:109], off
	v_add_u32_e32 v158, v116, v119
	v_lshl_add_u64 v[32:33], v[158:159], 2, s[90:91]
	global_load_dwordx4 v[44:47], v[32:33], off
	v_add_u32_e32 v158, v116, v118
	v_lshl_add_u64 v[32:33], v[158:159], 2, s[90:91]
	global_load_dwordx4 v[40:43], v[32:33], off
	global_load_dwordx2 v[48:49], v[110:111], off
	v_add_u32_e32 v158, v117, v119
	v_lshl_add_u64 v[32:33], v[158:159], 2, s[90:91]
	global_load_dwordx4 v[36:39], v[32:33], off
	v_add_u32_e32 v158, v117, v118
	v_lshl_add_u64 v[32:33], v[158:159], 2, s[90:91]
	global_load_dwordx4 v[32:35], v[32:33], off
	v_add_u32_e32 v158, 0x40080, v148
	s_waitcnt vmcnt(0)
; #define PG8_WAIT_V(n) asm volatile("s_waitcnt vmcnt(" #n ")" ::: "memory")
; #define PG8_BAR __builtin_amdgcn_s_barrier()
; template <class Epi>
; DI void gemm_phase(LAS unsigned char* lds, const Gemm g, const StaticOrder& S, const Epi& E) {
;     ...
;         E(acc, cur, wr, wc, fr, fq);
;         if (!has_next) break;
; #pragma unroll
;         for (int a = 0; a < 2; ++a)
; #pragma unroll
;             for (int b = 0; b < 2; ++b)
; #pragma unroll
;                 for (int m = 0; m < 4; ++m)
; #pragma unroll
;                     for (int n = 0; n < 2; ++n) acc[a][b][m][n] = (f32x4){0.f, 0.f, 0.f, 0.f};
;         cur = nxt; cA = nA; cB = nB; ++ui;
;     }
;     PG8_WAIT_V(0);
;     if (wr == 0) PG8_BAR;
;     template <bool LN, int BJ, int LO, int HI> DI void batch(const f32x4 (&acc)[2][2][4][2], unsigned row0, unsigned col0, const f32x4 (&gv)[2], const f32x4 (&bv)[2]) const {
;         f32x4 r[HI - LO]; float mean[(HI - LO) / 2], rstd[(HI - LO) / 2];
; #pragma unroll
;         for (int i = LO; i < HI; ++i) { const int ai = i >> 3, m = (i >> 1) & 3, n = i & 1; const unsigned row = row0 + ai * HALF + m * 16;
;             if (n == 0) { mean[(i - LO) >> 1] = 0.f; rstd[(i - LO) >> 1] = 1.f;
;                 if (LN) { const float2 st = *(const float2*)(stats + row * 2u); mean[(i - LO) >> 1] = st.x; rstd[(i - LO) >> 1] = st.y; } }
;             r[i - LO] = *(const f32x4*)(src + (row * (unsigned)DM + col0 + BJ * HALF + n * 16)); }
; #pragma unroll
;         for (int i = LO; i < HI; ++i) { const int ai = i >> 3, m = (i >> 1) & 3, n = i & 1; const unsigned row = row0 + ai * HALF + m * 16;
;             *(f32x4*)(Y + (row * (unsigned)DM + col0 + BJ * HALF + n * 16)) = acc[ai][BJ][m][n] + ((r[i - LO] - mean[(i - LO) >> 1]) * rstd[(i - LO) >> 1]) * gv[n] + bv[n]; }
	v_sub_f32_e32 v55, v55, v62
	v_sub_f32_e32 v54, v54, v62
	v_sub_f32_e32 v57, v57, v62
	v_sub_f32_e32 v56, v56, v62
	v_pk_mul_f32 v[56:57], v[62:63], v[56:57] op_sel:[1,0]
	v_pk_mul_f32 v[54:55], v[62:63], v[54:55] op_sel:[1,0]
	v_pk_fma_f32 v[30:31], v[96:97], v[56:57], v[30:31]
	v_pk_fma_f32 v[28:29], v[98:99], v[54:55], v[28:29]
	v_pk_fma_f32 v[30:31], v[70:71], s[78:79], v[30:31] op_sel_hi:[1,0,1]
	v_pk_fma_f32 v[28:29], v[68:69], s[78:79], v[28:29] op_sel_hi:[1,0,1]
	v_lshl_add_u64 v[54:55], v[158:159], 2, s[88:89]
	global_store_dwordx4 v[54:55], v[28:31], off
	v_add_u32_e32 v158, 0x40090, v148
	s_nop 0
	v_sub_f32_e32 v29, v59, v62
	v_sub_f32_e32 v28, v58, v62
	v_sub_f32_e32 v31, v61, v62
	v_sub_f32_e32 v30, v60, v62
	v_pk_mul_f32 v[30:31], v[62:63], v[30:31] op_sel:[1,0]
	v_pk_mul_f32 v[28:29], v[62:63], v[28:29] op_sel:[1,0]
	v_pk_fma_f32 v[26:27], v[92:93], v[30:31], v[26:27]
	v_pk_fma_f32 v[24:25], v[94:95], v[28:29], v[24:25]
	v_pk_fma_f32 v[26:27], v[66:67], s[78:79], v[26:27] op_sel_hi:[1,0,1]
	v_pk_fma_f32 v[24:25], v[64:65], s[78:79], v[24:25] op_sel_hi:[1,0,1]
	v_lshl_add_u64 v[28:29], v[158:159], 2, s[88:89]
	global_store_dwordx4 v[28:29], v[24:27], off
	v_add_u32_e32 v158, 0x48080, v148
	s_nop 0
	v_sub_f32_e32 v25, v73, v52
	v_sub_f32_e32 v24, v72, v52
	v_sub_f32_e32 v27, v75, v52
	v_sub_f32_e32 v26, v74, v52
	v_pk_mul_f32 v[26:27], v[52:53], v[26:27] op_sel:[1,0]
	v_pk_mul_f32 v[24:25], v[52:53], v[24:25] op_sel:[1,0]
	v_pk_fma_f32 v[22:23], v[96:97], v[26:27], v[22:23]
	v_pk_fma_f32 v[20:21], v[98:99], v[24:25], v[20:21]
	v_pk_fma_f32 v[22:23], v[70:71], s[78:79], v[22:23] op_sel_hi:[1,0,1]
	v_pk_fma_f32 v[20:21], v[68:69], s[78:79], v[20:21] op_sel_hi:[1,0,1]
	v_lshl_add_u64 v[24:25], v[158:159], 2, s[88:89]
	global_store_dwordx4 v[24:25], v[20:23], off
	v_add_u32_e32 v158, 0x48090, v148
	s_nop 0
	v_sub_f32_e32 v21, v77, v52
	v_sub_f32_e32 v20, v76, v52
	v_sub_f32_e32 v23, v79, v52
	v_sub_f32_e32 v22, v78, v52
	v_pk_mul_f32 v[22:23], v[52:53], v[22:23] op_sel:[1,0]
	v_pk_mul_f32 v[20:21], v[52:53], v[20:21] op_sel:[1,0]
	v_pk_fma_f32 v[18:19], v[92:93], v[22:23], v[18:19]
	v_pk_fma_f32 v[16:17], v[94:95], v[20:21], v[16:17]
	v_pk_fma_f32 v[18:19], v[66:67], s[78:79], v[18:19] op_sel_hi:[1,0,1]
	v_pk_fma_f32 v[16:17], v[64:65], s[78:79], v[16:17] op_sel_hi:[1,0,1]
	v_lshl_add_u64 v[20:21], v[158:159], 2, s[88:89]
	global_store_dwordx4 v[20:21], v[16:19], off
	v_add_u32_e32 v158, 0x50080, v148
	s_nop 0
	v_sub_f32_e32 v17, v45, v50
	v_sub_f32_e32 v16, v44, v50
	v_sub_f32_e32 v19, v47, v50
	v_sub_f32_e32 v18, v46, v50
	v_pk_mul_f32 v[18:19], v[50:51], v[18:19] op_sel:[1,0]
	v_pk_mul_f32 v[16:17], v[50:51], v[16:17] op_sel:[1,0]
	v_pk_fma_f32 v[14:15], v[96:97], v[18:19], v[14:15]
	v_pk_fma_f32 v[12:13], v[98:99], v[16:17], v[12:13]
	v_pk_fma_f32 v[14:15], v[70:71], s[78:79], v[14:15] op_sel_hi:[1,0,1]
	v_pk_fma_f32 v[12:13], v[68:69], s[78:79], v[12:13] op_sel_hi:[1,0,1]
	v_lshl_add_u64 v[16:17], v[158:159], 2, s[88:89]
	global_store_dwordx4 v[16:17], v[12:15], off
	v_add_u32_e32 v158, 0x50090, v148
	s_nop 0
	v_sub_f32_e32 v13, v41, v50
	v_sub_f32_e32 v12, v40, v50
	v_sub_f32_e32 v15, v43, v50
	v_sub_f32_e32 v14, v42, v50
	v_pk_mul_f32 v[14:15], v[50:51], v[14:15] op_sel:[1,0]
	v_pk_mul_f32 v[12:13], v[50:51], v[12:13] op_sel:[1,0]
	v_pk_fma_f32 v[10:11], v[92:93], v[14:15], v[10:11]
	v_pk_fma_f32 v[8:9], v[94:95], v[12:13], v[8:9]
	v_pk_fma_f32 v[10:11], v[66:67], s[78:79], v[10:11] op_sel_hi:[1,0,1]
	v_pk_fma_f32 v[8:9], v[64:65], s[78:79], v[8:9] op_sel_hi:[1,0,1]
	v_lshl_add_u64 v[12:13], v[158:159], 2, s[88:89]
	global_store_dwordx4 v[12:13], v[8:11], off
	v_add_u32_e32 v158, 0x58080, v148
	s_nop 0
	v_sub_f32_e32 v9, v37, v48
	v_sub_f32_e32 v8, v36, v48
	v_sub_f32_e32 v11, v39, v48
	v_sub_f32_e32 v10, v38, v48
	v_pk_mul_f32 v[10:11], v[48:49], v[10:11] op_sel:[1,0]
	v_pk_mul_f32 v[8:9], v[48:49], v[8:9] op_sel:[1,0]
	v_pk_fma_f32 v[6:7], v[96:97], v[10:11], v[6:7]
	v_pk_fma_f32 v[4:5], v[98:99], v[8:9], v[4:5]
	v_pk_fma_f32 v[6:7], v[70:71], s[78:79], v[6:7] op_sel_hi:[1,0,1]
	v_pk_fma_f32 v[4:5], v[68:69], s[78:79], v[4:5] op_sel_hi:[1,0,1]
	v_lshl_add_u64 v[8:9], v[158:159], 2, s[88:89]
	global_store_dwordx4 v[8:9], v[4:7], off
	v_add_u32_e32 v158, 0x58090, v148
	s_nop 0
	v_sub_f32_e32 v5, v33, v48
	v_sub_f32_e32 v4, v32, v48
	v_sub_f32_e32 v7, v35, v48
	v_sub_f32_e32 v6, v34, v48
	v_pk_mul_f32 v[6:7], v[48:49], v[6:7] op_sel:[1,0]
	v_pk_mul_f32 v[4:5], v[48:49], v[4:5] op_sel:[1,0]
	v_pk_fma_f32 v[2:3], v[92:93], v[6:7], v[2:3]
	v_pk_fma_f32 v[0:1], v[94:95], v[4:5], v[0:1]
	v_pk_fma_f32 v[2:3], v[66:67], s[78:79], v[2:3] op_sel_hi:[1,0,1]
	v_pk_fma_f32 v[0:1], v[64:65], s[78:79], v[0:1] op_sel_hi:[1,0,1]
	v_lshl_add_u64 v[4:5], v[158:159], 2, s[88:89]
	global_store_dwordx4 v[4:5], v[0:3], off
	s_and_b64 vcc, exec, s[6:7]
	s_mov_b32 s2, s37
	s_mov_b32 s3, s38
	s_mov_b64 s[18:19], s[10:11]
	s_mov_b64 s[16:17], s[8:9]
	v_readlane_b32 s33, v255, 39
	s_cbranch_vccz .LBB0_123
	s_waitcnt vmcnt(0)
	s_cmpk_gt_u32 s24, 0xff
	s_cbranch_scc1 .LBB0_138
	s_barrier

; #define PG8_STAGE(bufoff, gbase) do { _Pragma("unroll") for (int _i = 0; _i < 2; ++_i) \
;         __builtin_amdgcn_global_load_lds((const unsigned*)((const char*)(gbase) + voff[_i]), (LAS unsigned*)(lds + (bufoff) + ldsw + _i * 8192), 16, 0, 0); } while (0)
; #define PG8_LDA(dst, b, h) do { _Pragma("unroll") for (int m = 0; m < 4; ++m) _Pragma("unroll") for (int k = 0; k < 2; ++k) dst[m][k] = *(const LAS bf16x8*)(lds + PG8_SA(b, h) + aoff + m * 2048 + k * 1024); } while (0)
; #define PG8_LDB(dst, b, h) do { _Pragma("unroll") for (int n = 0; n < 2; ++n) _Pragma("unroll") for (int k = 0; k < 2; ++k) dst[n][k] = *(const LAS bf16x8*)(lds + PG8_SB(b, h) + boff + n * 2048 + k * 1024); } while (0)
; #define PG8_MMA(ai, bj, At, Bt) do { __builtin_amdgcn_s_setprio(1); _Pragma("unroll") for (int m = 0; m < 4; ++m) _Pragma("unroll") for (int n = 0; n < 2; ++n) _Pragma("unroll") for (int k = 0; k < 2; ++k) \
;         acc[ai][bj][m][n] = __builtin_amdgcn_mfma_f32_16x16x32_bf16(Bt[n][k], At[m][k], acc[ai][bj][m][n], 0, 0, 0); __builtin_amdgcn_s_setprio(0); } while (0)
; #define PG8_WAIT_L(n) asm volatile("s_waitcnt lgkmcnt(" #n ")" ::: "memory")
; #define PG8_BAR __builtin_amdgcn_s_barrier()
; #define PG8_SCHED __builtin_amdgcn_sched_barrier(0)
; template <class Epi>
; DI void gemm_phase(LAS unsigned char* lds, const Gemm g, const StaticOrder& S, const Epi& E) {
;     ...
;             PG8_LDB(B0, 0, 0); PG8_SCHED; PG8_LDA(At, 0, 0); PG8_STAGE(PG8_SA(1, 1), a1 + hstep);
;             PG8_WAIT_L(8); PG8_BAR; PG8_WAIT_L(0); PG8_MMA(0, 0, At, B0); PG8_BAR; PG8_SCHED;
;             PG8_LDB(B1, 0, 1); PG8_STAGE(PG8_SB(0, 0), b2);
;             PG8_BAR; PG8_WAIT_L(0); PG8_MMA(0, 1, At, B1); PG8_BAR;
;             PG8_LDA(At, 0, 1); PG8_STAGE(PG8_SA(0, 0), a2);
;             PG8_BAR; PG8_WAIT_L(0); PG8_MMA(1, 0, At, B0); PG8_BAR; PG8_SCHED;
.LBB0_202:
	s_add_u32 s18, s8, 0xfff80080
	s_addc_u32 s19, s9, -1
	s_add_i32 s37, 0, 0x10000
	s_waitcnt lgkmcnt(0)
	ds_read_b128 v[128:131], v187
	ds_read_b128 v[132:135], v187 offset:1024
	ds_read_b128 v[136:139], v187 offset:2048
	ds_read_b128 v[190:193], v187 offset:3072
	s_cmp_eq_u32 s36, 28
	s_cselect_b32 s21, s4, s19
	s_cselect_b32 s20, s5, s18
	s_cselect_b32 s19, s11, s35
	s_cselect_b32 s18, s13, s33
	s_add_i32 m0, s26, 0xc000
	ds_read_b128 v[194:197], v189
	ds_read_b128 v[198:201], v189 offset:1024
	ds_read_b128 v[202:205], v189 offset:2048
	ds_read_b128 v[206:209], v189 offset:3072
	ds_read_b128 v[210:213], v189 offset:4096
	ds_read_b128 v[214:217], v189 offset:5120
	ds_read_b128 v[226:229], v189 offset:6144
	ds_read_b128 v[230:233], v189 offset:7168
	global_load_lds_dwordx4 v150, s[8:9]
	s_add_i32 m0, s26, 0xe000
	s_nop 0
	global_load_lds_dwordx4 v152, s[8:9]
	s_waitcnt lgkmcnt(8)
	s_setprio 1
	s_barrier
	s_waitcnt lgkmcnt(0)
	v_mfma_f32_16x16x32_bf16 v[124:127], v[128:131], v[194:197], v[124:127]
	v_mfma_f32_16x16x32_bf16 v[120:123], v[136:139], v[194:197], v[120:123]
	v_mfma_f32_16x16x32_bf16 v[108:111], v[128:131], v[202:205], v[108:111]
	v_mfma_f32_16x16x32_bf16 v[104:107], v[136:139], v[202:205], v[104:107]
	v_mfma_f32_16x16x32_bf16 v[92:95], v[128:131], v[210:213], v[92:95]
	v_mfma_f32_16x16x32_bf16 v[88:91], v[136:139], v[210:213], v[88:91]
	v_mfma_f32_16x16x32_bf16 v[76:79], v[128:131], v[226:229], v[76:79]
	v_mfma_f32_16x16x32_bf16 v[72:75], v[136:139], v[226:229], v[72:75]
	v_mfma_f32_16x16x32_bf16 v[124:127], v[132:135], v[198:201], v[124:127]
	v_mfma_f32_16x16x32_bf16 v[120:123], v[190:193], v[198:201], v[120:123]
	v_mfma_f32_16x16x32_bf16 v[108:111], v[132:135], v[206:209], v[108:111]
	v_mfma_f32_16x16x32_bf16 v[104:107], v[190:193], v[206:209], v[104:107]
	v_mfma_f32_16x16x32_bf16 v[92:95], v[132:135], v[214:217], v[92:95]
	v_mfma_f32_16x16x32_bf16 v[88:91], v[190:193], v[214:217], v[88:91]
	v_mfma_f32_16x16x32_bf16 v[76:79], v[132:135], v[230:233], v[76:79]
	s_setprio 0
	v_mfma_f32_16x16x32_bf16 v[72:75], v[190:193], v[230:233], v[72:75]
	s_barrier
	s_add_i32 s40, 0, 0x14000
	s_add_i32 s37, s37, s25
	ds_read_b128 v[234:237], v187 offset:16384
	ds_read_b128 v[238:241], v187 offset:17408
	ds_read_b128 v[242:245], v187 offset:18432
	ds_read_b128 v[246:249], v187 offset:19456
	v_lshl_add_u64 v[140:141], s[18:19], 0, v[144:145]
	s_mov_b32 m0, s37
	v_lshl_add_u64 v[154:155], s[18:19], 0, v[142:143]
	global_load_lds_dwordx4 v[140:141], off
	s_add_i32 m0, s37, 0x2000
	s_nop 0
	global_load_lds_dwordx4 v[154:155], off
	s_waitcnt lgkmcnt(0)
	s_setprio 1
	s_barrier
	v_mfma_f32_16x16x32_bf16 v[116:119], v[234:237], v[194:197], v[116:119]
	v_mfma_f32_16x16x32_bf16 v[112:115], v[242:245], v[194:197], v[112:115]
	v_mfma_f32_16x16x32_bf16 v[100:103], v[234:237], v[202:205], v[100:103]
	v_mfma_f32_16x16x32_bf16 v[96:99], v[242:245], v[202:205], v[96:99]
	v_mfma_f32_16x16x32_bf16 v[84:87], v[234:237], v[210:213], v[84:87]
	v_mfma_f32_16x16x32_bf16 v[80:83], v[242:245], v[210:213], v[80:83]
	v_mfma_f32_16x16x32_bf16 v[68:71], v[234:237], v[226:229], v[68:71]
	v_mfma_f32_16x16x32_bf16 v[64:67], v[242:245], v[226:229], v[64:67]
	v_mfma_f32_16x16x32_bf16 v[116:119], v[238:241], v[198:201], v[116:119]
	s_mov_b32 m0, s26
	v_mfma_f32_16x16x32_bf16 v[112:115], v[246:249], v[198:201], v[112:115]
	v_lshl_add_u64 v[218:219], s[20:21], 0, v[144:145]
	v_mfma_f32_16x16x32_bf16 v[100:103], v[238:241], v[206:209], v[100:103]
	v_mfma_f32_16x16x32_bf16 v[96:99], v[246:249], v[206:209], v[96:99]
	v_mfma_f32_16x16x32_bf16 v[84:87], v[238:241], v[214:217], v[84:87]
	v_mfma_f32_16x16x32_bf16 v[80:83], v[246:249], v[214:217], v[80:83]
	v_mfma_f32_16x16x32_bf16 v[68:71], v[238:241], v[230:233], v[68:71]
	s_setprio 0
	v_mfma_f32_16x16x32_bf16 v[64:67], v[246:249], v[230:233], v[64:67]
	s_barrier
	ds_read_b128 v[194:197], v189 offset:16384
	ds_read_b128 v[198:201], v189 offset:17408
	ds_read_b128 v[202:205], v189 offset:18432
	ds_read_b128 v[206:209], v189 offset:19456
	ds_read_b128 v[210:213], v189 offset:20480
	ds_read_b128 v[214:217], v189 offset:21504
	ds_read_b128 v[226:229], v189 offset:22528
	ds_read_b128 v[230:233], v189 offset:23552
	global_load_lds_dwordx4 v[218:219], off
	v_lshl_add_u64 v[250:251], s[20:21], 0, v[142:143]
	s_mov_b32 m0, s27
	s_nop 0
	global_load_lds_dwordx4 v[250:251], off
	s_waitcnt lgkmcnt(0)
	s_setprio 1
	s_barrier
	v_mfma_f32_16x16x32_bf16 v[60:63], v[128:131], v[194:197], v[60:63]
	v_mfma_f32_16x16x32_bf16 v[56:59], v[136:139], v[194:197], v[56:59]
	v_mfma_f32_16x16x32_bf16 v[44:47], v[128:131], v[202:205], v[44:47]
	v_mfma_f32_16x16x32_bf16 v[40:43], v[136:139], v[202:205], v[40:43]
	v_mfma_f32_16x16x32_bf16 v[28:31], v[128:131], v[210:213], v[28:31]
	v_mfma_f32_16x16x32_bf16 v[24:27], v[136:139], v[210:213], v[24:27]
	v_mfma_f32_16x16x32_bf16 v[12:15], v[128:131], v[226:229], v[12:15]
	v_mfma_f32_16x16x32_bf16 v[8:11], v[136:139], v[226:229], v[8:11]
	v_mfma_f32_16x16x32_bf16 v[60:63], v[132:135], v[198:201], v[60:63]
	v_mfma_f32_16x16x32_bf16 v[56:59], v[190:193], v[198:201], v[56:59]
	v_mfma_f32_16x16x32_bf16 v[44:47], v[132:135], v[206:209], v[44:47]
	v_mfma_f32_16x16x32_bf16 v[40:43], v[190:193], v[206:209], v[40:43]
	v_mfma_f32_16x16x32_bf16 v[28:31], v[132:135], v[214:217], v[28:31]
	v_mfma_f32_16x16x32_bf16 v[24:27], v[190:193], v[214:217], v[24:27]
	v_mfma_f32_16x16x32_bf16 v[12:15], v[132:135], v[230:233], v[12:15]
	s_setprio 0
	v_mfma_f32_16x16x32_bf16 v[8:11], v[190:193], v[230:233], v[8:11]
	s_barrier
; #define PG8_STAGE(bufoff, gbase) do { _Pragma("unroll") for (int _i = 0; _i < 2; ++_i) \
;         __builtin_amdgcn_global_load_lds((const unsigned*)((const char*)(gbase) + voff[_i]), (LAS unsigned*)(lds + (bufoff) + ldsw + _i * 8192), 16, 0, 0); } while (0)
; #define PG8_LDA(dst, b, h) do { _Pragma("unroll") for (int m = 0; m < 4; ++m) _Pragma("unroll") for (int k = 0; k < 2; ++k) dst[m][k] = *(const LAS bf16x8*)(lds + PG8_SA(b, h) + aoff + m * 2048 + k * 1024); } while (0)
; #define PG8_LDB(dst, b, h) do { _Pragma("unroll") for (int n = 0; n < 2; ++n) _Pragma("unroll") for (int k = 0; k < 2; ++k) dst[n][k] = *(const LAS bf16x8*)(lds + PG8_SB(b, h) + boff + n * 2048 + k * 1024); } while (0)
; #define PG8_MMA(ai, bj, At, Bt) do { __builtin_amdgcn_s_setprio(1); _Pragma("unroll") for (int m = 0; m < 4; ++m) _Pragma("unroll") for (int n = 0; n < 2; ++n) _Pragma("unroll") for (int k = 0; k < 2; ++k) \
;         acc[ai][bj][m][n] = __builtin_amdgcn_mfma_f32_16x16x32_bf16(Bt[n][k], At[m][k], acc[ai][bj][m][n], 0, 0, 0); __builtin_amdgcn_s_setprio(0); } while (0)
; #define PG8_WAIT_V(n) asm volatile("s_waitcnt vmcnt(" #n ")" ::: "memory")
; #define PG8_WAIT_L(n) asm volatile("s_waitcnt lgkmcnt(" #n ")" ::: "memory")
; #define PG8_BAR __builtin_amdgcn_s_barrier()
; #define PG8_SCHED __builtin_amdgcn_sched_barrier(0)
; template <class Epi>
; DI void gemm_phase(LAS unsigned char* lds, const Gemm g, const StaticOrder& S, const Epi& E) {
;     ...
;             PG8_STAGE(PG8_SB(0, 1), b2 + hstep);
;             PG8_WAIT_V(6); PG8_BAR; PG8_MMA(1, 1, At, B1); PG8_BAR;
;             PG8_LDB(B0, 1, 0); PG8_SCHED; PG8_LDA(At, 1, 0); PG8_STAGE(PG8_SA(0, 1), a2 + hstep);
;             PG8_WAIT_L(8); PG8_BAR; PG8_WAIT_L(0); PG8_MMA(0, 0, At, B0); PG8_BAR; PG8_SCHED;
;             PG8_LDB(B1, 1, 1); PG8_STAGE(PG8_SB(1, 0), b3);
;             PG8_BAR; PG8_WAIT_L(0); PG8_MMA(0, 1, At, B1); PG8_BAR;
;             PG8_LDA(At, 1, 1); PG8_STAGE(PG8_SA(1, 0), a3);
;             PG8_BAR; PG8_WAIT_L(0); PG8_MMA(1, 0, At, B0); PG8_BAR; PG8_SCHED;
	s_add_u32 s38, s18, 0x80000
	s_addc_u32 s39, s19, 0
	s_add_i32 s37, s40, s25
	s_mov_b32 m0, s37
	s_nop 0
	global_load_lds_dwordx4 v144, s[38:39]
	s_add_i32 m0, s37, 0x2000
	s_nop 0
	global_load_lds_dwordx4 v142, s[38:39]
	s_waitcnt vmcnt(6)
	s_setprio 1
	s_barrier
	v_mfma_f32_16x16x32_bf16 v[52:55], v[234:237], v[194:197], v[52:55]
	v_mfma_f32_16x16x32_bf16 v[48:51], v[242:245], v[194:197], v[48:51]
	v_mfma_f32_16x16x32_bf16 v[36:39], v[234:237], v[202:205], v[36:39]
	v_mfma_f32_16x16x32_bf16 v[32:35], v[242:245], v[202:205], v[32:35]
	v_mfma_f32_16x16x32_bf16 v[20:23], v[234:237], v[210:213], v[20:23]
	v_mfma_f32_16x16x32_bf16 v[16:19], v[242:245], v[210:213], v[16:19]
	v_mfma_f32_16x16x32_bf16 v[4:7], v[234:237], v[226:229], v[4:7]
	v_mfma_f32_16x16x32_bf16 v[0:3], v[242:245], v[226:229], v[0:3]
	v_mfma_f32_16x16x32_bf16 v[52:55], v[238:241], v[198:201], v[52:55]
	s_add_i32 s37, 0, 0x18000
	v_mfma_f32_16x16x32_bf16 v[48:51], v[246:249], v[198:201], v[48:51]
	v_mfma_f32_16x16x32_bf16 v[36:39], v[238:241], v[206:209], v[36:39]
	v_mfma_f32_16x16x32_bf16 v[32:35], v[246:249], v[206:209], v[32:35]
	v_mfma_f32_16x16x32_bf16 v[20:23], v[238:241], v[214:217], v[20:23]
	v_mfma_f32_16x16x32_bf16 v[16:19], v[246:249], v[214:217], v[16:19]
	v_mfma_f32_16x16x32_bf16 v[4:7], v[238:241], v[230:233], v[4:7]
	s_setprio 0
	v_mfma_f32_16x16x32_bf16 v[0:3], v[246:249], v[230:233], v[0:3]
	s_barrier
	ds_read_b128 v[128:131], v187 offset:32768
	ds_read_b128 v[132:135], v187 offset:33792
	ds_read_b128 v[136:139], v187 offset:34816
	ds_read_b128 v[190:193], v187 offset:35840
	s_add_u32 s20, s20, 0x80000
	s_addc_u32 s21, s21, 0
	s_mov_b32 m0, s28
	ds_read_b128 v[194:197], v189 offset:32768
	ds_read_b128 v[198:201], v189 offset:33792
	ds_read_b128 v[202:205], v189 offset:34816
	ds_read_b128 v[206:209], v189 offset:35840
	ds_read_b128 v[210:213], v189 offset:36864
	ds_read_b128 v[214:217], v189 offset:37888
	ds_read_b128 v[226:229], v189 offset:38912
	ds_read_b128 v[230:233], v189 offset:39936
	global_load_lds_dwordx4 v144, s[20:21]
	s_mov_b32 m0, s29
	s_nop 0
	global_load_lds_dwordx4 v142, s[20:21]
	s_waitcnt lgkmcnt(8)
	s_setprio 1
	s_barrier
	s_waitcnt lgkmcnt(0)
	v_mfma_f32_16x16x32_bf16 v[124:127], v[128:131], v[194:197], v[124:127]
	v_mfma_f32_16x16x32_bf16 v[120:123], v[136:139], v[194:197], v[120:123]
	v_mfma_f32_16x16x32_bf16 v[108:111], v[128:131], v[202:205], v[108:111]
	v_mfma_f32_16x16x32_bf16 v[104:107], v[136:139], v[202:205], v[104:107]
	v_mfma_f32_16x16x32_bf16 v[92:95], v[128:131], v[210:213], v[92:95]
	v_mfma_f32_16x16x32_bf16 v[88:91], v[136:139], v[210:213], v[88:91]
	v_mfma_f32_16x16x32_bf16 v[76:79], v[128:131], v[226:229], v[76:79]
	v_mfma_f32_16x16x32_bf16 v[72:75], v[136:139], v[226:229], v[72:75]
	v_mfma_f32_16x16x32_bf16 v[124:127], v[132:135], v[198:201], v[124:127]
	v_mfma_f32_16x16x32_bf16 v[120:123], v[190:193], v[198:201], v[120:123]
	v_mfma_f32_16x16x32_bf16 v[108:111], v[132:135], v[206:209], v[108:111]
	v_mfma_f32_16x16x32_bf16 v[104:107], v[190:193], v[206:209], v[104:107]
	v_mfma_f32_16x16x32_bf16 v[92:95], v[132:135], v[214:217], v[92:95]
	v_mfma_f32_16x16x32_bf16 v[88:91], v[190:193], v[214:217], v[88:91]
	v_mfma_f32_16x16x32_bf16 v[76:79], v[132:135], v[230:233], v[76:79]
	s_setprio 0
	v_mfma_f32_16x16x32_bf16 v[72:75], v[190:193], v[230:233], v[72:75]
	s_barrier
	s_add_i32 s20, 0, 0x1c000
	s_add_i32 s21, s37, s25
	s_add_i32 m0, s21, 0xffffff80
	ds_read_b128 v[234:237], v187 offset:49152
	ds_read_b128 v[238:241], v187 offset:50176
	ds_read_b128 v[242:245], v187 offset:51200
	ds_read_b128 v[246:249], v187 offset:52224
	global_load_lds_dwordx4 v[140:141], off offset:128
	s_add_i32 m0, s21, 0x1f80
	s_nop 0
	global_load_lds_dwordx4 v[154:155], off offset:128
	s_waitcnt lgkmcnt(0)
	s_setprio 1
	s_barrier
	v_mfma_f32_16x16x32_bf16 v[116:119], v[234:237], v[194:197], v[116:119]
	v_mfma_f32_16x16x32_bf16 v[112:115], v[242:245], v[194:197], v[112:115]
	v_mfma_f32_16x16x32_bf16 v[100:103], v[234:237], v[202:205], v[100:103]
	v_mfma_f32_16x16x32_bf16 v[96:99], v[242:245], v[202:205], v[96:99]
	v_mfma_f32_16x16x32_bf16 v[84:87], v[234:237], v[210:213], v[84:87]
	v_mfma_f32_16x16x32_bf16 v[80:83], v[242:245], v[210:213], v[80:83]
	v_mfma_f32_16x16x32_bf16 v[68:71], v[234:237], v[226:229], v[68:71]
	v_mfma_f32_16x16x32_bf16 v[64:67], v[242:245], v[226:229], v[64:67]
	v_mfma_f32_16x16x32_bf16 v[116:119], v[238:241], v[198:201], v[116:119]
	s_mov_b32 m0, s30
	v_mfma_f32_16x16x32_bf16 v[112:115], v[246:249], v[198:201], v[112:115]
	v_lshl_add_u64 v[140:141], v[218:219], 0, s[94:95]
	v_mfma_f32_16x16x32_bf16 v[100:103], v[238:241], v[206:209], v[100:103]
	v_mfma_f32_16x16x32_bf16 v[96:99], v[246:249], v[206:209], v[96:99]
	v_mfma_f32_16x16x32_bf16 v[84:87], v[238:241], v[214:217], v[84:87]
	v_mfma_f32_16x16x32_bf16 v[80:83], v[246:249], v[214:217], v[80:83]
	v_mfma_f32_16x16x32_bf16 v[68:71], v[238:241], v[230:233], v[68:71]
	s_setprio 0
	v_mfma_f32_16x16x32_bf16 v[64:67], v[246:249], v[230:233], v[64:67]
	s_barrier
; #define PG8_STAGE(bufoff, gbase) do { _Pragma("unroll") for (int _i = 0; _i < 2; ++_i) \
;         __builtin_amdgcn_global_load_lds((const unsigned*)((const char*)(gbase) + voff[_i]), (LAS unsigned*)(lds + (bufoff) + ldsw + _i * 8192), 16, 0, 0); } while (0)
; #define PG8_MMA(ai, bj, At, Bt) do { __builtin_amdgcn_s_setprio(1); _Pragma("unroll") for (int m = 0; m < 4; ++m) _Pragma("unroll") for (int n = 0; n < 2; ++n) _Pragma("unroll") for (int k = 0; k < 2; ++k) \
;         acc[ai][bj][m][n] = __builtin_amdgcn_mfma_f32_16x16x32_bf16(Bt[n][k], At[m][k], acc[ai][bj][m][n], 0, 0, 0); __builtin_amdgcn_s_setprio(0); } while (0)
; #define PG8_WAIT_V(n) asm volatile("s_waitcnt vmcnt(" #n ")" ::: "memory")
; #define PG8_WAIT_L(n) asm volatile("s_waitcnt lgkmcnt(" #n ")" ::: "memory")
; #define PG8_BAR __builtin_amdgcn_s_barrier()
; #define PG8_SCHED __builtin_amdgcn_sched_barrier(0)
; template <class Epi>
; DI void gemm_phase(LAS unsigned char* lds, const Gemm g, const StaticOrder& S, const Epi& E) {
;     ...
;             PG8_BAR; PG8_WAIT_L(0); PG8_MMA(1, 0, At, B0); PG8_BAR; PG8_SCHED;
;             PG8_STAGE(PG8_SB(1, 1), b3 + hstep);
;             PG8_WAIT_V(6); PG8_BAR; PG8_MMA(1, 1, At, B1); PG8_BAR;
;     DI void operator()(const f32x4 (&acc)[2][2][4][2], const Unit& u, int wr, int wc, int fr, int fq) const {
;         const int row0 = u.pm * BM + wr * 64 + fr, col0 = u.pn * BM + wc * 16 + 4 * fq;
;         const bool rot = u.pn < 18;
; #pragma unroll
;         for (int ai = 0; ai < 2; ++ai)
; #pragma unroll
;             for (int m = 0; m < 4; ++m) { const int row = row0 + ai * HALF + m * 16; u16* rowp = O + (size_t)row * NQKV_DIL + col0;
;                 f32x4 c4 = (f32x4){1.f, 1.f, 1.f, 1.f}, s4 = (f32x4){0.f, 0.f, 0.f, 0.f};
;                 if (rot) { const int pos = row & (SEQ - 1); c4 = *(const f32x4*)(cs + pos * 64 + wc * 16 + 4 * fq); s4 = *(const f32x4*)(sn + pos * 64 + wc * 16 + 4 * fq); }
	ds_read_b128 v[194:197], v189 offset:49152
	ds_read_b128 v[198:201], v189 offset:50176
	ds_read_b128 v[202:205], v189 offset:51200
	ds_read_b128 v[206:209], v189 offset:52224
	ds_read_b128 v[210:213], v189 offset:53248
	ds_read_b128 v[214:217], v189 offset:54272
	ds_read_b128 v[226:229], v189 offset:55296
	ds_read_b128 v[230:233], v189 offset:56320
	global_load_lds_dwordx4 v[140:141], off
	s_add_i32 m0, s31, 0xffffff80
	s_nop 0
	global_load_lds_dwordx4 v[250:251], off offset:128
	s_waitcnt lgkmcnt(0)
	s_setprio 1
	s_barrier
	v_mfma_f32_16x16x32_bf16 v[60:63], v[128:131], v[194:197], v[60:63]
	v_mfma_f32_16x16x32_bf16 v[56:59], v[136:139], v[194:197], v[56:59]
	v_mfma_f32_16x16x32_bf16 v[44:47], v[128:131], v[202:205], v[44:47]
	v_mfma_f32_16x16x32_bf16 v[40:43], v[136:139], v[202:205], v[40:43]
	v_mfma_f32_16x16x32_bf16 v[28:31], v[128:131], v[210:213], v[28:31]
	v_mfma_f32_16x16x32_bf16 v[24:27], v[136:139], v[210:213], v[24:27]
	v_mfma_f32_16x16x32_bf16 v[12:15], v[128:131], v[226:229], v[12:15]
	v_mfma_f32_16x16x32_bf16 v[8:11], v[136:139], v[226:229], v[8:11]
	v_mfma_f32_16x16x32_bf16 v[60:63], v[132:135], v[198:201], v[60:63]
	v_mfma_f32_16x16x32_bf16 v[56:59], v[190:193], v[198:201], v[56:59]
	v_mfma_f32_16x16x32_bf16 v[44:47], v[132:135], v[206:209], v[44:47]
	v_mfma_f32_16x16x32_bf16 v[40:43], v[190:193], v[206:209], v[40:43]
	v_mfma_f32_16x16x32_bf16 v[28:31], v[132:135], v[214:217], v[28:31]
	v_mfma_f32_16x16x32_bf16 v[24:27], v[190:193], v[214:217], v[24:27]
	v_mfma_f32_16x16x32_bf16 v[12:15], v[132:135], v[230:233], v[12:15]
	s_setprio 0
	v_mfma_f32_16x16x32_bf16 v[8:11], v[190:193], v[230:233], v[8:11]
	s_barrier
	s_add_u32 s18, s18, 0x80080
	s_addc_u32 s19, s19, 0
	s_add_i32 s20, s20, s25
	s_mov_b32 m0, s20
	s_nop 0
	global_load_lds_dwordx4 v144, s[18:19]
	s_add_i32 m0, s20, 0x2000
	s_nop 0
	global_load_lds_dwordx4 v142, s[18:19]
	s_waitcnt vmcnt(6)
	s_setprio 1
	s_barrier
	v_mfma_f32_16x16x32_bf16 v[52:55], v[234:237], v[194:197], v[52:55]
	v_mfma_f32_16x16x32_bf16 v[48:51], v[242:245], v[194:197], v[48:51]
	v_mfma_f32_16x16x32_bf16 v[36:39], v[234:237], v[202:205], v[36:39]
	v_mfma_f32_16x16x32_bf16 v[32:35], v[242:245], v[202:205], v[32:35]
	v_mfma_f32_16x16x32_bf16 v[20:23], v[234:237], v[210:213], v[20:23]
	v_mfma_f32_16x16x32_bf16 v[16:19], v[242:245], v[210:213], v[16:19]
	v_mfma_f32_16x16x32_bf16 v[4:7], v[234:237], v[226:229], v[4:7]
	v_mfma_f32_16x16x32_bf16 v[0:3], v[242:245], v[226:229], v[0:3]
	v_mfma_f32_16x16x32_bf16 v[52:55], v[238:241], v[198:201], v[52:55]
	s_add_i32 s36, s36, 2
	v_mfma_f32_16x16x32_bf16 v[48:51], v[246:249], v[198:201], v[48:51]
	s_add_u32 s8, s8, 0x100
	v_mfma_f32_16x16x32_bf16 v[36:39], v[238:241], v[206:209], v[36:39]
	s_addc_u32 s9, s9, 0
	v_mfma_f32_16x16x32_bf16 v[32:35], v[246:249], v[206:209], v[32:35]
	s_add_u32 s33, s33, 0x100
	v_mfma_f32_16x16x32_bf16 v[20:23], v[238:241], v[214:217], v[20:23]
	s_addc_u32 s35, s35, 0
	v_mfma_f32_16x16x32_bf16 v[16:19], v[246:249], v[214:217], v[16:19]
	s_cmp_gt_u32 s36, 29
	v_mfma_f32_16x16x32_bf16 v[4:7], v[238:241], v[230:233], v[4:7]
	s_setprio 0
	v_mfma_f32_16x16x32_bf16 v[0:3], v[246:249], v[230:233], v[0:3]
	s_barrier
	s_cbranch_scc0 .LBB0_202
	s_cmp_lt_i32 s2, 18
	v_lshl_add_u32 v190, s3, 8, v186
	v_mov_b32_e32 v128, 1.0
	v_mov_b32_e32 v132, 0
	s_cselect_b64 s[18:19], -1, 0
	s_cmp_gt_i32 s2, 17
	v_mov_b32_e32 v134, 0
	v_mov_b32_e32 v135, 0
	v_mov_b32_e32 v136, 0
	v_mov_b32_e32 v137, 0
	v_mov_b32_e32 v138, 1.0
	v_mov_b32_e32 v139, 1.0
	v_mov_b32_e32 v140, 1.0
	v_mov_b32_e32 v141, 1.0
	s_cbranch_scc1 .LBB0_205
	v_lshlrev_b32_e32 v129, 8, v190
	v_and_b32_e32 v158, 0xfcf00, v129
	v_lshl_add_u64 v[130:131], v[146:147], 0, v[158:159]
	v_lshl_add_u64 v[134:135], v[148:149], 0, v[158:159]
	global_load_dwordx4 v[138:141], v[130:131], off
	s_nop 0
	global_load_dwordx4 v[134:137], v[134:135], off

; #define PG8_STAGE(bufoff, gbase) do { _Pragma("unroll") for (int _i = 0; _i < 2; ++_i) \
;         __builtin_amdgcn_global_load_lds((const unsigned*)((const char*)(gbase) + voff[_i]), (LAS unsigned*)(lds + (bufoff) + ldsw + _i * 8192), 16, 0, 0); } while (0)
; #define PG8_LDA(dst, b, h) do { _Pragma("unroll") for (int m = 0; m < 4; ++m) _Pragma("unroll") for (int k = 0; k < 2; ++k) dst[m][k] = *(const LAS bf16x8*)(lds + PG8_SA(b, h) + aoff + m * 2048 + k * 1024); } while (0)
; #define PG8_LDB(dst, b, h) do { _Pragma("unroll") for (int n = 0; n < 2; ++n) _Pragma("unroll") for (int k = 0; k < 2; ++k) dst[n][k] = *(const LAS bf16x8*)(lds + PG8_SB(b, h) + boff + n * 2048 + k * 1024); } while (0)
; #define PG8_MMA(ai, bj, At, Bt) do { __builtin_amdgcn_s_setprio(1); _Pragma("unroll") for (int m = 0; m < 4; ++m) _Pragma("unroll") for (int n = 0; n < 2; ++n) _Pragma("unroll") for (int k = 0; k < 2; ++k) \
;         acc[ai][bj][m][n] = __builtin_amdgcn_mfma_f32_16x16x32_bf16(Bt[n][k], At[m][k], acc[ai][bj][m][n], 0, 0, 0); __builtin_amdgcn_s_setprio(0); } while (0)
; #define PG8_WAIT_L(n) asm volatile("s_waitcnt lgkmcnt(" #n ")" ::: "memory")
; #define PG8_BAR __builtin_amdgcn_s_barrier()
; #define PG8_SCHED __builtin_amdgcn_sched_barrier(0)
; template <class Epi>
; DI void gemm_phase(LAS unsigned char* lds, const Gemm g, const StaticOrder& S, const Epi& E) {
;     ...
;             PG8_LDB(B0, 0, 0); PG8_SCHED; PG8_LDA(At, 0, 0); PG8_STAGE(PG8_SA(1, 1), a1 + hstep);
;             PG8_WAIT_L(8); PG8_BAR; PG8_WAIT_L(0); PG8_MMA(0, 0, At, B0); PG8_BAR; PG8_SCHED;
;             PG8_LDB(B1, 0, 1); PG8_STAGE(PG8_SB(0, 0), b2);
;             PG8_BAR; PG8_WAIT_L(0); PG8_MMA(0, 1, At, B1); PG8_BAR;
;             PG8_LDA(At, 0, 1); PG8_STAGE(PG8_SA(0, 0), a2);
;             PG8_BAR; PG8_WAIT_L(0); PG8_MMA(1, 0, At, B0); PG8_BAR; PG8_SCHED;
.LBB0_231:
	s_add_u32 s18, s16, 0xfff80080
	s_addc_u32 s19, s17, -1
	s_add_i32 s37, 0, 0x10000
	ds_read_b128 v[138:141], v135
	ds_read_b128 v[142:145], v135 offset:1024
	ds_read_b128 v[146:149], v135 offset:2048
	ds_read_b128 v[150:153], v135 offset:3072
	s_cmp_eq_u32 s36, 28
	s_cselect_b32 s21, s4, s19
	s_cselect_b32 s20, s5, s18
	s_cselect_b32 s19, s9, s35
	s_cselect_b32 s18, s11, s34
	s_add_i32 m0, s24, 0xc000
	ds_read_b128 v[186:189], v137
	ds_read_b128 v[190:193], v137 offset:1024
	ds_read_b128 v[194:197], v137 offset:2048
	ds_read_b128 v[198:201], v137 offset:3072
	ds_read_b128 v[202:205], v137 offset:4096
	ds_read_b128 v[206:209], v137 offset:5120
	ds_read_b128 v[210:213], v137 offset:6144
	ds_read_b128 v[214:217], v137 offset:7168
	global_load_lds_dwordx4 v130, s[16:17]
	s_add_i32 m0, s24, 0xe000
	s_nop 0
	global_load_lds_dwordx4 v132, s[16:17]
	s_waitcnt lgkmcnt(8)
	s_setprio 1
	s_barrier
	s_waitcnt lgkmcnt(0)
	v_mfma_f32_16x16x32_bf16 v[124:127], v[138:141], v[186:189], v[124:127]
	v_mfma_f32_16x16x32_bf16 v[120:123], v[146:149], v[186:189], v[120:123]
	v_mfma_f32_16x16x32_bf16 v[116:119], v[138:141], v[194:197], v[116:119]
	v_mfma_f32_16x16x32_bf16 v[112:115], v[146:149], v[194:197], v[112:115]
	v_mfma_f32_16x16x32_bf16 v[100:103], v[138:141], v[202:205], v[100:103]
	v_mfma_f32_16x16x32_bf16 v[96:99], v[146:149], v[202:205], v[96:99]
	v_mfma_f32_16x16x32_bf16 v[84:87], v[138:141], v[210:213], v[84:87]
	v_mfma_f32_16x16x32_bf16 v[80:83], v[146:149], v[210:213], v[80:83]
	v_mfma_f32_16x16x32_bf16 v[124:127], v[142:145], v[190:193], v[124:127]
	v_mfma_f32_16x16x32_bf16 v[120:123], v[150:153], v[190:193], v[120:123]
	v_mfma_f32_16x16x32_bf16 v[116:119], v[142:145], v[198:201], v[116:119]
	v_mfma_f32_16x16x32_bf16 v[112:115], v[150:153], v[198:201], v[112:115]
	v_mfma_f32_16x16x32_bf16 v[100:103], v[142:145], v[206:209], v[100:103]
	v_mfma_f32_16x16x32_bf16 v[96:99], v[150:153], v[206:209], v[96:99]
	v_mfma_f32_16x16x32_bf16 v[84:87], v[142:145], v[214:217], v[84:87]
	s_setprio 0
	v_mfma_f32_16x16x32_bf16 v[80:83], v[150:153], v[214:217], v[80:83]
	s_barrier
	s_add_i32 s40, 0, 0x14000
	s_add_i32 s37, s37, s23
	ds_read_b128 v[226:229], v135 offset:16384
	ds_read_b128 v[230:233], v135 offset:17408
	ds_read_b128 v[234:237], v135 offset:18432
	ds_read_b128 v[238:241], v135 offset:19456
	v_lshl_add_u64 v[154:155], s[18:19], 0, v[158:159]
	s_mov_b32 m0, s37
	v_lshl_add_u64 v[218:219], s[18:19], 0, v[128:129]
	global_load_lds_dwordx4 v[154:155], off
	s_add_i32 m0, s37, 0x2000
	s_nop 0
	global_load_lds_dwordx4 v[218:219], off
	s_waitcnt lgkmcnt(0)
	s_setprio 1
	s_barrier
	v_mfma_f32_16x16x32_bf16 v[108:111], v[226:229], v[186:189], v[108:111]
	v_mfma_f32_16x16x32_bf16 v[104:107], v[234:237], v[186:189], v[104:107]
	v_mfma_f32_16x16x32_bf16 v[92:95], v[226:229], v[194:197], v[92:95]
	v_mfma_f32_16x16x32_bf16 v[88:91], v[234:237], v[194:197], v[88:91]
	v_mfma_f32_16x16x32_bf16 v[76:79], v[226:229], v[202:205], v[76:79]
	v_mfma_f32_16x16x32_bf16 v[72:75], v[234:237], v[202:205], v[72:75]
	v_mfma_f32_16x16x32_bf16 v[68:71], v[226:229], v[210:213], v[68:71]
	v_mfma_f32_16x16x32_bf16 v[64:67], v[234:237], v[210:213], v[64:67]
	v_mfma_f32_16x16x32_bf16 v[108:111], v[230:233], v[190:193], v[108:111]
	s_mov_b32 m0, s24
	v_mfma_f32_16x16x32_bf16 v[104:107], v[238:241], v[190:193], v[104:107]
	v_lshl_add_u64 v[242:243], s[20:21], 0, v[158:159]
	v_mfma_f32_16x16x32_bf16 v[92:95], v[230:233], v[198:201], v[92:95]
	v_mfma_f32_16x16x32_bf16 v[88:91], v[238:241], v[198:201], v[88:91]
	v_mfma_f32_16x16x32_bf16 v[76:79], v[230:233], v[206:209], v[76:79]
	v_mfma_f32_16x16x32_bf16 v[72:75], v[238:241], v[206:209], v[72:75]
	v_mfma_f32_16x16x32_bf16 v[68:71], v[230:233], v[214:217], v[68:71]
	s_setprio 0
	v_mfma_f32_16x16x32_bf16 v[64:67], v[238:241], v[214:217], v[64:67]
	s_barrier
	ds_read_b128 v[186:189], v137 offset:16384
	ds_read_b128 v[190:193], v137 offset:17408
	ds_read_b128 v[194:197], v137 offset:18432
	ds_read_b128 v[198:201], v137 offset:19456
	ds_read_b128 v[202:205], v137 offset:20480
	ds_read_b128 v[206:209], v137 offset:21504
	ds_read_b128 v[210:213], v137 offset:22528
	ds_read_b128 v[214:217], v137 offset:23552
	global_load_lds_dwordx4 v[242:243], off
	v_lshl_add_u64 v[244:245], s[20:21], 0, v[128:129]
	s_mov_b32 m0, s25
	s_nop 0
	global_load_lds_dwordx4 v[244:245], off
	s_waitcnt lgkmcnt(0)
	s_setprio 1
	s_barrier
	v_mfma_f32_16x16x32_bf16 v[60:63], v[138:141], v[186:189], v[60:63]
	v_mfma_f32_16x16x32_bf16 v[56:59], v[146:149], v[186:189], v[56:59]
	v_mfma_f32_16x16x32_bf16 v[52:55], v[138:141], v[194:197], v[52:55]
	v_mfma_f32_16x16x32_bf16 v[48:51], v[146:149], v[194:197], v[48:51]
	v_mfma_f32_16x16x32_bf16 v[36:39], v[138:141], v[202:205], v[36:39]
	v_mfma_f32_16x16x32_bf16 v[32:35], v[146:149], v[202:205], v[32:35]
	v_mfma_f32_16x16x32_bf16 v[20:23], v[138:141], v[210:213], v[20:23]
	v_mfma_f32_16x16x32_bf16 v[16:19], v[146:149], v[210:213], v[16:19]
	v_mfma_f32_16x16x32_bf16 v[60:63], v[142:145], v[190:193], v[60:63]
	v_mfma_f32_16x16x32_bf16 v[56:59], v[150:153], v[190:193], v[56:59]
	v_mfma_f32_16x16x32_bf16 v[52:55], v[142:145], v[198:201], v[52:55]
	v_mfma_f32_16x16x32_bf16 v[48:51], v[150:153], v[198:201], v[48:51]
	v_mfma_f32_16x16x32_bf16 v[36:39], v[142:145], v[206:209], v[36:39]
	v_mfma_f32_16x16x32_bf16 v[32:35], v[150:153], v[206:209], v[32:35]
	v_mfma_f32_16x16x32_bf16 v[20:23], v[142:145], v[214:217], v[20:23]
	s_setprio 0
	v_mfma_f32_16x16x32_bf16 v[16:19], v[150:153], v[214:217], v[16:19]
	s_barrier
; #define PG8_STAGE(bufoff, gbase) do { _Pragma("unroll") for (int _i = 0; _i < 2; ++_i) \
;         __builtin_amdgcn_global_load_lds((const unsigned*)((const char*)(gbase) + voff[_i]), (LAS unsigned*)(lds + (bufoff) + ldsw + _i * 8192), 16, 0, 0); } while (0)
; #define PG8_LDA(dst, b, h) do { _Pragma("unroll") for (int m = 0; m < 4; ++m) _Pragma("unroll") for (int k = 0; k < 2; ++k) dst[m][k] = *(const LAS bf16x8*)(lds + PG8_SA(b, h) + aoff + m * 2048 + k * 1024); } while (0)
; #define PG8_LDB(dst, b, h) do { _Pragma("unroll") for (int n = 0; n < 2; ++n) _Pragma("unroll") for (int k = 0; k < 2; ++k) dst[n][k] = *(const LAS bf16x8*)(lds + PG8_SB(b, h) + boff + n * 2048 + k * 1024); } while (0)
; #define PG8_MMA(ai, bj, At, Bt) do { __builtin_amdgcn_s_setprio(1); _Pragma("unroll") for (int m = 0; m < 4; ++m) _Pragma("unroll") for (int n = 0; n < 2; ++n) _Pragma("unroll") for (int k = 0; k < 2; ++k) \
;         acc[ai][bj][m][n] = __builtin_amdgcn_mfma_f32_16x16x32_bf16(Bt[n][k], At[m][k], acc[ai][bj][m][n], 0, 0, 0); __builtin_amdgcn_s_setprio(0); } while (0)
; #define PG8_WAIT_V(n) asm volatile("s_waitcnt vmcnt(" #n ")" ::: "memory")
; #define PG8_WAIT_L(n) asm volatile("s_waitcnt lgkmcnt(" #n ")" ::: "memory")
; #define PG8_BAR __builtin_amdgcn_s_barrier()
; #define PG8_SCHED __builtin_amdgcn_sched_barrier(0)
; template <class Epi>
; DI void gemm_phase(LAS unsigned char* lds, const Gemm g, const StaticOrder& S, const Epi& E) {
;     ...
;             PG8_STAGE(PG8_SB(0, 1), b2 + hstep);
;             PG8_WAIT_V(6); PG8_BAR; PG8_MMA(1, 1, At, B1); PG8_BAR;
;             PG8_LDB(B0, 1, 0); PG8_SCHED; PG8_LDA(At, 1, 0); PG8_STAGE(PG8_SA(0, 1), a2 + hstep);
;             PG8_WAIT_L(8); PG8_BAR; PG8_WAIT_L(0); PG8_MMA(0, 0, At, B0); PG8_BAR; PG8_SCHED;
;             PG8_LDB(B1, 1, 1); PG8_STAGE(PG8_SB(1, 0), b3);
;             PG8_BAR; PG8_WAIT_L(0); PG8_MMA(0, 1, At, B1); PG8_BAR;
;             PG8_LDA(At, 1, 1); PG8_STAGE(PG8_SA(1, 0), a3);
;             PG8_BAR; PG8_WAIT_L(0); PG8_MMA(1, 0, At, B0); PG8_BAR; PG8_SCHED;
	s_add_u32 s38, s18, 0x80000
	s_addc_u32 s39, s19, 0
	s_add_i32 s37, s40, s23
	s_mov_b32 m0, s37
	s_nop 0
	global_load_lds_dwordx4 v158, s[38:39]
	s_add_i32 m0, s37, 0x2000
	s_nop 0
	global_load_lds_dwordx4 v128, s[38:39]
	s_waitcnt vmcnt(6)
	s_setprio 1
	s_barrier
	v_mfma_f32_16x16x32_bf16 v[44:47], v[226:229], v[186:189], v[44:47]
	v_mfma_f32_16x16x32_bf16 v[40:43], v[234:237], v[186:189], v[40:43]
	v_mfma_f32_16x16x32_bf16 v[28:31], v[226:229], v[194:197], v[28:31]
	v_mfma_f32_16x16x32_bf16 v[24:27], v[234:237], v[194:197], v[24:27]
	v_mfma_f32_16x16x32_bf16 v[12:15], v[226:229], v[202:205], v[12:15]
	v_mfma_f32_16x16x32_bf16 v[8:11], v[234:237], v[202:205], v[8:11]
	v_mfma_f32_16x16x32_bf16 v[4:7], v[226:229], v[210:213], v[4:7]
	v_mfma_f32_16x16x32_bf16 v[0:3], v[234:237], v[210:213], v[0:3]
	v_mfma_f32_16x16x32_bf16 v[44:47], v[230:233], v[190:193], v[44:47]
	s_add_i32 s37, 0, 0x18000
	v_mfma_f32_16x16x32_bf16 v[40:43], v[238:241], v[190:193], v[40:43]
	v_mfma_f32_16x16x32_bf16 v[28:31], v[230:233], v[198:201], v[28:31]
	v_mfma_f32_16x16x32_bf16 v[24:27], v[238:241], v[198:201], v[24:27]
	v_mfma_f32_16x16x32_bf16 v[12:15], v[230:233], v[206:209], v[12:15]
	v_mfma_f32_16x16x32_bf16 v[8:11], v[238:241], v[206:209], v[8:11]
	v_mfma_f32_16x16x32_bf16 v[4:7], v[230:233], v[214:217], v[4:7]
	s_setprio 0
	v_mfma_f32_16x16x32_bf16 v[0:3], v[238:241], v[214:217], v[0:3]
	s_barrier
	ds_read_b128 v[138:141], v135 offset:32768
	ds_read_b128 v[142:145], v135 offset:33792
	ds_read_b128 v[146:149], v135 offset:34816
	ds_read_b128 v[150:153], v135 offset:35840
	s_add_u32 s20, s20, 0x80000
	s_addc_u32 s21, s21, 0
	s_mov_b32 m0, s26
	ds_read_b128 v[186:189], v137 offset:32768
	ds_read_b128 v[190:193], v137 offset:33792
	ds_read_b128 v[194:197], v137 offset:34816
	ds_read_b128 v[198:201], v137 offset:35840
	ds_read_b128 v[202:205], v137 offset:36864
	ds_read_b128 v[206:209], v137 offset:37888
	ds_read_b128 v[210:213], v137 offset:38912
	ds_read_b128 v[214:217], v137 offset:39936
	global_load_lds_dwordx4 v158, s[20:21]
	s_mov_b32 m0, s27
	s_nop 0
	global_load_lds_dwordx4 v128, s[20:21]
	s_waitcnt lgkmcnt(8)
	s_setprio 1
	s_barrier
	s_waitcnt lgkmcnt(0)
	v_mfma_f32_16x16x32_bf16 v[124:127], v[138:141], v[186:189], v[124:127]
	v_mfma_f32_16x16x32_bf16 v[120:123], v[146:149], v[186:189], v[120:123]
	v_mfma_f32_16x16x32_bf16 v[116:119], v[138:141], v[194:197], v[116:119]
	v_mfma_f32_16x16x32_bf16 v[112:115], v[146:149], v[194:197], v[112:115]
	v_mfma_f32_16x16x32_bf16 v[100:103], v[138:141], v[202:205], v[100:103]
	v_mfma_f32_16x16x32_bf16 v[96:99], v[146:149], v[202:205], v[96:99]
	v_mfma_f32_16x16x32_bf16 v[84:87], v[138:141], v[210:213], v[84:87]
	v_mfma_f32_16x16x32_bf16 v[80:83], v[146:149], v[210:213], v[80:83]
	v_mfma_f32_16x16x32_bf16 v[124:127], v[142:145], v[190:193], v[124:127]
	v_mfma_f32_16x16x32_bf16 v[120:123], v[150:153], v[190:193], v[120:123]
	v_mfma_f32_16x16x32_bf16 v[116:119], v[142:145], v[198:201], v[116:119]
	v_mfma_f32_16x16x32_bf16 v[112:115], v[150:153], v[198:201], v[112:115]
	v_mfma_f32_16x16x32_bf16 v[100:103], v[142:145], v[206:209], v[100:103]
	v_mfma_f32_16x16x32_bf16 v[96:99], v[150:153], v[206:209], v[96:99]
	v_mfma_f32_16x16x32_bf16 v[84:87], v[142:145], v[214:217], v[84:87]
	s_setprio 0
	v_mfma_f32_16x16x32_bf16 v[80:83], v[150:153], v[214:217], v[80:83]
	s_barrier
	s_add_i32 s20, 0, 0x1c000
	s_add_i32 s21, s37, s23
	s_add_i32 m0, s21, 0xffffff80
	ds_read_b128 v[226:229], v135 offset:49152
	ds_read_b128 v[230:233], v135 offset:50176
	ds_read_b128 v[234:237], v135 offset:51200
	ds_read_b128 v[238:241], v135 offset:52224
	global_load_lds_dwordx4 v[154:155], off offset:128
	s_add_i32 m0, s21, 0x1f80
	s_nop 0
	global_load_lds_dwordx4 v[218:219], off offset:128
	s_waitcnt lgkmcnt(0)
	s_setprio 1
	s_barrier
	v_mfma_f32_16x16x32_bf16 v[108:111], v[226:229], v[186:189], v[108:111]
	v_mfma_f32_16x16x32_bf16 v[104:107], v[234:237], v[186:189], v[104:107]
	v_mfma_f32_16x16x32_bf16 v[92:95], v[226:229], v[194:197], v[92:95]
	v_mfma_f32_16x16x32_bf16 v[88:91], v[234:237], v[194:197], v[88:91]
	v_mfma_f32_16x16x32_bf16 v[76:79], v[226:229], v[202:205], v[76:79]
	v_mfma_f32_16x16x32_bf16 v[72:75], v[234:237], v[202:205], v[72:75]
	v_mfma_f32_16x16x32_bf16 v[68:71], v[226:229], v[210:213], v[68:71]
	v_mfma_f32_16x16x32_bf16 v[64:67], v[234:237], v[210:213], v[64:67]
	v_mfma_f32_16x16x32_bf16 v[108:111], v[230:233], v[190:193], v[108:111]
	s_mov_b32 m0, s28
	v_mfma_f32_16x16x32_bf16 v[104:107], v[238:241], v[190:193], v[104:107]
	v_lshl_add_u64 v[154:155], v[242:243], 0, s[94:95]
	v_mfma_f32_16x16x32_bf16 v[92:95], v[230:233], v[198:201], v[92:95]
	v_mfma_f32_16x16x32_bf16 v[88:91], v[238:241], v[198:201], v[88:91]
	v_mfma_f32_16x16x32_bf16 v[76:79], v[230:233], v[206:209], v[76:79]
	v_mfma_f32_16x16x32_bf16 v[72:75], v[238:241], v[206:209], v[72:75]
	v_mfma_f32_16x16x32_bf16 v[68:71], v[230:233], v[214:217], v[68:71]
	s_setprio 0
	v_mfma_f32_16x16x32_bf16 v[64:67], v[238:241], v[214:217], v[64:67]
	s_barrier
	ds_read_b128 v[186:189], v137 offset:49152
	ds_read_b128 v[190:193], v137 offset:50176
	ds_read_b128 v[194:197], v137 offset:51200
	ds_read_b128 v[198:201], v137 offset:52224
	ds_read_b128 v[202:205], v137 offset:53248
	ds_read_b128 v[206:209], v137 offset:54272
	ds_read_b128 v[210:213], v137 offset:55296
	ds_read_b128 v[214:217], v137 offset:56320
	global_load_lds_dwordx4 v[154:155], off
	s_add_i32 m0, s29, 0xffffff80
	s_nop 0
	global_load_lds_dwordx4 v[244:245], off offset:128
	s_waitcnt lgkmcnt(0)
	s_setprio 1
	s_barrier
; #define PG8_STAGE(bufoff, gbase) do { _Pragma("unroll") for (int _i = 0; _i < 2; ++_i) \
;         __builtin_amdgcn_global_load_lds((const unsigned*)((const char*)(gbase) + voff[_i]), (LAS unsigned*)(lds + (bufoff) + ldsw + _i * 8192), 16, 0, 0); } while (0)
; #define PG8_MMA(ai, bj, At, Bt) do { __builtin_amdgcn_s_setprio(1); _Pragma("unroll") for (int m = 0; m < 4; ++m) _Pragma("unroll") for (int n = 0; n < 2; ++n) _Pragma("unroll") for (int k = 0; k < 2; ++k) \
;         acc[ai][bj][m][n] = __builtin_amdgcn_mfma_f32_16x16x32_bf16(Bt[n][k], At[m][k], acc[ai][bj][m][n], 0, 0, 0); __builtin_amdgcn_s_setprio(0); } while (0)
; #define PG8_WAIT_V(n) asm volatile("s_waitcnt vmcnt(" #n ")" ::: "memory")
; #define PG8_WAIT_L(n) asm volatile("s_waitcnt lgkmcnt(" #n ")" ::: "memory")
; #define PG8_BAR __builtin_amdgcn_s_barrier()
; #define PG8_SCHED __builtin_amdgcn_sched_barrier(0)
; template <class Epi>
; DI void gemm_phase(LAS unsigned char* lds, const Gemm g, const StaticOrder& S, const Epi& E) {
;     ...
;             PG8_BAR; PG8_WAIT_L(0); PG8_MMA(1, 0, At, B0); PG8_BAR; PG8_SCHED;
;             PG8_STAGE(PG8_SB(1, 1), b3 + hstep);
;             PG8_WAIT_V(6); PG8_BAR; PG8_MMA(1, 1, At, B1); PG8_BAR;
	v_mfma_f32_16x16x32_bf16 v[60:63], v[138:141], v[186:189], v[60:63]
	v_mfma_f32_16x16x32_bf16 v[56:59], v[146:149], v[186:189], v[56:59]
	v_mfma_f32_16x16x32_bf16 v[52:55], v[138:141], v[194:197], v[52:55]
	v_mfma_f32_16x16x32_bf16 v[48:51], v[146:149], v[194:197], v[48:51]
	v_mfma_f32_16x16x32_bf16 v[36:39], v[138:141], v[202:205], v[36:39]
	v_mfma_f32_16x16x32_bf16 v[32:35], v[146:149], v[202:205], v[32:35]
	v_mfma_f32_16x16x32_bf16 v[20:23], v[138:141], v[210:213], v[20:23]
	v_mfma_f32_16x16x32_bf16 v[16:19], v[146:149], v[210:213], v[16:19]
	v_mfma_f32_16x16x32_bf16 v[60:63], v[142:145], v[190:193], v[60:63]
	v_mfma_f32_16x16x32_bf16 v[56:59], v[150:153], v[190:193], v[56:59]
	v_mfma_f32_16x16x32_bf16 v[52:55], v[142:145], v[198:201], v[52:55]
	v_mfma_f32_16x16x32_bf16 v[48:51], v[150:153], v[198:201], v[48:51]
	v_mfma_f32_16x16x32_bf16 v[36:39], v[142:145], v[206:209], v[36:39]
	v_mfma_f32_16x16x32_bf16 v[32:35], v[150:153], v[206:209], v[32:35]
	v_mfma_f32_16x16x32_bf16 v[20:23], v[142:145], v[214:217], v[20:23]
	s_setprio 0
	v_mfma_f32_16x16x32_bf16 v[16:19], v[150:153], v[214:217], v[16:19]
	s_barrier
	s_add_u32 s18, s18, 0x80080
	s_addc_u32 s19, s19, 0
	s_add_i32 s20, s20, s23
	s_mov_b32 m0, s20
	s_nop 0
	global_load_lds_dwordx4 v158, s[18:19]
	s_add_i32 m0, s20, 0x2000
	s_nop 0
	global_load_lds_dwordx4 v128, s[18:19]
	s_waitcnt vmcnt(6)
	s_setprio 1
	s_barrier
	v_mfma_f32_16x16x32_bf16 v[44:47], v[226:229], v[186:189], v[44:47]
	v_mfma_f32_16x16x32_bf16 v[40:43], v[234:237], v[186:189], v[40:43]
	v_mfma_f32_16x16x32_bf16 v[28:31], v[226:229], v[194:197], v[28:31]
	v_mfma_f32_16x16x32_bf16 v[24:27], v[234:237], v[194:197], v[24:27]
	v_mfma_f32_16x16x32_bf16 v[12:15], v[226:229], v[202:205], v[12:15]
	v_mfma_f32_16x16x32_bf16 v[8:11], v[234:237], v[202:205], v[8:11]
	v_mfma_f32_16x16x32_bf16 v[4:7], v[226:229], v[210:213], v[4:7]
	v_mfma_f32_16x16x32_bf16 v[0:3], v[234:237], v[210:213], v[0:3]
	v_mfma_f32_16x16x32_bf16 v[44:47], v[230:233], v[190:193], v[44:47]
	s_add_i32 s36, s36, 2
	v_mfma_f32_16x16x32_bf16 v[40:43], v[238:241], v[190:193], v[40:43]
	s_add_u32 s16, s16, 0x100
	v_mfma_f32_16x16x32_bf16 v[28:31], v[230:233], v[198:201], v[28:31]
	s_addc_u32 s17, s17, 0
	v_mfma_f32_16x16x32_bf16 v[24:27], v[238:241], v[198:201], v[24:27]
	s_add_u32 s34, s34, 0x100
	v_mfma_f32_16x16x32_bf16 v[12:15], v[230:233], v[206:209], v[12:15]
	s_addc_u32 s35, s35, 0
	v_mfma_f32_16x16x32_bf16 v[8:11], v[238:241], v[206:209], v[8:11]
	s_cmp_gt_u32 s36, 29
	v_mfma_f32_16x16x32_bf16 v[4:7], v[230:233], v[214:217], v[4:7]
	s_setprio 0
	v_mfma_f32_16x16x32_bf16 v[0:3], v[238:241], v[214:217], v[0:3]
	s_barrier
	s_cbranch_scc0 .LBB0_231
; #define PG8_WAIT_V(n) asm volatile("s_waitcnt vmcnt(" #n ")" ::: "memory")
; #define PG8_BAR __builtin_amdgcn_s_barrier()
; template <class Epi>
; DI void gemm_phase(LAS unsigned char* lds, const Gemm g, const StaticOrder& S, const Epi& E) {
;     ...
;         E(acc, cur, wr, wc, fr, fq);
;         if (!has_next) break;
; #pragma unroll
;         for (int a = 0; a < 2; ++a)
; #pragma unroll
;             for (int b = 0; b < 2; ++b)
; #pragma unroll
;                 for (int m = 0; m < 4; ++m)
; #pragma unroll
;                     for (int n = 0; n < 2; ++n) acc[a][b][m][n] = (f32x4){0.f, 0.f, 0.f, 0.f};
;         cur = nxt; cA = nA; cB = nB; ++ui;
;     }
;     PG8_WAIT_V(0);
;     if (wr == 0) PG8_BAR;
;     DI void operator()(const f32x4 (&acc)[2][2][4][2], const Unit& u, int wr, int wc, int fr, int fq) const {
;         const int row0 = u.pm * BM + wr * 64 + fr, col0 = u.pn * BM + wc * 32 + 8 * fq;
; #pragma unroll
;         for (int ai = 0; ai < 2; ++ai)
; #pragma unroll
;             for (int m = 0; m < 4; ++m) { u16* rowp = O + (size_t)(row0 + ai * HALF + m * 16) * ldc + col0;
; #pragma unroll
;                 for (int bj = 0; bj < 2; ++bj) { const f32x4 v0 = acc[ai][bj][m][0], v1 = acc[ai][bj][m][1];
;                     *(u32x4*)(rowp + bj * HALF) = (u32x4){pk(v0[0], v0[1]), pk(v0[2], v0[3]), pk(v1[0], v1[1]), pk(v1[2], v1[3])}; } }
	v_lshl_add_u32 v144, s33, 8, v134
	v_lshl_or_b32 v138, s31, 8, v136
	v_ashrrev_i32_e32 v139, 31, v138
	v_mov_b64_e32 v[140:141], s[50:51]
	s_movk_i32 s9, 0x3000
	v_cvt_pk_bf16_f32 v68, v68, v69
	v_cvt_pk_bf16_f32 v69, v70, v71
	v_cvt_pk_bf16_f32 v70, v64, v65
	v_add_u32_e32 v64, 0x80, v144
	v_mad_i64_i32 v[142:143], s[4:5], v144, s9, v[140:141]
	v_lshlrev_b64 v[138:139], 1, v[138:139]
	v_cvt_pk_bf16_f32 v108, v108, v109
	v_cvt_pk_bf16_f32 v109, v110, v111
	v_cvt_pk_bf16_f32 v110, v104, v105
	v_or_b32_e32 v104, 16, v144
	v_mad_i64_i32 v[64:65], s[4:5], v64, s9, v[140:141]
	v_cvt_pk_bf16_f32 v44, v44, v45
	v_cvt_pk_bf16_f32 v45, v46, v47
	v_cvt_pk_bf16_f32 v46, v40, v41
	v_add_u32_e32 v40, 0x90, v144
	v_lshl_add_u64 v[142:143], v[142:143], 0, v[138:139]
	v_cvt_pk_bf16_f32 v111, v106, v107
	v_mad_i64_i32 v[104:105], s[4:5], v104, s9, v[140:141]
	v_cvt_pk_bf16_f32 v92, v92, v93
	v_cvt_pk_bf16_f32 v93, v94, v95
	v_cvt_pk_bf16_f32 v94, v88, v89
	v_or_b32_e32 v88, 32, v144
	v_lshl_add_u64 v[64:65], v[64:65], 0, v[138:139]
	v_cvt_pk_bf16_f32 v47, v42, v43
	v_mad_i64_i32 v[40:41], s[4:5], v40, s9, v[140:141]
	v_cvt_pk_bf16_f32 v28, v28, v29
	v_cvt_pk_bf16_f32 v29, v30, v31
	v_cvt_pk_bf16_f32 v30, v24, v25
	v_add_u32_e32 v24, 0xa0, v144
	global_store_dwordx4 v[142:143], v[108:111], off offset:256
	v_cvt_pk_bf16_f32 v95, v90, v91
	v_mad_i64_i32 v[88:89], s[4:5], v88, s9, v[140:141]
	v_lshl_add_u64 v[108:109], v[104:105], 0, v[138:139]
	v_cvt_pk_bf16_f32 v76, v76, v77
	v_cvt_pk_bf16_f32 v77, v78, v79
	v_cvt_pk_bf16_f32 v78, v72, v73
	v_or_b32_e32 v72, 48, v144
	global_store_dwordx4 v[64:65], v[44:47], off offset:256
	v_cvt_pk_bf16_f32 v31, v26, v27
	v_mad_i64_i32 v[24:25], s[4:5], v24, s9, v[140:141]
	v_lshl_add_u64 v[44:45], v[40:41], 0, v[138:139]
	v_cvt_pk_bf16_f32 v12, v12, v13
	v_cvt_pk_bf16_f32 v13, v14, v15
	v_cvt_pk_bf16_f32 v14, v8, v9
	v_add_u32_e32 v8, 0xb0, v144
	global_store_dwordx4 v[108:109], v[92:95], off offset:256
	v_cvt_pk_bf16_f32 v79, v74, v75
	v_mad_i64_i32 v[72:73], s[4:5], v72, s9, v[140:141]
	v_lshl_add_u64 v[92:93], v[88:89], 0, v[138:139]
	global_store_dwordx4 v[44:45], v[28:31], off offset:256
	v_cvt_pk_bf16_f32 v15, v10, v11
	v_mad_i64_i32 v[8:9], s[4:5], v8, s9, v[140:141]
	v_lshl_add_u64 v[28:29], v[24:25], 0, v[138:139]
	v_cvt_pk_bf16_f32 v124, v124, v125
	v_cvt_pk_bf16_f32 v125, v126, v127
	v_cvt_pk_bf16_f32 v126, v120, v121
	v_cvt_pk_bf16_f32 v127, v122, v123
	v_cvt_pk_bf16_f32 v104, v116, v117
	v_cvt_pk_bf16_f32 v105, v118, v119
	v_cvt_pk_bf16_f32 v106, v112, v113
	v_cvt_pk_bf16_f32 v107, v114, v115
	v_cvt_pk_bf16_f32 v88, v100, v101
	v_cvt_pk_bf16_f32 v89, v102, v103
	v_cvt_pk_bf16_f32 v90, v96, v97
	v_cvt_pk_bf16_f32 v91, v98, v99
	global_store_dwordx4 v[92:93], v[76:79], off offset:256
	v_cvt_pk_bf16_f32 v74, v80, v81
	v_cvt_pk_bf16_f32 v75, v82, v83
	v_lshl_add_u64 v[76:77], v[72:73], 0, v[138:139]
	v_cvt_pk_bf16_f32 v72, v84, v85
	v_cvt_pk_bf16_f32 v73, v86, v87
	v_cvt_pk_bf16_f32 v71, v66, v67
	v_cvt_pk_bf16_f32 v60, v60, v61
	v_cvt_pk_bf16_f32 v61, v62, v63
	v_cvt_pk_bf16_f32 v62, v56, v57
	v_cvt_pk_bf16_f32 v63, v58, v59
	v_cvt_pk_bf16_f32 v40, v52, v53
	v_cvt_pk_bf16_f32 v41, v54, v55
	v_cvt_pk_bf16_f32 v42, v48, v49
	v_cvt_pk_bf16_f32 v43, v50, v51
	v_cvt_pk_bf16_f32 v24, v36, v37
	v_cvt_pk_bf16_f32 v25, v38, v39
	v_cvt_pk_bf16_f32 v26, v32, v33
	v_cvt_pk_bf16_f32 v27, v34, v35
	global_store_dwordx4 v[28:29], v[12:15], off offset:256
	v_cvt_pk_bf16_f32 v10, v16, v17
	v_cvt_pk_bf16_f32 v11, v18, v19
	v_lshl_add_u64 v[12:13], v[8:9], 0, v[138:139]
	v_cvt_pk_bf16_f32 v8, v20, v21
	v_cvt_pk_bf16_f32 v9, v22, v23
	v_cvt_pk_bf16_f32 v4, v4, v5
	v_cvt_pk_bf16_f32 v5, v6, v7
	v_cvt_pk_bf16_f32 v6, v0, v1
	v_cvt_pk_bf16_f32 v7, v2, v3
	s_and_b64 vcc, exec, s[6:7]
	s_mov_b32 s31, s8
	s_mov_b32 s33, s10
	s_mov_b64 s[18:19], s[14:15]
	s_mov_b64 s[16:17], s[12:13]
	global_store_dwordx4 v[142:143], v[124:127], off
	global_store_dwordx4 v[108:109], v[104:107], off
	global_store_dwordx4 v[92:93], v[88:91], off
	global_store_dwordx4 v[76:77], v[72:75], off
	global_store_dwordx4 v[76:77], v[68:71], off offset:256
	global_store_dwordx4 v[64:65], v[60:63], off
	global_store_dwordx4 v[44:45], v[40:43], off
	global_store_dwordx4 v[28:29], v[24:27], off
	global_store_dwordx4 v[12:13], v[8:11], off
	global_store_dwordx4 v[12:13], v[4:7], off offset:256
	s_cbranch_vccz .LBB0_228
	s_waitcnt vmcnt(0)
	s_cmpk_gt_u32 s2, 0xff
	s_cbranch_scc1 .LBB0_235
	s_barrier

; #define PG8_STAGE(bufoff, gbase) do { _Pragma("unroll") for (int _i = 0; _i < 2; ++_i) \
;         __builtin_amdgcn_global_load_lds((const unsigned*)((const char*)(gbase) + voff[_i]), (LAS unsigned*)(lds + (bufoff) + ldsw + _i * 8192), 16, 0, 0); } while (0)
; #define PG8_LDA(dst, b, h) do { _Pragma("unroll") for (int m = 0; m < 4; ++m) _Pragma("unroll") for (int k = 0; k < 2; ++k) dst[m][k] = *(const LAS bf16x8*)(lds + PG8_SA(b, h) + aoff + m * 2048 + k * 1024); } while (0)
; #define PG8_LDB(dst, b, h) do { _Pragma("unroll") for (int n = 0; n < 2; ++n) _Pragma("unroll") for (int k = 0; k < 2; ++k) dst[n][k] = *(const LAS bf16x8*)(lds + PG8_SB(b, h) + boff + n * 2048 + k * 1024); } while (0)
; #define PG8_MMA(ai, bj, At, Bt) do { __builtin_amdgcn_s_setprio(1); _Pragma("unroll") for (int m = 0; m < 4; ++m) _Pragma("unroll") for (int n = 0; n < 2; ++n) _Pragma("unroll") for (int k = 0; k < 2; ++k) \
;         acc[ai][bj][m][n] = __builtin_amdgcn_mfma_f32_16x16x32_bf16(Bt[n][k], At[m][k], acc[ai][bj][m][n], 0, 0, 0); __builtin_amdgcn_s_setprio(0); } while (0)
; #define PG8_WAIT_L(n) asm volatile("s_waitcnt lgkmcnt(" #n ")" ::: "memory")
; #define PG8_BAR __builtin_amdgcn_s_barrier()
; #define PG8_SCHED __builtin_amdgcn_sched_barrier(0)
; template <class Epi>
; DI void gemm_phase(LAS unsigned char* lds, const Gemm g, const StaticOrder& S, const Epi& E) {
;     ...
;             PG8_LDB(B0, 0, 0); PG8_SCHED; PG8_LDA(At, 0, 0); PG8_STAGE(PG8_SA(1, 1), a1 + hstep);
;             PG8_WAIT_L(8); PG8_BAR; PG8_WAIT_L(0); PG8_MMA(0, 0, At, B0); PG8_BAR; PG8_SCHED;
;             PG8_LDB(B1, 0, 1); PG8_STAGE(PG8_SB(0, 0), b2);
;             PG8_BAR; PG8_WAIT_L(0); PG8_MMA(0, 1, At, B1); PG8_BAR;
;             PG8_LDA(At, 0, 1); PG8_STAGE(PG8_SA(0, 0), a2);
;             PG8_BAR; PG8_WAIT_L(0); PG8_MMA(1, 0, At, B0); PG8_BAR; PG8_SCHED;
.LBB0_320:
	s_add_u32 s26, s24, 0x100
	s_addc_u32 s27, s25, 0
	s_add_i32 s47, 0, 0x10000
	ds_read_b128 v[128:131], v226
	ds_read_b128 v[132:135], v226 offset:1024
	ds_read_b128 v[136:139], v226 offset:2048
	ds_read_b128 v[140:143], v226 offset:3072
	s_cmp_eq_u32 s46, 28
	s_cselect_b32 s31, s4, s27
	s_cselect_b32 s30, s5, s26
	s_cselect_b32 s29, s9, s45
	s_cselect_b32 s28, s11, s33
	v_lshl_add_u64 v[214:215], s[24:25], 0, v[190:191]
	s_add_i32 m0, s38, 0xc000
	ds_read_b128 v[144:147], v228
	ds_read_b128 v[148:151], v228 offset:1024
	ds_read_b128 v[152:155], v228 offset:2048
	ds_read_b128 v[194:197], v228 offset:3072
	ds_read_b128 v[198:201], v228 offset:4096
	ds_read_b128 v[202:205], v228 offset:5120
	ds_read_b128 v[206:209], v228 offset:6144
	ds_read_b128 v[210:213], v228 offset:7168
	global_load_lds_dwordx4 v[214:215], off
	v_lshl_add_u64 v[214:215], s[24:25], 0, v[192:193]
	s_add_i32 m0, s38, 0xe000
	s_nop 0
	global_load_lds_dwordx4 v[214:215], off
	s_waitcnt lgkmcnt(8)
	s_setprio 1
	s_barrier
	s_waitcnt lgkmcnt(0)
	v_mfma_f32_16x16x32_bf16 v[124:127], v[128:131], v[144:147], v[124:127]
	v_mfma_f32_16x16x32_bf16 v[120:123], v[136:139], v[144:147], v[120:123]
	v_mfma_f32_16x16x32_bf16 v[116:119], v[128:131], v[152:155], v[116:119]
	v_mfma_f32_16x16x32_bf16 v[112:115], v[136:139], v[152:155], v[112:115]
	v_mfma_f32_16x16x32_bf16 v[108:111], v[128:131], v[198:201], v[108:111]
	v_mfma_f32_16x16x32_bf16 v[104:107], v[136:139], v[198:201], v[104:107]
	v_mfma_f32_16x16x32_bf16 v[100:103], v[128:131], v[206:209], v[100:103]
	v_mfma_f32_16x16x32_bf16 v[96:99], v[136:139], v[206:209], v[96:99]
	v_mfma_f32_16x16x32_bf16 v[124:127], v[132:135], v[148:151], v[124:127]
	v_mfma_f32_16x16x32_bf16 v[120:123], v[140:143], v[148:151], v[120:123]
	v_mfma_f32_16x16x32_bf16 v[116:119], v[132:135], v[194:197], v[116:119]
	v_mfma_f32_16x16x32_bf16 v[112:115], v[140:143], v[194:197], v[112:115]
	v_mfma_f32_16x16x32_bf16 v[108:111], v[132:135], v[202:205], v[108:111]
	v_mfma_f32_16x16x32_bf16 v[104:107], v[140:143], v[202:205], v[104:107]
	v_mfma_f32_16x16x32_bf16 v[100:103], v[132:135], v[210:213], v[100:103]
	s_setprio 0
	v_mfma_f32_16x16x32_bf16 v[96:99], v[140:143], v[210:213], v[96:99]
	s_barrier
	s_add_i32 s48, 0, 0x14000
	s_add_i32 s24, s47, s37
	v_lshl_add_u64 v[218:219], s[28:29], 0, v[188:189]
	s_mov_b32 m0, s24
	ds_read_b128 v[214:217], v226 offset:16384
	ds_read_b128 v[230:233], v226 offset:17408
	ds_read_b128 v[234:237], v226 offset:18432
	ds_read_b128 v[238:241], v226 offset:19456
	global_load_lds_dwordx4 v[218:219], off
	v_lshl_add_u64 v[220:221], s[28:29], 0, v[186:187]
	s_add_i32 m0, s24, 0x2000
	s_nop 0
	global_load_lds_dwordx4 v[220:221], off
	s_waitcnt lgkmcnt(0)
	s_setprio 1
	s_barrier
	v_mfma_f32_16x16x32_bf16 v[60:63], v[214:217], v[144:147], v[60:63]
	v_mfma_f32_16x16x32_bf16 v[56:59], v[234:237], v[144:147], v[56:59]
	v_mfma_f32_16x16x32_bf16 v[52:55], v[214:217], v[152:155], v[52:55]
	v_mfma_f32_16x16x32_bf16 v[48:51], v[234:237], v[152:155], v[48:51]
	v_mfma_f32_16x16x32_bf16 v[44:47], v[214:217], v[198:201], v[44:47]
	v_mfma_f32_16x16x32_bf16 v[40:43], v[234:237], v[198:201], v[40:43]
	v_mfma_f32_16x16x32_bf16 v[36:39], v[214:217], v[206:209], v[36:39]
	v_mfma_f32_16x16x32_bf16 v[32:35], v[234:237], v[206:209], v[32:35]
	v_mfma_f32_16x16x32_bf16 v[60:63], v[230:233], v[148:151], v[60:63]
	s_mov_b32 m0, s38
	v_mfma_f32_16x16x32_bf16 v[56:59], v[238:241], v[148:151], v[56:59]
	v_lshl_add_u64 v[242:243], s[30:31], 0, v[188:189]
	v_mfma_f32_16x16x32_bf16 v[52:55], v[230:233], v[194:197], v[52:55]
	v_mfma_f32_16x16x32_bf16 v[48:51], v[238:241], v[194:197], v[48:51]
	v_mfma_f32_16x16x32_bf16 v[44:47], v[230:233], v[202:205], v[44:47]
	v_mfma_f32_16x16x32_bf16 v[40:43], v[238:241], v[202:205], v[40:43]
	v_mfma_f32_16x16x32_bf16 v[36:39], v[230:233], v[210:213], v[36:39]
	s_setprio 0
	v_mfma_f32_16x16x32_bf16 v[32:35], v[238:241], v[210:213], v[32:35]
	s_barrier
	ds_read_b128 v[144:147], v228 offset:16384
	ds_read_b128 v[148:151], v228 offset:17408
	ds_read_b128 v[152:155], v228 offset:18432
	ds_read_b128 v[194:197], v228 offset:19456
	ds_read_b128 v[198:201], v228 offset:20480
	ds_read_b128 v[202:205], v228 offset:21504
	ds_read_b128 v[206:209], v228 offset:22528
	ds_read_b128 v[210:213], v228 offset:23552
	global_load_lds_dwordx4 v[242:243], off
	v_lshl_add_u64 v[244:245], s[30:31], 0, v[186:187]
	s_mov_b32 m0, s39
	s_nop 0
	global_load_lds_dwordx4 v[244:245], off
	s_waitcnt lgkmcnt(0)
	s_setprio 1
	s_barrier
	v_mfma_f32_16x16x32_bf16 v[92:95], v[128:131], v[144:147], v[92:95]
	v_mfma_f32_16x16x32_bf16 v[88:91], v[136:139], v[144:147], v[88:91]
	v_mfma_f32_16x16x32_bf16 v[84:87], v[128:131], v[152:155], v[84:87]
	v_mfma_f32_16x16x32_bf16 v[80:83], v[136:139], v[152:155], v[80:83]
	v_mfma_f32_16x16x32_bf16 v[76:79], v[128:131], v[198:201], v[76:79]
	v_mfma_f32_16x16x32_bf16 v[72:75], v[136:139], v[198:201], v[72:75]
	v_mfma_f32_16x16x32_bf16 v[68:71], v[128:131], v[206:209], v[68:71]
	v_mfma_f32_16x16x32_bf16 v[64:67], v[136:139], v[206:209], v[64:67]
	v_mfma_f32_16x16x32_bf16 v[92:95], v[132:135], v[148:151], v[92:95]
	v_mfma_f32_16x16x32_bf16 v[88:91], v[140:143], v[148:151], v[88:91]
	v_mfma_f32_16x16x32_bf16 v[84:87], v[132:135], v[194:197], v[84:87]
	v_mfma_f32_16x16x32_bf16 v[80:83], v[140:143], v[194:197], v[80:83]
	v_mfma_f32_16x16x32_bf16 v[76:79], v[132:135], v[202:205], v[76:79]
	v_mfma_f32_16x16x32_bf16 v[72:75], v[140:143], v[202:205], v[72:75]
	v_mfma_f32_16x16x32_bf16 v[68:71], v[132:135], v[210:213], v[68:71]
	s_setprio 0
	v_mfma_f32_16x16x32_bf16 v[64:67], v[140:143], v[210:213], v[64:67]
	s_barrier
; #define PG8_STAGE(bufoff, gbase) do { _Pragma("unroll") for (int _i = 0; _i < 2; ++_i) \
;         __builtin_amdgcn_global_load_lds((const unsigned*)((const char*)(gbase) + voff[_i]), (LAS unsigned*)(lds + (bufoff) + ldsw + _i * 8192), 16, 0, 0); } while (0)
; #define PG8_LDA(dst, b, h) do { _Pragma("unroll") for (int m = 0; m < 4; ++m) _Pragma("unroll") for (int k = 0; k < 2; ++k) dst[m][k] = *(const LAS bf16x8*)(lds + PG8_SA(b, h) + aoff + m * 2048 + k * 1024); } while (0)
; #define PG8_LDB(dst, b, h) do { _Pragma("unroll") for (int n = 0; n < 2; ++n) _Pragma("unroll") for (int k = 0; k < 2; ++k) dst[n][k] = *(const LAS bf16x8*)(lds + PG8_SB(b, h) + boff + n * 2048 + k * 1024); } while (0)
; #define PG8_MMA(ai, bj, At, Bt) do { __builtin_amdgcn_s_setprio(1); _Pragma("unroll") for (int m = 0; m < 4; ++m) _Pragma("unroll") for (int n = 0; n < 2; ++n) _Pragma("unroll") for (int k = 0; k < 2; ++k) \
;         acc[ai][bj][m][n] = __builtin_amdgcn_mfma_f32_16x16x32_bf16(Bt[n][k], At[m][k], acc[ai][bj][m][n], 0, 0, 0); __builtin_amdgcn_s_setprio(0); } while (0)
; #define PG8_WAIT_V(n) asm volatile("s_waitcnt vmcnt(" #n ")" ::: "memory")
; #define PG8_WAIT_L(n) asm volatile("s_waitcnt lgkmcnt(" #n ")" ::: "memory")
; #define PG8_BAR __builtin_amdgcn_s_barrier()
; #define PG8_SCHED __builtin_amdgcn_sched_barrier(0)
; template <class Epi>
; DI void gemm_phase(LAS unsigned char* lds, const Gemm g, const StaticOrder& S, const Epi& E) {
;     ...
;             PG8_STAGE(PG8_SB(0, 1), b2 + hstep);
;             PG8_WAIT_V(6); PG8_BAR; PG8_MMA(1, 1, At, B1); PG8_BAR;
;             PG8_LDB(B0, 1, 0); PG8_SCHED; PG8_LDA(At, 1, 0); PG8_STAGE(PG8_SA(0, 1), a2 + hstep);
;             PG8_WAIT_L(8); PG8_BAR; PG8_WAIT_L(0); PG8_MMA(0, 0, At, B0); PG8_BAR; PG8_SCHED;
;             PG8_LDB(B1, 1, 1); PG8_STAGE(PG8_SB(1, 0), b3);
;             PG8_BAR; PG8_WAIT_L(0); PG8_MMA(0, 1, At, B1); PG8_BAR;
;             PG8_LDA(At, 1, 1); PG8_STAGE(PG8_SA(1, 0), a3);
;             PG8_BAR; PG8_WAIT_L(0); PG8_MMA(1, 0, At, B0); PG8_BAR; PG8_SCHED;
	s_add_u32 s24, s28, 0x80000
	s_addc_u32 s25, s29, 0
	s_add_i32 s47, s48, s37
	s_mov_b32 m0, s47
	s_nop 0
	global_load_lds_dwordx4 v188, s[24:25]
	s_add_i32 m0, s47, 0x2000
	s_nop 0
	global_load_lds_dwordx4 v186, s[24:25]
	s_waitcnt vmcnt(6)
	s_setprio 1
	s_barrier
	v_mfma_f32_16x16x32_bf16 v[28:31], v[214:217], v[144:147], v[28:31]
	v_mfma_f32_16x16x32_bf16 v[24:27], v[234:237], v[144:147], v[24:27]
	v_mfma_f32_16x16x32_bf16 v[20:23], v[214:217], v[152:155], v[20:23]
	v_mfma_f32_16x16x32_bf16 v[16:19], v[234:237], v[152:155], v[16:19]
	v_mfma_f32_16x16x32_bf16 v[12:15], v[214:217], v[198:201], v[12:15]
	v_mfma_f32_16x16x32_bf16 v[8:11], v[234:237], v[198:201], v[8:11]
	v_mfma_f32_16x16x32_bf16 v[4:7], v[214:217], v[206:209], v[4:7]
	v_mfma_f32_16x16x32_bf16 v[0:3], v[234:237], v[206:209], v[0:3]
	v_mfma_f32_16x16x32_bf16 v[28:31], v[230:233], v[148:151], v[28:31]
	s_add_i32 s47, 0, 0x18000
	v_mfma_f32_16x16x32_bf16 v[24:27], v[238:241], v[148:151], v[24:27]
	v_mfma_f32_16x16x32_bf16 v[20:23], v[230:233], v[194:197], v[20:23]
	v_mfma_f32_16x16x32_bf16 v[16:19], v[238:241], v[194:197], v[16:19]
	v_mfma_f32_16x16x32_bf16 v[12:15], v[230:233], v[202:205], v[12:15]
	v_mfma_f32_16x16x32_bf16 v[8:11], v[238:241], v[202:205], v[8:11]
	v_mfma_f32_16x16x32_bf16 v[4:7], v[230:233], v[210:213], v[4:7]
	s_setprio 0
	v_mfma_f32_16x16x32_bf16 v[0:3], v[238:241], v[210:213], v[0:3]
	s_barrier
	ds_read_b128 v[128:131], v226 offset:32768
	ds_read_b128 v[132:135], v226 offset:33792
	ds_read_b128 v[136:139], v226 offset:34816
	ds_read_b128 v[140:143], v226 offset:35840
	s_add_u32 s24, s30, 0x80000
	s_addc_u32 s25, s31, 0
	s_mov_b32 m0, s40
	ds_read_b128 v[144:147], v228 offset:32768
	ds_read_b128 v[148:151], v228 offset:33792
	ds_read_b128 v[152:155], v228 offset:34816
	ds_read_b128 v[194:197], v228 offset:35840
	ds_read_b128 v[198:201], v228 offset:36864
	ds_read_b128 v[202:205], v228 offset:37888
	ds_read_b128 v[206:209], v228 offset:38912
	ds_read_b128 v[210:213], v228 offset:39936
	global_load_lds_dwordx4 v188, s[24:25]
	s_mov_b32 m0, s41
	s_nop 0
	global_load_lds_dwordx4 v186, s[24:25]
	s_waitcnt lgkmcnt(8)
	s_setprio 1
	s_barrier
	s_waitcnt lgkmcnt(0)
	v_mfma_f32_16x16x32_bf16 v[124:127], v[128:131], v[144:147], v[124:127]
	v_mfma_f32_16x16x32_bf16 v[120:123], v[136:139], v[144:147], v[120:123]
	v_mfma_f32_16x16x32_bf16 v[116:119], v[128:131], v[152:155], v[116:119]
	v_mfma_f32_16x16x32_bf16 v[112:115], v[136:139], v[152:155], v[112:115]
	v_mfma_f32_16x16x32_bf16 v[108:111], v[128:131], v[198:201], v[108:111]
	v_mfma_f32_16x16x32_bf16 v[104:107], v[136:139], v[198:201], v[104:107]
	v_mfma_f32_16x16x32_bf16 v[100:103], v[128:131], v[206:209], v[100:103]
	v_mfma_f32_16x16x32_bf16 v[96:99], v[136:139], v[206:209], v[96:99]
	v_mfma_f32_16x16x32_bf16 v[124:127], v[132:135], v[148:151], v[124:127]
	v_mfma_f32_16x16x32_bf16 v[120:123], v[140:143], v[148:151], v[120:123]
	v_mfma_f32_16x16x32_bf16 v[116:119], v[132:135], v[194:197], v[116:119]
	v_mfma_f32_16x16x32_bf16 v[112:115], v[140:143], v[194:197], v[112:115]
	v_mfma_f32_16x16x32_bf16 v[108:111], v[132:135], v[202:205], v[108:111]
	v_mfma_f32_16x16x32_bf16 v[104:107], v[140:143], v[202:205], v[104:107]
	v_mfma_f32_16x16x32_bf16 v[100:103], v[132:135], v[210:213], v[100:103]
	s_setprio 0
	v_mfma_f32_16x16x32_bf16 v[96:99], v[140:143], v[210:213], v[96:99]
	s_barrier
	s_add_i32 s30, 0, 0x1c000
	s_add_i32 s24, s47, s37
	s_add_i32 m0, s24, 0xffffff80
	ds_read_b128 v[214:217], v226 offset:49152
	ds_read_b128 v[230:233], v226 offset:50176
	ds_read_b128 v[234:237], v226 offset:51200
	ds_read_b128 v[238:241], v226 offset:52224
	global_load_lds_dwordx4 v[218:219], off offset:128
	s_add_i32 m0, s24, 0x1f80
	s_nop 0
	global_load_lds_dwordx4 v[220:221], off offset:128
	s_waitcnt lgkmcnt(0)
	s_setprio 1
	s_barrier
	v_mfma_f32_16x16x32_bf16 v[60:63], v[214:217], v[144:147], v[60:63]
	v_mfma_f32_16x16x32_bf16 v[56:59], v[234:237], v[144:147], v[56:59]
	v_mfma_f32_16x16x32_bf16 v[52:55], v[214:217], v[152:155], v[52:55]
	v_mfma_f32_16x16x32_bf16 v[48:51], v[234:237], v[152:155], v[48:51]
	v_mfma_f32_16x16x32_bf16 v[44:47], v[214:217], v[198:201], v[44:47]
	v_mfma_f32_16x16x32_bf16 v[40:43], v[234:237], v[198:201], v[40:43]
	v_mfma_f32_16x16x32_bf16 v[36:39], v[214:217], v[206:209], v[36:39]
	v_mfma_f32_16x16x32_bf16 v[32:35], v[234:237], v[206:209], v[32:35]
	v_mfma_f32_16x16x32_bf16 v[60:63], v[230:233], v[148:151], v[60:63]
	s_mov_b32 m0, s42
	v_mfma_f32_16x16x32_bf16 v[56:59], v[238:241], v[148:151], v[56:59]
	v_lshl_add_u64 v[218:219], v[242:243], 0, s[94:95]
	v_mfma_f32_16x16x32_bf16 v[52:55], v[230:233], v[194:197], v[52:55]
	v_mfma_f32_16x16x32_bf16 v[48:51], v[238:241], v[194:197], v[48:51]
	v_mfma_f32_16x16x32_bf16 v[44:47], v[230:233], v[202:205], v[44:47]
	v_mfma_f32_16x16x32_bf16 v[40:43], v[238:241], v[202:205], v[40:43]
	v_mfma_f32_16x16x32_bf16 v[36:39], v[230:233], v[210:213], v[36:39]
	s_setprio 0
	v_mfma_f32_16x16x32_bf16 v[32:35], v[238:241], v[210:213], v[32:35]
	s_barrier
	ds_read_b128 v[144:147], v228 offset:49152
	ds_read_b128 v[148:151], v228 offset:50176
	ds_read_b128 v[152:155], v228 offset:51200
	ds_read_b128 v[194:197], v228 offset:52224
	ds_read_b128 v[198:201], v228 offset:53248
	ds_read_b128 v[202:205], v228 offset:54272
	ds_read_b128 v[206:209], v228 offset:55296
	ds_read_b128 v[210:213], v228 offset:56320
	global_load_lds_dwordx4 v[218:219], off
	s_add_i32 m0, s43, 0xffffff80
	s_nop 0
	global_load_lds_dwordx4 v[244:245], off offset:128
	s_waitcnt lgkmcnt(0)
	s_setprio 1
	s_barrier
; #define PG8_STAGE(bufoff, gbase) do { _Pragma("unroll") for (int _i = 0; _i < 2; ++_i) \
;         __builtin_amdgcn_global_load_lds((const unsigned*)((const char*)(gbase) + voff[_i]), (LAS unsigned*)(lds + (bufoff) + ldsw + _i * 8192), 16, 0, 0); } while (0)
; #define PG8_MMA(ai, bj, At, Bt) do { __builtin_amdgcn_s_setprio(1); _Pragma("unroll") for (int m = 0; m < 4; ++m) _Pragma("unroll") for (int n = 0; n < 2; ++n) _Pragma("unroll") for (int k = 0; k < 2; ++k) \
;         acc[ai][bj][m][n] = __builtin_amdgcn_mfma_f32_16x16x32_bf16(Bt[n][k], At[m][k], acc[ai][bj][m][n], 0, 0, 0); __builtin_amdgcn_s_setprio(0); } while (0)
; #define PG8_WAIT_V(n) asm volatile("s_waitcnt vmcnt(" #n ")" ::: "memory")
; #define PG8_WAIT_L(n) asm volatile("s_waitcnt lgkmcnt(" #n ")" ::: "memory")
; #define PG8_BAR __builtin_amdgcn_s_barrier()
; #define PG8_SCHED __builtin_amdgcn_sched_barrier(0)
; template <class Epi>
; DI void gemm_phase(LAS unsigned char* lds, const Gemm g, const StaticOrder& S, const Epi& E) {
;     ...
;             PG8_BAR; PG8_WAIT_L(0); PG8_MMA(1, 0, At, B0); PG8_BAR; PG8_SCHED;
;             PG8_STAGE(PG8_SB(1, 1), b3 + hstep);
;             PG8_WAIT_V(6); PG8_BAR; PG8_MMA(1, 1, At, B1); PG8_BAR;
;     template <bool LN, int BJ> DI void load_gb(unsigned col0, f32x4 (&gv)[2], f32x4 (&bv)[2]) const {
; #pragma unroll
;         for (int n = 0; n < 2; ++n) {
;             if (LN) { gv[n] = *(const f32x4*)(gam + col0 + BJ * HALF + n * 16) * ALPHA; bv[n] = *(const f32x4*)(bet + col0 + BJ * HALF + n * 16) * ALPHA; }
;             else { gv[n] = (f32x4){ALPHA, ALPHA, ALPHA, ALPHA}; bv[n] = (f32x4){0.f, 0.f, 0.f, 0.f}; }
;         }
;     }
;     template <bool LN> DI void run(const f32x4 (&acc)[2][2][4][2], const Unit& u, int wr, int wc, int fr, int fq) const {
;         const unsigned row0 = u.pm * BM + wr * 64 + fr, col0 = u.pn * BM + wc * 32 + 4 * fq;
;         f32x4 gv[2], bv[2];
;         load_gb<LN, 0>(col0, gv, bv);
;         batch<LN, 0, 0, 4>(acc, row0, col0, gv, bv);
	v_mfma_f32_16x16x32_bf16 v[92:95], v[128:131], v[144:147], v[92:95]
	v_mfma_f32_16x16x32_bf16 v[88:91], v[136:139], v[144:147], v[88:91]
	v_mfma_f32_16x16x32_bf16 v[84:87], v[128:131], v[152:155], v[84:87]
	v_mfma_f32_16x16x32_bf16 v[80:83], v[136:139], v[152:155], v[80:83]
	v_mfma_f32_16x16x32_bf16 v[76:79], v[128:131], v[198:201], v[76:79]
	v_mfma_f32_16x16x32_bf16 v[72:75], v[136:139], v[198:201], v[72:75]
	v_mfma_f32_16x16x32_bf16 v[68:71], v[128:131], v[206:209], v[68:71]
	v_mfma_f32_16x16x32_bf16 v[64:67], v[136:139], v[206:209], v[64:67]
	v_mfma_f32_16x16x32_bf16 v[92:95], v[132:135], v[148:151], v[92:95]
	v_mfma_f32_16x16x32_bf16 v[88:91], v[140:143], v[148:151], v[88:91]
	v_mfma_f32_16x16x32_bf16 v[84:87], v[132:135], v[194:197], v[84:87]
	v_mfma_f32_16x16x32_bf16 v[80:83], v[140:143], v[194:197], v[80:83]
	v_mfma_f32_16x16x32_bf16 v[76:79], v[132:135], v[202:205], v[76:79]
	v_mfma_f32_16x16x32_bf16 v[72:75], v[140:143], v[202:205], v[72:75]
	v_mfma_f32_16x16x32_bf16 v[68:71], v[132:135], v[210:213], v[68:71]
	s_setprio 0
	v_mfma_f32_16x16x32_bf16 v[64:67], v[140:143], v[210:213], v[64:67]
	s_barrier
	s_add_u32 s24, s28, 0x80080
	s_addc_u32 s25, s29, 0
	s_add_i32 s28, s30, s37
	s_mov_b32 m0, s28
	s_nop 0
	global_load_lds_dwordx4 v188, s[24:25]
	s_add_i32 m0, s28, 0x2000
	s_nop 0
	global_load_lds_dwordx4 v186, s[24:25]
	s_waitcnt vmcnt(6)
	s_setprio 1
	s_barrier
	v_mfma_f32_16x16x32_bf16 v[28:31], v[214:217], v[144:147], v[28:31]
	v_mfma_f32_16x16x32_bf16 v[24:27], v[234:237], v[144:147], v[24:27]
	v_mfma_f32_16x16x32_bf16 v[20:23], v[214:217], v[152:155], v[20:23]
	v_mfma_f32_16x16x32_bf16 v[16:19], v[234:237], v[152:155], v[16:19]
	v_mfma_f32_16x16x32_bf16 v[12:15], v[214:217], v[198:201], v[12:15]
	v_mfma_f32_16x16x32_bf16 v[8:11], v[234:237], v[198:201], v[8:11]
	v_mfma_f32_16x16x32_bf16 v[4:7], v[214:217], v[206:209], v[4:7]
	v_mfma_f32_16x16x32_bf16 v[0:3], v[234:237], v[206:209], v[0:3]
	v_mfma_f32_16x16x32_bf16 v[28:31], v[230:233], v[148:151], v[28:31]
	s_add_i32 s46, s46, 2
	v_mfma_f32_16x16x32_bf16 v[24:27], v[238:241], v[148:151], v[24:27]
	s_add_u32 s33, s33, 0x100
	v_mfma_f32_16x16x32_bf16 v[20:23], v[230:233], v[194:197], v[20:23]
	s_addc_u32 s45, s45, 0
	v_mfma_f32_16x16x32_bf16 v[16:19], v[238:241], v[194:197], v[16:19]
	s_cmp_gt_u32 s46, 29
	v_mfma_f32_16x16x32_bf16 v[12:15], v[230:233], v[202:205], v[12:15]
	s_mov_b64 s[24:25], s[26:27]
	v_mfma_f32_16x16x32_bf16 v[8:11], v[238:241], v[202:205], v[8:11]
	v_mfma_f32_16x16x32_bf16 v[4:7], v[230:233], v[210:213], v[4:7]
	s_setprio 0
	v_mfma_f32_16x16x32_bf16 v[0:3], v[238:241], v[210:213], v[0:3]
	s_barrier
	s_cbranch_scc0 .LBB0_320
	v_lshl_add_u32 v206, s3, 8, v225
	v_lshl_or_b32 v158, s2, 8, v227
	v_lshlrev_b32_e32 v232, 11, v206
	s_andn2_b64 vcc, exec, s[14:15]
	v_or_b32_e32 v231, 16, v158
	v_add_u32_e32 v194, v232, v158
	v_or_b32_e32 v230, 0x80, v158
	v_or_b32_e32 v229, 0x90, v158
	s_cbranch_vccnz .LBB0_323
	v_lshlrev_b64 v[132:133], 2, v[158:159]
	v_lshl_add_u64 v[140:141], s[16:17], 0, v[132:133]
	global_load_dwordx4 v[128:131], v[140:141], off
	v_lshl_add_u64 v[142:143], s[18:19], 0, v[132:133]
	v_readlane_b32 s2, v253, 8
	v_mov_b32_e32 v195, v159
	v_lshlrev_b32_e32 v136, 1, v206
	v_mov_b32_e32 v137, v159
	v_readlane_b32 s3, v253, 9
	v_lshlrev_b64 v[212:213], 2, v[194:195]
	v_add_u32_e32 v146, v232, v231
	v_lshl_add_u64 v[144:145], v[136:137], 2, s[2:3]
	v_lshl_add_u64 v[136:137], s[88:89], 0, v[212:213]
	v_mov_b32_e32 v147, v159
	v_lshl_add_u64 v[146:147], v[146:147], 2, s[88:89]
	v_or_b32_e32 v195, 16, v206
	v_mov_b32_e32 v201, v159
	v_mov_b32_e32 v209, v159
	v_lshl_add_u64 v[212:213], s[90:91], 0, v[212:213]
	s_waitcnt vmcnt(0)
	v_pk_mul_f32 v[152:153], v[130:131], s[78:79] op_sel_hi:[1,0]
	v_pk_mul_f32 v[154:155], v[128:129], s[78:79] op_sel_hi:[1,0]
	global_load_dwordx4 v[132:135], v[142:143], off
	global_load_dwordx4 v[128:131], v[140:141], off offset:64
	global_load_dwordx2 v[204:205], v[144:145], off
	global_load_dwordx4 v[196:199], v[146:147], off
	v_lshlrev_b32_e32 v146, 1, v195
	global_load_dwordx4 v[136:139], v[136:137], off
	v_lshlrev_b32_e32 v195, 11, v195
	v_mov_b32_e32 v147, v159
	v_add_u32_e32 v200, v195, v158
	v_lshl_add_u64 v[146:147], v[146:147], 2, s[2:3]
	v_lshl_add_u64 v[200:201], v[200:201], 2, s[88:89]
	global_load_dwordx2 v[214:215], v[146:147], off
	v_add_u32_e32 v208, v195, v231
	global_load_dwordx4 v[200:203], v[200:201], off
	v_lshl_add_u64 v[208:209], v[208:209], 2, s[88:89]
	global_load_dwordx4 v[208:211], v[208:209], off
	s_waitcnt vmcnt(0)
	v_pk_mul_f32 v[148:149], v[130:131], s[78:79] op_sel_hi:[1,0]
	v_pk_mul_f32 v[150:151], v[128:129], s[78:79] op_sel_hi:[1,0]
	global_load_dwordx4 v[128:131], v[142:143], off offset:64
	v_sub_f32_e32 v137, v137, v204
	v_sub_f32_e32 v136, v136, v204
	v_sub_f32_e32 v139, v139, v204
	v_sub_f32_e32 v138, v138, v204
	v_pk_mul_f32 v[138:139], v[204:205], v[138:139] op_sel:[1,0]
	v_pk_mul_f32 v[136:137], v[204:205], v[136:137] op_sel:[1,0]
	v_pk_fma_f32 v[138:139], v[152:153], v[138:139], v[126:127]
	v_pk_fma_f32 v[136:137], v[154:155], v[136:137], v[124:125]
	v_pk_fma_f32 v[138:139], v[134:135], s[78:79], v[138:139] op_sel_hi:[1,0,1]
	v_pk_fma_f32 v[136:137], v[132:133], s[78:79], v[136:137] op_sel_hi:[1,0,1]
	global_store_dwordx4 v[212:213], v[136:139], off
	s_nop 1
	v_sub_f32_e32 v137, v197, v204
	v_sub_f32_e32 v136, v196, v204
	v_sub_f32_e32 v139, v199, v204
	v_sub_f32_e32 v138, v198, v204
	v_pk_mul_f32 v[138:139], v[204:205], v[138:139] op_sel:[1,0]
	v_pk_mul_f32 v[136:137], v[204:205], v[136:137] op_sel:[1,0]
	v_pk_fma_f32 v[138:139], v[148:149], v[138:139], v[122:123]
	v_pk_fma_f32 v[136:137], v[150:151], v[136:137], v[120:121]
	v_or_b32_e32 v196, 16, v194
	v_mov_b32_e32 v197, v159
	v_lshl_add_u64 v[196:197], v[196:197], 2, s[90:91]
	s_waitcnt vmcnt(0)
;     template <bool LN, int BJ, int LO, int HI> DI void batch(const f32x4 (&acc)[2][2][4][2], unsigned row0, unsigned col0, const f32x4 (&gv)[2], const f32x4 (&bv)[2]) const {
;         f32x4 r[HI - LO]; float mean[(HI - LO) / 2], rstd[(HI - LO) / 2];
; #pragma unroll
;         for (int i = LO; i < HI; ++i) { const int ai = i >> 3, m = (i >> 1) & 3, n = i & 1; const unsigned row = row0 + ai * HALF + m * 16;
;             if (n == 0) { mean[(i - LO) >> 1] = 0.f; rstd[(i - LO) >> 1] = 1.f;
;                 if (LN) { const float2 st = *(const float2*)(stats + row * 2u); mean[(i - LO) >> 1] = st.x; rstd[(i - LO) >> 1] = st.y; } }
;             r[i - LO] = *(const f32x4*)(src + (row * (unsigned)DM + col0 + BJ * HALF + n * 16)); }
; #pragma unroll
;         for (int i = LO; i < HI; ++i) { const int ai = i >> 3, m = (i >> 1) & 3, n = i & 1; const unsigned row = row0 + ai * HALF + m * 16;
;             *(f32x4*)(Y + (row * (unsigned)DM + col0 + BJ * HALF + n * 16)) = acc[ai][BJ][m][n] + ((r[i - LO] - mean[(i - LO) >> 1]) * rstd[(i - LO) >> 1]) * gv[n] + bv[n]; }
	v_pk_fma_f32 v[138:139], v[130:131], s[78:79], v[138:139] op_sel_hi:[1,0,1]
	v_pk_fma_f32 v[136:137], v[128:129], s[78:79], v[136:137] op_sel_hi:[1,0,1]
	global_store_dwordx4 v[196:197], v[136:139], off
	v_add_u32_e32 v196, 0x8000, v194
	v_mov_b32_e32 v197, v159
	v_sub_f32_e32 v137, v201, v214
	v_sub_f32_e32 v136, v200, v214
	v_sub_f32_e32 v139, v203, v214
	v_sub_f32_e32 v138, v202, v214
	v_pk_mul_f32 v[138:139], v[214:215], v[138:139] op_sel:[1,0]
	v_pk_mul_f32 v[136:137], v[214:215], v[136:137] op_sel:[1,0]
	v_pk_fma_f32 v[138:139], v[152:153], v[138:139], v[118:119]
	v_pk_fma_f32 v[136:137], v[154:155], v[136:137], v[116:117]
	v_pk_fma_f32 v[138:139], v[134:135], s[78:79], v[138:139] op_sel_hi:[1,0,1]
	v_pk_fma_f32 v[136:137], v[132:133], s[78:79], v[136:137] op_sel_hi:[1,0,1]
	v_lshl_add_u64 v[196:197], v[196:197], 2, s[90:91]
	global_store_dwordx4 v[196:197], v[136:139], off
	v_add_u32_e32 v196, 0x8010, v194
	v_mov_b32_e32 v197, v159
	v_sub_f32_e32 v137, v209, v214
	v_sub_f32_e32 v136, v208, v214
	v_sub_f32_e32 v139, v211, v214
	v_sub_f32_e32 v138, v210, v214
	v_pk_mul_f32 v[138:139], v[214:215], v[138:139] op_sel:[1,0]
	v_pk_mul_f32 v[136:137], v[214:215], v[136:137] op_sel:[1,0]
	v_pk_fma_f32 v[138:139], v[148:149], v[138:139], v[114:115]
	v_pk_fma_f32 v[136:137], v[150:151], v[136:137], v[112:113]
	v_pk_fma_f32 v[138:139], v[130:131], s[78:79], v[138:139] op_sel_hi:[1,0,1]
	v_pk_fma_f32 v[136:137], v[128:129], s[78:79], v[136:137] op_sel_hi:[1,0,1]
	v_lshl_add_u64 v[196:197], v[196:197], 2, s[90:91]
	global_store_dwordx4 v[196:197], v[136:139], off
	s_nop 1
	v_or_b32_e32 v138, 32, v206
	v_lshlrev_b32_e32 v136, 1, v138
	v_mov_b32_e32 v137, v159
	v_lshlrev_b32_e32 v236, 11, v138
	v_lshl_add_u64 v[200:201], v[136:137], 2, s[2:3]
	v_add_u32_e32 v136, v236, v158
	v_lshl_add_u64 v[136:137], v[136:137], 2, s[88:89]
	global_load_dwordx2 v[204:205], v[200:201], off
	v_add_u32_e32 v196, v236, v231
	global_load_dwordx4 v[136:139], v[136:137], off
	v_mov_b32_e32 v197, v159
	v_lshl_add_u64 v[196:197], v[196:197], 2, s[88:89]
	global_load_dwordx4 v[196:199], v[196:197], off
	v_or_b32_e32 v207, 48, v206
	v_lshlrev_b32_e32 v235, 11, v207
	v_lshlrev_b32_e32 v202, 1, v207
	v_mov_b32_e32 v203, v159
	v_add_u32_e32 v208, v235, v158
	v_mov_b32_e32 v209, v159
	v_lshl_add_u64 v[202:203], v[202:203], 2, s[2:3]
	v_lshl_add_u64 v[208:209], v[208:209], 2, s[88:89]
	global_load_dwordx2 v[216:217], v[202:203], off
	v_add_u32_e32 v212, v235, v231
	global_load_dwordx4 v[208:211], v[208:209], off
	v_mov_b32_e32 v213, v159
	v_lshl_add_u64 v[212:213], v[212:213], 2, s[88:89]
	global_load_dwordx4 v[212:215], v[212:213], off
	v_add_u32_e32 v218, 0x10000, v194
	v_mov_b32_e32 v219, v159
	v_lshl_add_u64 v[218:219], v[218:219], 2, s[90:91]
	s_waitcnt vmcnt(0)
	v_sub_f32_e32 v137, v137, v204
	v_sub_f32_e32 v136, v136, v204
	v_sub_f32_e32 v139, v139, v204
	v_sub_f32_e32 v138, v138, v204
	v_pk_mul_f32 v[138:139], v[204:205], v[138:139] op_sel:[1,0]
	v_pk_mul_f32 v[136:137], v[204:205], v[136:137] op_sel:[1,0]
	v_pk_fma_f32 v[138:139], v[152:153], v[138:139], v[110:111]
	v_pk_fma_f32 v[136:137], v[154:155], v[136:137], v[108:109]
	v_pk_fma_f32 v[138:139], v[134:135], s[78:79], v[138:139] op_sel_hi:[1,0,1]
	v_pk_fma_f32 v[136:137], v[132:133], s[78:79], v[136:137] op_sel_hi:[1,0,1]
	global_store_dwordx4 v[218:219], v[136:139], off
	s_nop 1
	v_sub_f32_e32 v137, v197, v204
	v_sub_f32_e32 v136, v196, v204
	v_sub_f32_e32 v139, v199, v204
	v_sub_f32_e32 v138, v198, v204
	v_pk_mul_f32 v[138:139], v[204:205], v[138:139] op_sel:[1,0]
	v_pk_mul_f32 v[136:137], v[204:205], v[136:137] op_sel:[1,0]
	v_pk_fma_f32 v[138:139], v[148:149], v[138:139], v[106:107]
	v_pk_fma_f32 v[136:137], v[150:151], v[136:137], v[104:105]
	v_add_u32_e32 v196, 0x10010, v194
	v_mov_b32_e32 v197, v159
	v_pk_fma_f32 v[138:139], v[130:131], s[78:79], v[138:139] op_sel_hi:[1,0,1]
	v_pk_fma_f32 v[136:137], v[128:129], s[78:79], v[136:137] op_sel_hi:[1,0,1]
	v_lshl_add_u64 v[196:197], v[196:197], 2, s[90:91]
	global_store_dwordx4 v[196:197], v[136:139], off
	v_add_u32_e32 v196, 0x18000, v194
	v_mov_b32_e32 v197, v159
	v_sub_f32_e32 v137, v209, v216
	v_sub_f32_e32 v136, v208, v216
	v_sub_f32_e32 v139, v211, v216
	v_sub_f32_e32 v138, v210, v216
	v_pk_mul_f32 v[138:139], v[216:217], v[138:139] op_sel:[1,0]
	v_pk_mul_f32 v[136:137], v[216:217], v[136:137] op_sel:[1,0]
	v_pk_fma_f32 v[138:139], v[152:153], v[138:139], v[102:103]
	v_pk_fma_f32 v[136:137], v[154:155], v[136:137], v[100:101]
	v_pk_fma_f32 v[138:139], v[134:135], s[78:79], v[138:139] op_sel_hi:[1,0,1]
	v_pk_fma_f32 v[136:137], v[132:133], s[78:79], v[136:137] op_sel_hi:[1,0,1]
	v_lshl_add_u64 v[196:197], v[196:197], 2, s[90:91]
	global_store_dwordx4 v[196:197], v[136:139], off
	v_add_u32_e32 v196, 0x18010, v194
	v_mov_b32_e32 v197, v159
	v_sub_f32_e32 v137, v213, v216
	v_sub_f32_e32 v136, v212, v216
	v_sub_f32_e32 v139, v215, v216
	v_sub_f32_e32 v138, v214, v216
	v_pk_mul_f32 v[138:139], v[216:217], v[138:139] op_sel:[1,0]
	v_pk_mul_f32 v[136:137], v[216:217], v[136:137] op_sel:[1,0]
	v_pk_fma_f32 v[138:139], v[148:149], v[138:139], v[98:99]
	v_pk_fma_f32 v[136:137], v[150:151], v[136:137], v[96:97]
	v_pk_fma_f32 v[138:139], v[130:131], s[78:79], v[138:139] op_sel_hi:[1,0,1]
	v_pk_fma_f32 v[136:137], v[128:129], s[78:79], v[136:137] op_sel_hi:[1,0,1]
	v_lshl_add_u64 v[196:197], v[196:197], 2, s[90:91]
	global_store_dwordx4 v[196:197], v[136:139], off
	s_nop 1
	v_add_u32_e32 v138, 0x80, v206
	v_lshlrev_b32_e32 v136, 1, v138
	v_mov_b32_e32 v137, v159
	v_lshlrev_b32_e32 v233, 11, v138
	v_lshl_add_u64 v[196:197], v[136:137], 2, s[2:3]
	v_add_u32_e32 v136, v233, v158
	v_lshl_add_u64 v[136:137], v[136:137], 2, s[88:89]
	global_load_dwordx2 v[204:205], v[196:197], off
	v_add_u32_e32 v198, v233, v231
	global_load_dwordx4 v[136:139], v[136:137], off
	v_mov_b32_e32 v199, v159
	v_add_u32_e32 v207, 0x90, v206
	v_lshl_add_u64 v[198:199], v[198:199], 2, s[88:89]
	v_lshlrev_b32_e32 v234, 11, v207
	global_load_dwordx4 v[208:211], v[198:199], off
	v_add_u32_e32 v212, v234, v158
	v_mov_b32_e32 v213, v159
	v_lshl_add_u64 v[212:213], v[212:213], 2, s[88:89]
	global_load_dwordx4 v[212:215], v[212:213], off
	v_lshlrev_b32_e32 v198, 1, v207
	v_mov_b32_e32 v199, v159
	v_lshl_add_u64 v[198:199], v[198:199], 2, s[2:3]
	global_load_dwordx2 v[238:239], v[198:199], off
	v_add_u32_e32 v216, v234, v231
	v_mov_b32_e32 v217, v159
	v_lshl_add_u64 v[216:217], v[216:217], 2, s[88:89]
	global_load_dwordx4 v[216:219], v[216:217], off
	v_add_u32_e32 v240, 0x40000, v194
	v_mov_b32_e32 v241, v159
	v_lshl_add_u64 v[240:241], v[240:241], 2, s[90:91]
	s_waitcnt vmcnt(0)
;     template <bool LN, int BJ, int LO, int HI> DI void batch(const f32x4 (&acc)[2][2][4][2], unsigned row0, unsigned col0, const f32x4 (&gv)[2], const f32x4 (&bv)[2]) const {
;         f32x4 r[HI - LO]; float mean[(HI - LO) / 2], rstd[(HI - LO) / 2];
; #pragma unroll
;         for (int i = LO; i < HI; ++i) { const int ai = i >> 3, m = (i >> 1) & 3, n = i & 1; const unsigned row = row0 + ai * HALF + m * 16;
;             if (n == 0) { mean[(i - LO) >> 1] = 0.f; rstd[(i - LO) >> 1] = 1.f;
;                 if (LN) { const float2 st = *(const float2*)(stats + row * 2u); mean[(i - LO) >> 1] = st.x; rstd[(i - LO) >> 1] = st.y; } }
;             r[i - LO] = *(const f32x4*)(src + (row * (unsigned)DM + col0 + BJ * HALF + n * 16)); }
; #pragma unroll
;         for (int i = LO; i < HI; ++i) { const int ai = i >> 3, m = (i >> 1) & 3, n = i & 1; const unsigned row = row0 + ai * HALF + m * 16;
;             *(f32x4*)(Y + (row * (unsigned)DM + col0 + BJ * HALF + n * 16)) = acc[ai][BJ][m][n] + ((r[i - LO] - mean[(i - LO) >> 1]) * rstd[(i - LO) >> 1]) * gv[n] + bv[n]; }
	v_sub_f32_e32 v137, v137, v204
	v_sub_f32_e32 v136, v136, v204
	v_sub_f32_e32 v139, v139, v204
	v_sub_f32_e32 v138, v138, v204
	v_pk_mul_f32 v[138:139], v[204:205], v[138:139] op_sel:[1,0]
	v_pk_mul_f32 v[136:137], v[204:205], v[136:137] op_sel:[1,0]
	v_pk_fma_f32 v[138:139], v[152:153], v[138:139], v[94:95]
	v_pk_fma_f32 v[136:137], v[154:155], v[136:137], v[92:93]
	v_pk_fma_f32 v[138:139], v[134:135], s[78:79], v[138:139] op_sel_hi:[1,0,1]
	v_pk_fma_f32 v[136:137], v[132:133], s[78:79], v[136:137] op_sel_hi:[1,0,1]
	global_store_dwordx4 v[240:241], v[136:139], off
	s_nop 1
	v_sub_f32_e32 v137, v209, v204
	v_sub_f32_e32 v136, v208, v204
	v_sub_f32_e32 v139, v211, v204
	v_sub_f32_e32 v138, v210, v204
	v_pk_mul_f32 v[138:139], v[204:205], v[138:139] op_sel:[1,0]
	v_pk_mul_f32 v[136:137], v[204:205], v[136:137] op_sel:[1,0]
	v_pk_fma_f32 v[138:139], v[148:149], v[138:139], v[90:91]
	v_pk_fma_f32 v[136:137], v[150:151], v[136:137], v[88:89]
	v_add_u32_e32 v204, 0x40010, v194
	v_mov_b32_e32 v205, v159
	v_pk_fma_f32 v[138:139], v[130:131], s[78:79], v[138:139] op_sel_hi:[1,0,1]
	v_pk_fma_f32 v[136:137], v[128:129], s[78:79], v[136:137] op_sel_hi:[1,0,1]
	v_lshl_add_u64 v[204:205], v[204:205], 2, s[90:91]
	global_store_dwordx4 v[204:205], v[136:139], off
	v_add_u32_e32 v204, 0x48000, v194
	v_mov_b32_e32 v205, v159
	v_sub_f32_e32 v137, v213, v238
	v_sub_f32_e32 v136, v212, v238
	v_sub_f32_e32 v139, v215, v238
	v_sub_f32_e32 v138, v214, v238
	v_pk_mul_f32 v[138:139], v[238:239], v[138:139] op_sel:[1,0]
	v_pk_mul_f32 v[136:137], v[238:239], v[136:137] op_sel:[1,0]
	v_pk_fma_f32 v[138:139], v[152:153], v[138:139], v[86:87]
	v_pk_fma_f32 v[136:137], v[154:155], v[136:137], v[84:85]
	v_pk_fma_f32 v[138:139], v[134:135], s[78:79], v[138:139] op_sel_hi:[1,0,1]
	v_pk_fma_f32 v[136:137], v[132:133], s[78:79], v[136:137] op_sel_hi:[1,0,1]
	v_lshl_add_u64 v[204:205], v[204:205], 2, s[90:91]
	global_store_dwordx4 v[204:205], v[136:139], off
	v_add_u32_e32 v204, 0x48010, v194
	v_mov_b32_e32 v205, v159
	v_sub_f32_e32 v137, v217, v238
	v_sub_f32_e32 v136, v216, v238
	v_sub_f32_e32 v139, v219, v238
	v_sub_f32_e32 v138, v218, v238
	v_pk_mul_f32 v[138:139], v[238:239], v[138:139] op_sel:[1,0]
	v_pk_mul_f32 v[136:137], v[238:239], v[136:137] op_sel:[1,0]
	v_pk_fma_f32 v[138:139], v[148:149], v[138:139], v[82:83]
	v_pk_fma_f32 v[136:137], v[150:151], v[136:137], v[80:81]
	v_pk_fma_f32 v[138:139], v[130:131], s[78:79], v[138:139] op_sel_hi:[1,0,1]
	v_pk_fma_f32 v[136:137], v[128:129], s[78:79], v[136:137] op_sel_hi:[1,0,1]
	v_lshl_add_u64 v[204:205], v[204:205], 2, s[90:91]
	global_store_dwordx4 v[204:205], v[136:139], off
	s_nop 1
	v_add_u32_e32 v138, 0xa0, v206
	v_lshlrev_b32_e32 v136, 1, v138
	v_mov_b32_e32 v137, v159
	v_lshlrev_b32_e32 v237, 11, v138
	v_lshl_add_u64 v[204:205], v[136:137], 2, s[2:3]
	v_add_u32_e32 v136, v237, v158
	v_lshl_add_u64 v[136:137], v[136:137], 2, s[88:89]
	global_load_dwordx2 v[240:241], v[204:205], off
	v_add_u32_e32 v208, v237, v231
	global_load_dwordx4 v[136:139], v[136:137], off
	v_mov_b32_e32 v209, v159
	v_lshl_add_u64 v[208:209], v[208:209], 2, s[88:89]
	global_load_dwordx4 v[212:215], v[208:209], off
	v_add_u32_e32 v208, 0xb0, v206
	v_lshlrev_b32_e32 v206, 1, v208
	v_mov_b32_e32 v207, v159
	v_lshlrev_b32_e32 v238, 11, v208
	v_lshl_add_u64 v[210:211], v[206:207], 2, s[2:3]
	v_add_u32_e32 v206, v238, v158
	v_lshl_add_u64 v[206:207], v[206:207], 2, s[88:89]
	global_load_dwordx2 v[242:243], v[210:211], off
	v_add_u32_e32 v216, v238, v231
	global_load_dwordx4 v[206:209], v[206:207], off
	v_mov_b32_e32 v217, v159
	v_lshl_add_u64 v[216:217], v[216:217], 2, s[88:89]
	global_load_dwordx4 v[216:219], v[216:217], off
	v_add_u32_e32 v244, 0x50000, v194
	v_mov_b32_e32 v245, v159
	v_lshl_add_u64 v[244:245], v[244:245], 2, s[90:91]
	s_waitcnt vmcnt(0)
	v_sub_f32_e32 v137, v137, v240
	v_sub_f32_e32 v136, v136, v240
	v_sub_f32_e32 v139, v139, v240
	v_sub_f32_e32 v138, v138, v240
	v_pk_mul_f32 v[138:139], v[240:241], v[138:139] op_sel:[1,0]
	v_pk_mul_f32 v[136:137], v[240:241], v[136:137] op_sel:[1,0]
	v_pk_fma_f32 v[138:139], v[152:153], v[138:139], v[78:79]
	v_pk_fma_f32 v[136:137], v[154:155], v[136:137], v[76:77]
	v_pk_fma_f32 v[138:139], v[134:135], s[78:79], v[138:139] op_sel_hi:[1,0,1]
	v_pk_fma_f32 v[136:137], v[132:133], s[78:79], v[136:137] op_sel_hi:[1,0,1]
	global_store_dwordx4 v[244:245], v[136:139], off
	s_nop 1
	v_sub_f32_e32 v137, v213, v240
	v_sub_f32_e32 v136, v212, v240
	v_sub_f32_e32 v139, v215, v240
	v_sub_f32_e32 v138, v214, v240
	v_pk_mul_f32 v[138:139], v[240:241], v[138:139] op_sel:[1,0]
	v_pk_mul_f32 v[136:137], v[240:241], v[136:137] op_sel:[1,0]
	v_pk_fma_f32 v[138:139], v[148:149], v[138:139], v[74:75]
	v_pk_fma_f32 v[136:137], v[150:151], v[136:137], v[72:73]
	v_add_u32_e32 v212, 0x50010, v194
	v_mov_b32_e32 v213, v159
	v_pk_fma_f32 v[138:139], v[130:131], s[78:79], v[138:139] op_sel_hi:[1,0,1]
	v_pk_fma_f32 v[136:137], v[128:129], s[78:79], v[136:137] op_sel_hi:[1,0,1]
	v_lshl_add_u64 v[212:213], v[212:213], 2, s[90:91]
	global_store_dwordx4 v[212:213], v[136:139], off
	s_nop 1
	v_sub_f32_e32 v137, v207, v242
	v_sub_f32_e32 v136, v206, v242
	v_sub_f32_e32 v139, v209, v242
	v_sub_f32_e32 v138, v208, v242
	v_pk_mul_f32 v[136:137], v[242:243], v[136:137] op_sel:[1,0]
	v_pk_mul_f32 v[138:139], v[242:243], v[138:139] op_sel:[1,0]
	v_pk_fma_f32 v[136:137], v[154:155], v[136:137], v[68:69]
	v_pk_fma_f32 v[138:139], v[152:153], v[138:139], v[70:71]
	v_pk_fma_f32 v[132:133], v[132:133], s[78:79], v[136:137] op_sel_hi:[1,0,1]
	v_add_u32_e32 v136, 0x58000, v194
	v_mov_b32_e32 v137, v159
	v_pk_fma_f32 v[134:135], v[134:135], s[78:79], v[138:139] op_sel_hi:[1,0,1]
	v_lshl_add_u64 v[136:137], v[136:137], 2, s[90:91]
	global_store_dwordx4 v[136:137], v[132:135], off
	s_nop 1
	v_sub_f32_e32 v133, v217, v242
	v_sub_f32_e32 v132, v216, v242
	v_sub_f32_e32 v135, v219, v242
	v_sub_f32_e32 v134, v218, v242
	v_pk_mul_f32 v[132:133], v[242:243], v[132:133] op_sel:[1,0]
	v_pk_mul_f32 v[134:135], v[242:243], v[134:135] op_sel:[1,0]
	v_pk_fma_f32 v[132:133], v[150:151], v[132:133], v[64:65]
	v_pk_fma_f32 v[134:135], v[148:149], v[134:135], v[66:67]
	v_pk_fma_f32 v[128:129], v[128:129], s[78:79], v[132:133] op_sel_hi:[1,0,1]
	v_add_u32_e32 v132, 0x58010, v194
	v_mov_b32_e32 v133, v159
	v_pk_fma_f32 v[130:131], v[130:131], s[78:79], v[134:135] op_sel_hi:[1,0,1]
	v_lshl_add_u64 v[132:133], v[132:133], 2, s[90:91]
	global_store_dwordx4 v[132:133], v[128:131], off
	global_load_dwordx4 v[128:131], v[140:141], off offset:512
	v_add_u32_e32 v136, v232, v230
	v_mov_b32_e32 v137, v159
	v_lshl_add_u64 v[136:137], v[136:137], 2, s[88:89]
	s_waitcnt vmcnt(0)
;     template <bool LN, int BJ, int LO, int HI> DI void batch(const f32x4 (&acc)[2][2][4][2], unsigned row0, unsigned col0, const f32x4 (&gv)[2], const f32x4 (&bv)[2]) const {
;         f32x4 r[HI - LO]; float mean[(HI - LO) / 2], rstd[(HI - LO) / 2];
; #pragma unroll
;         for (int i = LO; i < HI; ++i) { const int ai = i >> 3, m = (i >> 1) & 3, n = i & 1; const unsigned row = row0 + ai * HALF + m * 16;
;             if (n == 0) { mean[(i - LO) >> 1] = 0.f; rstd[(i - LO) >> 1] = 1.f;
;                 if (LN) { const float2 st = *(const float2*)(stats + row * 2u); mean[(i - LO) >> 1] = st.x; rstd[(i - LO) >> 1] = st.y; } }
;             r[i - LO] = *(const f32x4*)(src + (row * (unsigned)DM + col0 + BJ * HALF + n * 16)); }
; #pragma unroll
;         for (int i = LO; i < HI; ++i) { const int ai = i >> 3, m = (i >> 1) & 3, n = i & 1; const unsigned row = row0 + ai * HALF + m * 16;
;             *(f32x4*)(Y + (row * (unsigned)DM + col0 + BJ * HALF + n * 16)) = acc[ai][BJ][m][n] + ((r[i - LO] - mean[(i - LO) >> 1]) * rstd[(i - LO) >> 1]) * gv[n] + bv[n]; }
;         __builtin_amdgcn_sched_barrier(0);
;     }
;     template <bool LN, int BJ> DI void load_gb(unsigned col0, f32x4 (&gv)[2], f32x4 (&bv)[2]) const {
; #pragma unroll
;         for (int n = 0; n < 2; ++n) {
;             if (LN) { gv[n] = *(const f32x4*)(gam + col0 + BJ * HALF + n * 16) * ALPHA; bv[n] = *(const f32x4*)(bet + col0 + BJ * HALF + n * 16) * ALPHA; }
;     template <bool LN> DI void run(const f32x4 (&acc)[2][2][4][2], const Unit& u, int wr, int wc, int fr, int fq) const {
;     ...
;         batch<LN, 1, 0, 8>(acc, row0, col0, gv, bv);
	v_pk_mul_f32 v[212:213], v[130:131], s[78:79] op_sel_hi:[1,0]
	v_pk_mul_f32 v[214:215], v[128:129], s[78:79] op_sel_hi:[1,0]
	global_load_dwordx4 v[132:135], v[142:143], off offset:512
	global_load_dwordx4 v[128:131], v[140:141], off offset:576
	s_waitcnt vmcnt(0)
	v_pk_mul_f32 v[206:207], v[130:131], s[78:79] op_sel_hi:[1,0]
	v_pk_mul_f32 v[208:209], v[128:129], s[78:79] op_sel_hi:[1,0]
	global_load_dwordx4 v[128:131], v[142:143], off offset:576
	global_load_dwordx2 v[220:221], v[144:145], off
	global_load_dwordx4 v[240:243], v[136:137], off
	v_add_u32_e32 v136, v232, v229
	v_mov_b32_e32 v137, v159
	v_lshl_add_u64 v[136:137], v[136:137], 2, s[88:89]
	global_load_dwordx4 v[244:247], v[136:137], off
	global_load_dwordx2 v[218:219], v[146:147], off
	v_add_u32_e32 v136, v195, v230
	v_mov_b32_e32 v137, v159
	v_lshl_add_u64 v[136:137], v[136:137], 2, s[88:89]
	global_load_dwordx4 v[248:251], v[136:137], off
	v_add_u32_e32 v136, v195, v229
	v_mov_b32_e32 v137, v159
	v_lshl_add_u64 v[136:137], v[136:137], 2, s[88:89]
	global_load_dwordx4 v[152:155], v[136:137], off
	global_load_dwordx2 v[216:217], v[200:201], off
	v_add_u32_e32 v136, v236, v230
	v_mov_b32_e32 v137, v159
	v_lshl_add_u64 v[136:137], v[136:137], 2, s[88:89]
	global_load_dwordx4 v[148:151], v[136:137], off
	v_add_u32_e32 v136, v236, v229
	v_mov_b32_e32 v137, v159
	v_lshl_add_u64 v[136:137], v[136:137], 2, s[88:89]
	global_load_dwordx4 v[144:147], v[136:137], off
	global_load_dwordx2 v[200:201], v[202:203], off
	v_add_u32_e32 v136, v235, v230
	v_mov_b32_e32 v137, v159
	v_lshl_add_u64 v[136:137], v[136:137], 2, s[88:89]
	global_load_dwordx4 v[140:143], v[136:137], off
	v_add_u32_e32 v136, v235, v229
	v_mov_b32_e32 v137, v159
	v_lshl_add_u64 v[136:137], v[136:137], 2, s[88:89]
	global_load_dwordx4 v[136:139], v[136:137], off
	v_add_u32_e32 v202, 0x80, v194
	v_mov_b32_e32 v203, v159
	v_lshl_add_u64 v[202:203], v[202:203], 2, s[90:91]
	s_waitcnt vmcnt(0)
	v_sub_f32_e32 v241, v241, v220
	v_sub_f32_e32 v240, v240, v220
	v_sub_f32_e32 v243, v243, v220
	v_sub_f32_e32 v242, v242, v220
	v_pk_mul_f32 v[242:243], v[220:221], v[242:243] op_sel:[1,0]
	v_pk_mul_f32 v[240:241], v[220:221], v[240:241] op_sel:[1,0]
	v_pk_fma_f32 v[242:243], v[212:213], v[242:243], v[62:63]
	v_pk_fma_f32 v[240:241], v[214:215], v[240:241], v[60:61]
	v_pk_fma_f32 v[242:243], v[134:135], s[78:79], v[242:243] op_sel_hi:[1,0,1]
	v_pk_fma_f32 v[240:241], v[132:133], s[78:79], v[240:241] op_sel_hi:[1,0,1]
	global_store_dwordx4 v[202:203], v[240:243], off
	v_sub_f32_e32 v203, v245, v220
	v_sub_f32_e32 v202, v244, v220
	v_sub_f32_e32 v241, v247, v220
	v_sub_f32_e32 v240, v246, v220
	v_pk_mul_f32 v[202:203], v[220:221], v[202:203] op_sel:[1,0]
	v_pk_mul_f32 v[240:241], v[220:221], v[240:241] op_sel:[1,0]
	v_pk_fma_f32 v[202:203], v[208:209], v[202:203], v[56:57]
	v_pk_fma_f32 v[220:221], v[206:207], v[240:241], v[58:59]
	v_pk_fma_f32 v[240:241], v[128:129], s[78:79], v[202:203] op_sel_hi:[1,0,1]
	v_add_u32_e32 v202, 0x90, v194
	v_mov_b32_e32 v203, v159
	v_pk_fma_f32 v[242:243], v[130:131], s[78:79], v[220:221] op_sel_hi:[1,0,1]
	v_lshl_add_u64 v[202:203], v[202:203], 2, s[90:91]
	global_store_dwordx4 v[202:203], v[240:243], off
	v_sub_f32_e32 v203, v249, v218
	v_sub_f32_e32 v202, v248, v218
	v_sub_f32_e32 v221, v251, v218
	v_sub_f32_e32 v220, v250, v218
	v_pk_mul_f32 v[202:203], v[218:219], v[202:203] op_sel:[1,0]
	v_pk_mul_f32 v[220:221], v[218:219], v[220:221] op_sel:[1,0]
	v_pk_fma_f32 v[202:203], v[214:215], v[202:203], v[52:53]
	v_pk_fma_f32 v[220:221], v[212:213], v[220:221], v[54:55]
	v_pk_fma_f32 v[240:241], v[132:133], s[78:79], v[202:203] op_sel_hi:[1,0,1]
	v_add_u32_e32 v202, 0x8080, v194
	v_mov_b32_e32 v203, v159
	v_sub_f32_e32 v153, v153, v218
	v_sub_f32_e32 v152, v152, v218
	v_sub_f32_e32 v155, v155, v218
	v_sub_f32_e32 v154, v154, v218
	v_pk_fma_f32 v[242:243], v[134:135], s[78:79], v[220:221] op_sel_hi:[1,0,1]
	v_lshl_add_u64 v[202:203], v[202:203], 2, s[90:91]
	v_pk_mul_f32 v[154:155], v[218:219], v[154:155] op_sel:[1,0]
	v_pk_mul_f32 v[152:153], v[218:219], v[152:153] op_sel:[1,0]
	global_store_dwordx4 v[202:203], v[240:243], off
	v_pk_fma_f32 v[152:153], v[208:209], v[152:153], v[48:49]
	v_pk_fma_f32 v[154:155], v[206:207], v[154:155], v[50:51]
	v_add_u32_e32 v202, 0x8090, v194
	v_mov_b32_e32 v203, v159
	v_sub_f32_e32 v149, v149, v216
	v_sub_f32_e32 v148, v148, v216
	v_sub_f32_e32 v151, v151, v216
	v_sub_f32_e32 v150, v150, v216
	v_pk_fma_f32 v[154:155], v[130:131], s[78:79], v[154:155] op_sel_hi:[1,0,1]
	v_pk_fma_f32 v[152:153], v[128:129], s[78:79], v[152:153] op_sel_hi:[1,0,1]
	v_lshl_add_u64 v[202:203], v[202:203], 2, s[90:91]
	v_pk_mul_f32 v[150:151], v[216:217], v[150:151] op_sel:[1,0]
	v_pk_mul_f32 v[148:149], v[216:217], v[148:149] op_sel:[1,0]
	global_store_dwordx4 v[202:203], v[152:155], off
	v_pk_fma_f32 v[148:149], v[214:215], v[148:149], v[44:45]
	v_pk_fma_f32 v[150:151], v[212:213], v[150:151], v[46:47]
	v_add_u32_e32 v152, 0x10080, v194
	v_mov_b32_e32 v153, v159
	v_sub_f32_e32 v145, v145, v216
	v_sub_f32_e32 v144, v144, v216
	v_sub_f32_e32 v147, v147, v216
	v_sub_f32_e32 v146, v146, v216
	v_pk_fma_f32 v[150:151], v[134:135], s[78:79], v[150:151] op_sel_hi:[1,0,1]
	v_pk_fma_f32 v[148:149], v[132:133], s[78:79], v[148:149] op_sel_hi:[1,0,1]
	v_lshl_add_u64 v[152:153], v[152:153], 2, s[90:91]
	v_pk_mul_f32 v[146:147], v[216:217], v[146:147] op_sel:[1,0]
	v_pk_mul_f32 v[144:145], v[216:217], v[144:145] op_sel:[1,0]
	global_store_dwordx4 v[152:153], v[148:151], off
	v_pk_fma_f32 v[144:145], v[208:209], v[144:145], v[40:41]
	v_pk_fma_f32 v[146:147], v[206:207], v[146:147], v[42:43]
;     template <bool LN, int BJ, int LO, int HI> DI void batch(const f32x4 (&acc)[2][2][4][2], unsigned row0, unsigned col0, const f32x4 (&gv)[2], const f32x4 (&bv)[2]) const {
;         f32x4 r[HI - LO]; float mean[(HI - LO) / 2], rstd[(HI - LO) / 2];
; #pragma unroll
;         for (int i = LO; i < HI; ++i) { const int ai = i >> 3, m = (i >> 1) & 3, n = i & 1; const unsigned row = row0 + ai * HALF + m * 16;
;             if (n == 0) { mean[(i - LO) >> 1] = 0.f; rstd[(i - LO) >> 1] = 1.f;
;                 if (LN) { const float2 st = *(const float2*)(stats + row * 2u); mean[(i - LO) >> 1] = st.x; rstd[(i - LO) >> 1] = st.y; } }
;             r[i - LO] = *(const f32x4*)(src + (row * (unsigned)DM + col0 + BJ * HALF + n * 16)); }
; #pragma unroll
;         for (int i = LO; i < HI; ++i) { const int ai = i >> 3, m = (i >> 1) & 3, n = i & 1; const unsigned row = row0 + ai * HALF + m * 16;
;             *(f32x4*)(Y + (row * (unsigned)DM + col0 + BJ * HALF + n * 16)) = acc[ai][BJ][m][n] + ((r[i - LO] - mean[(i - LO) >> 1]) * rstd[(i - LO) >> 1]) * gv[n] + bv[n]; }
;     template <bool LN> DI void run(const f32x4 (&acc)[2][2][4][2], const Unit& u, int wr, int wc, int fr, int fq) const {
;     ...
;         load_gb<LN, 1>(col0, gv, bv);
;         batch<LN, 1, 0, 8>(acc, row0, col0, gv, bv);
;         batch<LN, 1, 8, 16>(acc, row0, col0, gv, bv);
	v_add_u32_e32 v148, 0x10090, v194
	v_mov_b32_e32 v149, v159
	v_sub_f32_e32 v141, v141, v200
	v_sub_f32_e32 v140, v140, v200
	v_sub_f32_e32 v143, v143, v200
	v_sub_f32_e32 v142, v142, v200
	v_pk_fma_f32 v[146:147], v[130:131], s[78:79], v[146:147] op_sel_hi:[1,0,1]
	v_pk_fma_f32 v[144:145], v[128:129], s[78:79], v[144:145] op_sel_hi:[1,0,1]
	v_lshl_add_u64 v[148:149], v[148:149], 2, s[90:91]
	v_pk_mul_f32 v[142:143], v[200:201], v[142:143] op_sel:[1,0]
	v_pk_mul_f32 v[140:141], v[200:201], v[140:141] op_sel:[1,0]
	global_store_dwordx4 v[148:149], v[144:147], off
	v_pk_fma_f32 v[140:141], v[214:215], v[140:141], v[36:37]
	v_pk_fma_f32 v[142:143], v[212:213], v[142:143], v[38:39]
	v_add_u32_e32 v144, 0x18080, v194
	v_mov_b32_e32 v145, v159
	v_sub_f32_e32 v137, v137, v200
	v_sub_f32_e32 v136, v136, v200
	v_sub_f32_e32 v139, v139, v200
	v_sub_f32_e32 v138, v138, v200
	v_pk_fma_f32 v[142:143], v[134:135], s[78:79], v[142:143] op_sel_hi:[1,0,1]
	v_pk_fma_f32 v[140:141], v[132:133], s[78:79], v[140:141] op_sel_hi:[1,0,1]
	v_lshl_add_u64 v[144:145], v[144:145], 2, s[90:91]
	v_pk_mul_f32 v[138:139], v[200:201], v[138:139] op_sel:[1,0]
	v_pk_mul_f32 v[136:137], v[200:201], v[136:137] op_sel:[1,0]
	global_store_dwordx4 v[144:145], v[140:143], off
	v_pk_fma_f32 v[136:137], v[208:209], v[136:137], v[32:33]
	v_pk_fma_f32 v[138:139], v[206:207], v[138:139], v[34:35]
	v_add_u32_e32 v140, 0x18090, v194
	v_mov_b32_e32 v141, v159
	v_pk_fma_f32 v[138:139], v[130:131], s[78:79], v[138:139] op_sel_hi:[1,0,1]
	v_pk_fma_f32 v[136:137], v[128:129], s[78:79], v[136:137] op_sel_hi:[1,0,1]
	v_lshl_add_u64 v[140:141], v[140:141], 2, s[90:91]
	global_store_dwordx4 v[140:141], v[136:139], off
	s_nop 1
	v_add_u32_e32 v136, v233, v230
	v_mov_b32_e32 v137, v159
	v_lshl_add_u64 v[136:137], v[136:137], 2, s[88:89]
	global_load_dwordx2 v[220:221], v[196:197], off
	global_load_dwordx4 v[216:219], v[136:137], off
	v_add_u32_e32 v136, v233, v229
	v_mov_b32_e32 v137, v159
	v_lshl_add_u64 v[136:137], v[136:137], 2, s[88:89]
	global_load_dwordx4 v[240:243], v[136:137], off
	global_load_dwordx2 v[200:201], v[198:199], off
	v_add_u32_e32 v136, v234, v230
	v_mov_b32_e32 v137, v159
	v_lshl_add_u64 v[136:137], v[136:137], 2, s[88:89]
	global_load_dwordx4 v[244:247], v[136:137], off
	v_add_u32_e32 v136, v234, v229
	v_mov_b32_e32 v137, v159
	v_lshl_add_u64 v[136:137], v[136:137], 2, s[88:89]
	global_load_dwordx4 v[152:155], v[136:137], off
	global_load_dwordx2 v[198:199], v[204:205], off
	v_add_u32_e32 v136, v237, v230
	v_mov_b32_e32 v137, v159
	v_lshl_add_u64 v[136:137], v[136:137], 2, s[88:89]
	global_load_dwordx4 v[148:151], v[136:137], off
	v_add_u32_e32 v136, v237, v229
	v_mov_b32_e32 v137, v159
	v_lshl_add_u64 v[136:137], v[136:137], 2, s[88:89]
	global_load_dwordx4 v[144:147], v[136:137], off
	global_load_dwordx2 v[196:197], v[210:211], off
	v_add_u32_e32 v136, v238, v230
	v_mov_b32_e32 v137, v159
	v_lshl_add_u64 v[136:137], v[136:137], 2, s[88:89]
	global_load_dwordx4 v[140:143], v[136:137], off
	v_add_u32_e32 v136, v238, v229
	v_mov_b32_e32 v137, v159
	v_lshl_add_u64 v[136:137], v[136:137], 2, s[88:89]
	global_load_dwordx4 v[136:139], v[136:137], off
	v_add_u32_e32 v210, 0x40080, v194
	v_mov_b32_e32 v211, v159
	v_lshl_add_u64 v[210:211], v[210:211], 2, s[90:91]
	s_waitcnt vmcnt(0)
;     template <bool LN, int BJ, int LO, int HI> DI void batch(const f32x4 (&acc)[2][2][4][2], unsigned row0, unsigned col0, const f32x4 (&gv)[2], const f32x4 (&bv)[2]) const {
;         f32x4 r[HI - LO]; float mean[(HI - LO) / 2], rstd[(HI - LO) / 2];
; #pragma unroll
;         for (int i = LO; i < HI; ++i) { const int ai = i >> 3, m = (i >> 1) & 3, n = i & 1; const unsigned row = row0 + ai * HALF + m * 16;
;             if (n == 0) { mean[(i - LO) >> 1] = 0.f; rstd[(i - LO) >> 1] = 1.f;
;                 if (LN) { const float2 st = *(const float2*)(stats + row * 2u); mean[(i - LO) >> 1] = st.x; rstd[(i - LO) >> 1] = st.y; } }
;             r[i - LO] = *(const f32x4*)(src + (row * (unsigned)DM + col0 + BJ * HALF + n * 16)); }
; #pragma unroll
;         for (int i = LO; i < HI; ++i) { const int ai = i >> 3, m = (i >> 1) & 3, n = i & 1; const unsigned row = row0 + ai * HALF + m * 16;
;             *(f32x4*)(Y + (row * (unsigned)DM + col0 + BJ * HALF + n * 16)) = acc[ai][BJ][m][n] + ((r[i - LO] - mean[(i - LO) >> 1]) * rstd[(i - LO) >> 1]) * gv[n] + bv[n]; }
;     template <bool LN> DI void run(const f32x4 (&acc)[2][2][4][2], const Unit& u, int wr, int wc, int fr, int fq) const {
;     ...
;         batch<LN, 1, 0, 8>(acc, row0, col0, gv, bv);
;         batch<LN, 1, 8, 16>(acc, row0, col0, gv, bv);
	v_sub_f32_e32 v203, v217, v220
	v_sub_f32_e32 v202, v216, v220
	v_sub_f32_e32 v205, v219, v220
	v_sub_f32_e32 v204, v218, v220
	v_pk_mul_f32 v[204:205], v[220:221], v[204:205] op_sel:[1,0]
	v_pk_mul_f32 v[202:203], v[220:221], v[202:203] op_sel:[1,0]
	v_pk_fma_f32 v[204:205], v[212:213], v[204:205], v[30:31]
	v_pk_fma_f32 v[202:203], v[214:215], v[202:203], v[28:29]
	v_pk_fma_f32 v[204:205], v[134:135], s[78:79], v[204:205] op_sel_hi:[1,0,1]
	v_pk_fma_f32 v[202:203], v[132:133], s[78:79], v[202:203] op_sel_hi:[1,0,1]
	global_store_dwordx4 v[210:211], v[202:205], off
	v_add_u32_e32 v210, 0x40090, v194
	v_mov_b32_e32 v211, v159
	v_sub_f32_e32 v203, v241, v220
	v_sub_f32_e32 v202, v240, v220
	v_sub_f32_e32 v205, v243, v220
	v_sub_f32_e32 v204, v242, v220
	v_pk_mul_f32 v[204:205], v[220:221], v[204:205] op_sel:[1,0]
	v_pk_mul_f32 v[202:203], v[220:221], v[202:203] op_sel:[1,0]
	v_pk_fma_f32 v[204:205], v[206:207], v[204:205], v[26:27]
	v_pk_fma_f32 v[202:203], v[208:209], v[202:203], v[24:25]
	v_pk_fma_f32 v[204:205], v[130:131], s[78:79], v[204:205] op_sel_hi:[1,0,1]
	v_pk_fma_f32 v[202:203], v[128:129], s[78:79], v[202:203] op_sel_hi:[1,0,1]
	v_lshl_add_u64 v[210:211], v[210:211], 2, s[90:91]
	global_store_dwordx4 v[210:211], v[202:205], off
	v_sub_f32_e32 v149, v149, v198
	v_sub_f32_e32 v148, v148, v198
	v_sub_f32_e32 v203, v245, v200
	v_sub_f32_e32 v202, v244, v200
	v_sub_f32_e32 v141, v141, v196
	v_sub_f32_e32 v140, v140, v196
	v_sub_f32_e32 v205, v247, v200
	v_sub_f32_e32 v204, v246, v200
	v_pk_mul_f32 v[202:203], v[200:201], v[202:203] op_sel:[1,0]
	v_sub_f32_e32 v151, v151, v198
	v_sub_f32_e32 v150, v150, v198
	v_pk_mul_f32 v[148:149], v[198:199], v[148:149] op_sel:[1,0]
	v_sub_f32_e32 v143, v143, v196
	v_sub_f32_e32 v142, v142, v196
	v_pk_mul_f32 v[140:141], v[196:197], v[140:141] op_sel:[1,0]
	v_pk_mul_f32 v[204:205], v[200:201], v[204:205] op_sel:[1,0]
	v_pk_fma_f32 v[202:203], v[214:215], v[202:203], v[20:21]
	v_sub_f32_e32 v153, v153, v200
	v_sub_f32_e32 v152, v152, v200
	v_sub_f32_e32 v155, v155, v200
	v_sub_f32_e32 v154, v154, v200
	v_pk_mul_f32 v[150:151], v[198:199], v[150:151] op_sel:[1,0]
	v_pk_fma_f32 v[148:149], v[214:215], v[148:149], v[12:13]
	v_pk_mul_f32 v[142:143], v[196:197], v[142:143] op_sel:[1,0]
	v_pk_fma_f32 v[140:141], v[214:215], v[140:141], v[4:5]
	v_pk_fma_f32 v[204:205], v[212:213], v[204:205], v[22:23]
	v_pk_fma_f32 v[202:203], v[132:133], s[78:79], v[202:203] op_sel_hi:[1,0,1]
	v_pk_mul_f32 v[154:155], v[200:201], v[154:155] op_sel:[1,0]
	v_pk_mul_f32 v[152:153], v[200:201], v[152:153] op_sel:[1,0]
	v_pk_fma_f32 v[150:151], v[212:213], v[150:151], v[14:15]
	v_pk_fma_f32 v[148:149], v[132:133], s[78:79], v[148:149] op_sel_hi:[1,0,1]
	v_pk_fma_f32 v[142:143], v[212:213], v[142:143], v[6:7]
	v_pk_fma_f32 v[132:133], v[132:133], s[78:79], v[140:141] op_sel_hi:[1,0,1]
	v_add_u32_e32 v140, 0x58080, v194
	v_mov_b32_e32 v141, v159
	v_pk_fma_f32 v[204:205], v[134:135], s[78:79], v[204:205] op_sel_hi:[1,0,1]
	v_pk_fma_f32 v[152:153], v[208:209], v[152:153], v[16:17]
	v_pk_fma_f32 v[154:155], v[206:207], v[154:155], v[18:19]
	v_add_u32_e32 v200, 0x48090, v194
	v_mov_b32_e32 v201, v159
	v_pk_fma_f32 v[150:151], v[134:135], s[78:79], v[150:151] op_sel_hi:[1,0,1]
	v_pk_fma_f32 v[134:135], v[134:135], s[78:79], v[142:143] op_sel_hi:[1,0,1]
	v_lshl_add_u64 v[140:141], v[140:141], 2, s[90:91]
	v_pk_fma_f32 v[154:155], v[130:131], s[78:79], v[154:155] op_sel_hi:[1,0,1]
	v_pk_fma_f32 v[152:153], v[128:129], s[78:79], v[152:153] op_sel_hi:[1,0,1]
	v_lshl_add_u64 v[200:201], v[200:201], 2, s[90:91]
	v_sub_f32_e32 v145, v145, v198
	v_sub_f32_e32 v144, v144, v198
	global_store_dwordx4 v[140:141], v[132:135], off
	global_store_dwordx4 v[200:201], v[152:155], off
	v_sub_f32_e32 v147, v147, v198
	v_sub_f32_e32 v133, v137, v196
	v_sub_f32_e32 v132, v136, v196
	v_add_u32_e32 v152, 0x50080, v194
	v_mov_b32_e32 v153, v159
	v_sub_f32_e32 v146, v146, v198
	v_pk_mul_f32 v[144:145], v[198:199], v[144:145] op_sel:[1,0]
	v_sub_f32_e32 v135, v139, v196
	v_sub_f32_e32 v134, v138, v196
	v_pk_mul_f32 v[132:133], v[196:197], v[132:133] op_sel:[1,0]
	v_lshl_add_u64 v[152:153], v[152:153], 2, s[90:91]
	v_pk_mul_f32 v[146:147], v[198:199], v[146:147] op_sel:[1,0]
	v_pk_fma_f32 v[144:145], v[208:209], v[144:145], v[8:9]
	v_pk_mul_f32 v[134:135], v[196:197], v[134:135] op_sel:[1,0]
	v_pk_fma_f32 v[132:133], v[208:209], v[132:133], v[0:1]
	v_add_u32_e32 v210, 0x48080, v194
	v_mov_b32_e32 v211, v159
	global_store_dwordx4 v[152:153], v[148:151], off
	v_pk_fma_f32 v[146:147], v[206:207], v[146:147], v[10:11]
	v_pk_fma_f32 v[144:145], v[128:129], s[78:79], v[144:145] op_sel_hi:[1,0,1]
	v_add_u32_e32 v148, 0x50090, v194
	v_mov_b32_e32 v149, v159
	v_pk_fma_f32 v[134:135], v[206:207], v[134:135], v[2:3]
	v_pk_fma_f32 v[128:129], v[128:129], s[78:79], v[132:133] op_sel_hi:[1,0,1]
	v_add_u32_e32 v132, 0x58090, v194
	v_mov_b32_e32 v133, v159
	v_lshl_add_u64 v[210:211], v[210:211], 2, s[90:91]
	v_pk_fma_f32 v[146:147], v[130:131], s[78:79], v[146:147] op_sel_hi:[1,0,1]
	v_lshl_add_u64 v[148:149], v[148:149], 2, s[90:91]
	v_pk_fma_f32 v[130:131], v[130:131], s[78:79], v[134:135] op_sel_hi:[1,0,1]
	v_lshl_add_u64 v[132:133], v[132:133], 2, s[90:91]
	global_store_dwordx4 v[210:211], v[202:205], off
	global_store_dwordx4 v[148:149], v[144:147], off
	global_store_dwordx4 v[132:133], v[128:131], off
	s_mov_b64 s[24:25], 0
	s_branch .LBB0_324
